# counted vmcnt waits in attention loop and sample loader, dead VALU removed from attention loop, FF1 epilogue stat loads hoisted, s_setprio deleted
# speedup vs baseline: 1.0065x; 1.0065x over previous
.LBB0_326:
	ds_read_b128 v[138:141], v196
	ds_read_b128 v[142:145], v196 offset:1024
	ds_read_b128 v[146:149], v196 offset:2048
	ds_read_b128 v[150:153], v196 offset:3072
	ds_read_b128 v[182:185], v197
	ds_read_b128 v[186:189], v197 offset:1024
	ds_read_b128 v[202:205], v197 offset:2048
	ds_read_b128 v[206:209], v197 offset:3072
	s_add_u32 s0, s8, 0xfff80080
	s_addc_u32 s1, s9, -1
	s_cmp_eq_u32 s51, 28
	s_cselect_b32 s49, s2, s1
	s_cselect_b32 s48, s11, s0
	s_cselect_b32 s1, s13, s50
	s_cselect_b32 s0, s41, s43
	v_lshl_add_u64 v[4:5], s[8:9], 0, v[174:175]
	s_add_i32 m0, s34, 0xc000
	ds_read_b128 v[210:213], v198
	ds_read_b128 v[214:217], v198 offset:1024
	ds_read_b128 v[218:221], v198 offset:2048
	ds_read_b128 v[222:225], v198 offset:3072
	ds_read_b128 v[226:229], v198 offset:4096
	ds_read_b128 v[230:233], v198 offset:5120
	ds_read_b128 v[234:237], v198 offset:6144
	ds_read_b128 v[238:241], v198 offset:7168
	global_load_lds_dwordx4 v[4:5], off
	v_lshl_add_u64 v[4:5], s[8:9], 0, v[176:177]
	s_add_i32 m0, s34, 0xe000
	s_nop 0
	global_load_lds_dwordx4 v[4:5], off
	s_waitcnt vmcnt(8)
	s_waitcnt lgkmcnt(0)
	s_barrier
	s_waitcnt lgkmcnt(0)
	v_mfma_f32_16x16x32_bf16 v[130:133], v[138:141], v[210:213], v[130:133]
	v_mfma_f32_16x16x32_bf16 v[134:137], v[146:149], v[210:213], v[134:137]
	v_mfma_f32_16x16x32_bf16 v[114:117], v[138:141], v[218:221], v[114:117]
	v_mfma_f32_16x16x32_bf16 v[118:121], v[146:149], v[218:221], v[118:121]
	v_mfma_f32_16x16x32_bf16 v[98:101], v[138:141], v[226:229], v[98:101]
	v_mfma_f32_16x16x32_bf16 v[102:105], v[146:149], v[226:229], v[102:105]
	v_mfma_f32_16x16x32_bf16 v[82:85], v[138:141], v[234:237], v[82:85]
	v_mfma_f32_16x16x32_bf16 v[86:89], v[146:149], v[234:237], v[86:89]
	v_mfma_f32_16x16x32_bf16 v[130:133], v[142:145], v[214:217], v[130:133]
	v_mfma_f32_16x16x32_bf16 v[134:137], v[150:153], v[214:217], v[134:137]
	v_mfma_f32_16x16x32_bf16 v[114:117], v[142:145], v[222:225], v[114:117]
	v_mfma_f32_16x16x32_bf16 v[118:121], v[150:153], v[222:225], v[118:121]
	v_mfma_f32_16x16x32_bf16 v[98:101], v[142:145], v[230:233], v[98:101]
	v_mfma_f32_16x16x32_bf16 v[102:105], v[150:153], v[230:233], v[102:105]
	v_mfma_f32_16x16x32_bf16 v[82:85], v[142:145], v[238:241], v[82:85]
	v_mfma_f32_16x16x32_bf16 v[86:89], v[150:153], v[238:241], v[86:89]
	v_mfma_f32_16x16x32_bf16 v[122:125], v[182:185], v[210:213], v[122:125]
	v_mfma_f32_16x16x32_bf16 v[126:129], v[202:205], v[210:213], v[126:129]
	v_mfma_f32_16x16x32_bf16 v[106:109], v[182:185], v[218:221], v[106:109]
	v_mfma_f32_16x16x32_bf16 v[110:113], v[202:205], v[218:221], v[110:113]
	v_mfma_f32_16x16x32_bf16 v[90:93], v[182:185], v[226:229], v[90:93]
	v_mfma_f32_16x16x32_bf16 v[94:97], v[202:205], v[226:229], v[94:97]
	v_mfma_f32_16x16x32_bf16 v[74:77], v[182:185], v[234:237], v[74:77]
	v_mfma_f32_16x16x32_bf16 v[78:81], v[202:205], v[234:237], v[78:81]
	v_mfma_f32_16x16x32_bf16 v[122:125], v[186:189], v[214:217], v[122:125]
	v_mfma_f32_16x16x32_bf16 v[126:129], v[206:209], v[214:217], v[126:129]
	v_mfma_f32_16x16x32_bf16 v[106:109], v[186:189], v[222:225], v[106:109]
	v_mfma_f32_16x16x32_bf16 v[110:113], v[206:209], v[222:225], v[110:113]
	v_mfma_f32_16x16x32_bf16 v[90:93], v[186:189], v[230:233], v[90:93]
	v_mfma_f32_16x16x32_bf16 v[94:97], v[206:209], v[230:233], v[94:97]
	v_mfma_f32_16x16x32_bf16 v[74:77], v[186:189], v[238:241], v[74:77]
	v_mfma_f32_16x16x32_bf16 v[78:81], v[206:209], v[238:241], v[78:81]
	s_barrier
	s_add_i32 s71, s59, s21
	v_lshl_add_u64 v[4:5], s[0:1], 0, v[156:157]
	s_mov_b32 m0, s71
	ds_read_b128 v[210:213], v198 offset:16384
	ds_read_b128 v[214:217], v198 offset:17408
	ds_read_b128 v[218:221], v198 offset:18432
	ds_read_b128 v[222:225], v198 offset:19456
	ds_read_b128 v[226:229], v198 offset:20480
	ds_read_b128 v[230:233], v198 offset:21504
	ds_read_b128 v[234:237], v198 offset:22528
	ds_read_b128 v[238:241], v198 offset:23552
	global_load_lds_dwordx4 v[4:5], off
	s_add_i32 m0, s71, 0x2000
	s_add_u32 s72, s0, 0x80000
	v_lshl_add_u64 v[242:243], s[0:1], 0, v[160:161]
	s_addc_u32 s73, s1, 0
	s_add_i32 s71, s60, s21
	global_load_lds_dwordx4 v[242:243], off
	v_lshl_add_u64 v[8:9], s[72:73], 0, v[156:157]
	s_mov_b32 m0, s71
	v_lshl_add_u64 v[244:245], s[48:49], 0, v[154:155]
	global_load_lds_dwordx4 v[8:9], off
	v_lshl_add_u64 v[8:9], s[72:73], 0, v[160:161]
	s_add_i32 m0, s71, 0x2000
	v_lshl_add_u64 v[246:247], s[48:49], 0, v[158:159]
	global_load_lds_dwordx4 v[8:9], off
	s_mov_b32 m0, s34
	s_nop 0
	global_load_lds_dwordx4 v[244:245], off
	s_mov_b32 m0, s35
	s_nop 0
	global_load_lds_dwordx4 v[246:247], off
	s_waitcnt vmcnt(8)
	s_waitcnt lgkmcnt(0)
	s_barrier
	s_waitcnt lgkmcnt(0)
	v_mfma_f32_16x16x32_bf16 v[66:69], v[138:141], v[210:213], v[66:69]
	v_mfma_f32_16x16x32_bf16 v[70:73], v[146:149], v[210:213], v[70:73]
	v_mfma_f32_16x16x32_bf16 v[50:53], v[138:141], v[218:221], v[50:53]
	v_mfma_f32_16x16x32_bf16 v[54:57], v[146:149], v[218:221], v[54:57]
	v_mfma_f32_16x16x32_bf16 v[34:37], v[138:141], v[226:229], v[34:37]
	v_mfma_f32_16x16x32_bf16 v[38:41], v[146:149], v[226:229], v[38:41]
	v_mfma_f32_16x16x32_bf16 v[18:21], v[138:141], v[234:237], v[18:21]
	v_mfma_f32_16x16x32_bf16 v[22:25], v[146:149], v[234:237], v[22:25]
	v_mfma_f32_16x16x32_bf16 v[66:69], v[142:145], v[214:217], v[66:69]
	v_mfma_f32_16x16x32_bf16 v[70:73], v[150:153], v[214:217], v[70:73]
	v_mfma_f32_16x16x32_bf16 v[50:53], v[142:145], v[222:225], v[50:53]
	v_mfma_f32_16x16x32_bf16 v[54:57], v[150:153], v[222:225], v[54:57]
	v_mfma_f32_16x16x32_bf16 v[34:37], v[142:145], v[230:233], v[34:37]
	v_mfma_f32_16x16x32_bf16 v[38:41], v[150:153], v[230:233], v[38:41]
	v_mfma_f32_16x16x32_bf16 v[18:21], v[142:145], v[238:241], v[18:21]
	v_mfma_f32_16x16x32_bf16 v[22:25], v[150:153], v[238:241], v[22:25]
	v_mfma_f32_16x16x32_bf16 v[58:61], v[182:185], v[210:213], v[58:61]
	v_mfma_f32_16x16x32_bf16 v[62:65], v[202:205], v[210:213], v[62:65]
	v_mfma_f32_16x16x32_bf16 v[42:45], v[182:185], v[218:221], v[42:45]
	v_mfma_f32_16x16x32_bf16 v[46:49], v[202:205], v[218:221], v[46:49]
	v_mfma_f32_16x16x32_bf16 v[26:29], v[182:185], v[226:229], v[26:29]
	v_mfma_f32_16x16x32_bf16 v[30:33], v[202:205], v[226:229], v[30:33]
	v_mfma_f32_16x16x32_bf16 v[14:17], v[182:185], v[234:237], v[14:17]
	v_mfma_f32_16x16x32_bf16 v[8:11], v[202:205], v[234:237], v[10:13]
	v_mfma_f32_16x16x32_bf16 v[58:61], v[186:189], v[214:217], v[58:61]
	v_mfma_f32_16x16x32_bf16 v[62:65], v[206:209], v[214:217], v[62:65]
	v_mfma_f32_16x16x32_bf16 v[42:45], v[186:189], v[222:225], v[42:45]
	v_mfma_f32_16x16x32_bf16 v[46:49], v[206:209], v[222:225], v[46:49]
	v_mfma_f32_16x16x32_bf16 v[26:29], v[186:189], v[230:233], v[26:29]
	v_mfma_f32_16x16x32_bf16 v[30:33], v[206:209], v[230:233], v[30:33]
	v_mfma_f32_16x16x32_bf16 v[14:17], v[186:189], v[238:241], v[14:17]
	v_mfma_f32_16x16x32_bf16 v[8:11], v[206:209], v[238:241], v[8:11]
	s_barrier
	s_add_i32 s71, 0, 0x18000
	v_add_u32_e32 v2, s71, v192
	s_add_i32 s72, 0, 0x1c000
	ds_read_b128 v[138:141], v2
	ds_read_b128 v[142:145], v2 offset:1024
	ds_read_b128 v[146:149], v2 offset:2048
	ds_read_b128 v[150:153], v2 offset:3072
	v_add_u32_e32 v2, s72, v192
	ds_read_b128 v[182:185], v2
	ds_read_b128 v[186:189], v2 offset:1024
	ds_read_b128 v[202:205], v2 offset:2048
	ds_read_b128 v[206:209], v2 offset:3072
	s_add_u32 s48, s48, 0x80000
	s_addc_u32 s49, s49, 0
	s_mov_b32 m0, s52
	v_lshl_add_u64 v[12:13], s[48:49], 0, v[154:155]
	ds_read_b128 v[210:213], v198 offset:32768
	ds_read_b128 v[214:217], v198 offset:33792
	ds_read_b128 v[218:221], v198 offset:34816
	ds_read_b128 v[222:225], v198 offset:35840
	ds_read_b128 v[226:229], v198 offset:36864
	ds_read_b128 v[230:233], v198 offset:37888
	ds_read_b128 v[234:237], v198 offset:38912
	ds_read_b128 v[238:241], v198 offset:39936
	global_load_lds_dwordx4 v[12:13], off
	v_lshl_add_u64 v[12:13], s[48:49], 0, v[158:159]
	s_mov_b32 m0, s53
	s_nop 0
	global_load_lds_dwordx4 v[12:13], off
	s_waitcnt vmcnt(8)
	s_waitcnt lgkmcnt(0)
	s_barrier
	s_waitcnt lgkmcnt(0)
	v_mfma_f32_16x16x32_bf16 v[130:133], v[138:141], v[210:213], v[130:133]
	v_mfma_f32_16x16x32_bf16 v[134:137], v[146:149], v[210:213], v[134:137]
	v_mfma_f32_16x16x32_bf16 v[114:117], v[138:141], v[218:221], v[114:117]
	v_mfma_f32_16x16x32_bf16 v[118:121], v[146:149], v[218:221], v[118:121]
	v_mfma_f32_16x16x32_bf16 v[98:101], v[138:141], v[226:229], v[98:101]
	v_mfma_f32_16x16x32_bf16 v[102:105], v[146:149], v[226:229], v[102:105]
	v_mfma_f32_16x16x32_bf16 v[82:85], v[138:141], v[234:237], v[82:85]
	v_mfma_f32_16x16x32_bf16 v[86:89], v[146:149], v[234:237], v[86:89]
	v_mfma_f32_16x16x32_bf16 v[130:133], v[142:145], v[214:217], v[130:133]
	v_mfma_f32_16x16x32_bf16 v[134:137], v[150:153], v[214:217], v[134:137]
	v_mfma_f32_16x16x32_bf16 v[114:117], v[142:145], v[222:225], v[114:117]
	v_mfma_f32_16x16x32_bf16 v[118:121], v[150:153], v[222:225], v[118:121]
	v_mfma_f32_16x16x32_bf16 v[98:101], v[142:145], v[230:233], v[98:101]
	v_mfma_f32_16x16x32_bf16 v[102:105], v[150:153], v[230:233], v[102:105]
	v_mfma_f32_16x16x32_bf16 v[82:85], v[142:145], v[238:241], v[82:85]
	v_mfma_f32_16x16x32_bf16 v[86:89], v[150:153], v[238:241], v[86:89]
	v_mfma_f32_16x16x32_bf16 v[122:125], v[182:185], v[210:213], v[122:125]
	v_mfma_f32_16x16x32_bf16 v[126:129], v[202:205], v[210:213], v[126:129]
	v_mfma_f32_16x16x32_bf16 v[106:109], v[182:185], v[218:221], v[106:109]
	v_mfma_f32_16x16x32_bf16 v[110:113], v[202:205], v[218:221], v[110:113]
	v_mfma_f32_16x16x32_bf16 v[90:93], v[182:185], v[226:229], v[90:93]
	v_mfma_f32_16x16x32_bf16 v[94:97], v[202:205], v[226:229], v[94:97]
	v_mfma_f32_16x16x32_bf16 v[74:77], v[182:185], v[234:237], v[74:77]
	v_mfma_f32_16x16x32_bf16 v[78:81], v[202:205], v[234:237], v[78:81]
	v_mfma_f32_16x16x32_bf16 v[122:125], v[186:189], v[214:217], v[122:125]
	v_mfma_f32_16x16x32_bf16 v[126:129], v[206:209], v[214:217], v[126:129]
	v_mfma_f32_16x16x32_bf16 v[106:109], v[186:189], v[222:225], v[106:109]
	v_mfma_f32_16x16x32_bf16 v[110:113], v[206:209], v[222:225], v[110:113]
	v_mfma_f32_16x16x32_bf16 v[90:93], v[186:189], v[230:233], v[90:93]
	v_mfma_f32_16x16x32_bf16 v[94:97], v[206:209], v[230:233], v[94:97]
	v_mfma_f32_16x16x32_bf16 v[74:77], v[186:189], v[238:241], v[74:77]
	v_mfma_f32_16x16x32_bf16 v[78:81], v[206:209], v[238:241], v[78:81]
	s_barrier
	s_add_i32 s48, s71, s21
	v_lshl_add_u64 v[4:5], v[4:5], 0, s[36:37]
	s_mov_b32 m0, s48
	ds_read_b128 v[210:213], v198 offset:49152
	ds_read_b128 v[214:217], v198 offset:50176
	ds_read_b128 v[218:221], v198 offset:51200
	ds_read_b128 v[222:225], v198 offset:52224
	ds_read_b128 v[226:229], v198 offset:53248
	ds_read_b128 v[230:233], v198 offset:54272
	ds_read_b128 v[234:237], v198 offset:55296
	ds_read_b128 v[238:241], v198 offset:56320
	global_load_lds_dwordx4 v[4:5], off
	s_add_i32 m0, s48, 0x2000
	s_add_u32 s0, s0, 0x80080
	v_lshl_add_u64 v[4:5], v[242:243], 0, s[36:37]
	s_addc_u32 s1, s1, 0
	s_add_i32 s48, s72, s21
	global_load_lds_dwordx4 v[4:5], off
	v_lshl_add_u64 v[4:5], s[0:1], 0, v[156:157]
	s_mov_b32 m0, s48
	s_nop 0
	global_load_lds_dwordx4 v[4:5], off
	v_lshl_add_u64 v[4:5], s[0:1], 0, v[160:161]
	s_add_i32 m0, s48, 0x2000
	s_nop 0
	global_load_lds_dwordx4 v[4:5], off
	v_lshl_add_u64 v[4:5], v[244:245], 0, s[36:37]
	s_mov_b32 m0, s56
	s_nop 0
	global_load_lds_dwordx4 v[4:5], off
	v_lshl_add_u64 v[4:5], v[246:247], 0, s[36:37]
	s_mov_b32 m0, s57
	s_nop 0
	global_load_lds_dwordx4 v[4:5], off
	s_waitcnt vmcnt(8)
	s_waitcnt lgkmcnt(0)
	s_barrier
	s_waitcnt lgkmcnt(0)
	v_mfma_f32_16x16x32_bf16 v[66:69], v[138:141], v[210:213], v[66:69]
	v_mfma_f32_16x16x32_bf16 v[70:73], v[146:149], v[210:213], v[70:73]
	v_mfma_f32_16x16x32_bf16 v[50:53], v[138:141], v[218:221], v[50:53]
	v_mfma_f32_16x16x32_bf16 v[54:57], v[146:149], v[218:221], v[54:57]
	v_mfma_f32_16x16x32_bf16 v[34:37], v[138:141], v[226:229], v[34:37]
	v_mfma_f32_16x16x32_bf16 v[38:41], v[146:149], v[226:229], v[38:41]
	v_mfma_f32_16x16x32_bf16 v[18:21], v[138:141], v[234:237], v[18:21]
	v_mfma_f32_16x16x32_bf16 v[22:25], v[146:149], v[234:237], v[22:25]
	v_mfma_f32_16x16x32_bf16 v[66:69], v[142:145], v[214:217], v[66:69]
	v_mfma_f32_16x16x32_bf16 v[70:73], v[150:153], v[214:217], v[70:73]
	v_mfma_f32_16x16x32_bf16 v[50:53], v[142:145], v[222:225], v[50:53]
	v_mfma_f32_16x16x32_bf16 v[54:57], v[150:153], v[222:225], v[54:57]
	v_mfma_f32_16x16x32_bf16 v[34:37], v[142:145], v[230:233], v[34:37]
	v_mfma_f32_16x16x32_bf16 v[38:41], v[150:153], v[230:233], v[38:41]
	v_mfma_f32_16x16x32_bf16 v[18:21], v[142:145], v[238:241], v[18:21]
	v_mfma_f32_16x16x32_bf16 v[22:25], v[150:153], v[238:241], v[22:25]
	v_mfma_f32_16x16x32_bf16 v[58:61], v[182:185], v[210:213], v[58:61]
	v_mfma_f32_16x16x32_bf16 v[62:65], v[202:205], v[210:213], v[62:65]
	v_mfma_f32_16x16x32_bf16 v[42:45], v[182:185], v[218:221], v[42:45]
	v_mfma_f32_16x16x32_bf16 v[46:49], v[202:205], v[218:221], v[46:49]
	v_mfma_f32_16x16x32_bf16 v[26:29], v[182:185], v[226:229], v[26:29]
	v_mfma_f32_16x16x32_bf16 v[30:33], v[202:205], v[226:229], v[30:33]
	v_mfma_f32_16x16x32_bf16 v[12:15], v[182:185], v[234:237], v[14:17]
	v_mfma_f32_16x16x32_bf16 v[8:11], v[202:205], v[234:237], v[8:11]
	v_mfma_f32_16x16x32_bf16 v[58:61], v[186:189], v[214:217], v[58:61]
	v_mfma_f32_16x16x32_bf16 v[62:65], v[206:209], v[214:217], v[62:65]
	v_mfma_f32_16x16x32_bf16 v[42:45], v[186:189], v[222:225], v[42:45]
	v_mfma_f32_16x16x32_bf16 v[46:49], v[206:209], v[222:225], v[46:49]
	v_mfma_f32_16x16x32_bf16 v[26:29], v[186:189], v[230:233], v[26:29]
	v_mfma_f32_16x16x32_bf16 v[30:33], v[206:209], v[230:233], v[30:33]
	v_mfma_f32_16x16x32_bf16 v[14:17], v[186:189], v[238:241], v[12:15]
	v_mfma_f32_16x16x32_bf16 v[10:13], v[206:209], v[238:241], v[8:11]
	s_barrier
	s_add_i32 s51, s51, 2
	s_add_u32 s8, s8, 0x100
	s_addc_u32 s9, s9, 0
	s_add_u32 s43, s43, 0x100
	s_addc_u32 s50, s50, 0
	s_cmp_gt_u32 s51, 29
	s_cbranch_scc0 .LBB0_326
	s_and_b64 vcc, exec, s[38:39]
	s_cbranch_vccz .LBB0_329
	s_barrier

.LBB0_561:
	s_add_u32 s39, s28, s38
	s_addc_u32 s42, s29, 0
	s_add_u32 s40, s39, 0x100
	s_addc_u32 s41, s42, 0
	s_and_b64 s[36:37], s[30:31], exec
	s_cselect_b32 s37, s11, s41
	s_cselect_b32 s36, s10, s40
	s_add_u32 s38, s14, s38
	s_addc_u32 s40, s15, 0
	s_add_u32 s38, s38, 0x100
	s_addc_u32 s40, s40, 0
	s_and_b64 s[30:31], s[30:31], exec
	s_cselect_b32 s41, s68, s40
	s_cselect_b32 s40, s69, s38
	s_add_u32 s44, s39, 0x18080
	ds_read_b128 v[82:85], v78
	ds_read_b128 v[86:89], v78 offset:1024
	ds_read_b128 v[90:93], v78 offset:2048
	ds_read_b128 v[94:97], v78 offset:3072
	s_addc_u32 s45, s42, 0
	s_add_u32 s42, s40, 0x10000
	s_addc_u32 s43, s41, 0
	s_add_u32 s30, s36, 0x18000
	s_addc_u32 s31, s37, 0
	s_add_u32 s38, s40, 0x10080
	s_addc_u32 s39, s41, 0
	s_mov_b32 m0, s58
	v_lshl_add_u64 v[76:77], s[44:45], 0, v[72:73]
	ds_read_b128 v[98:101], v79
	ds_read_b128 v[102:105], v79 offset:1024
	ds_read_b128 v[106:109], v79 offset:2048
	ds_read_b128 v[110:113], v79 offset:3072
	ds_read_b128 v[114:117], v79 offset:4096
	ds_read_b128 v[118:121], v79 offset:5120
	ds_read_b128 v[122:125], v79 offset:6144
	ds_read_b128 v[126:129], v79 offset:7168
	global_load_lds_dwordx4 v[76:77], off
	v_lshl_add_u64 v[76:77], s[44:45], 0, v[68:69]
	s_mov_b32 m0, s59
	s_nop 0
	global_load_lds_dwordx4 v[76:77], off
	s_waitcnt vmcnt(8)
	s_waitcnt lgkmcnt(0)
	s_barrier
	s_waitcnt lgkmcnt(0)
	v_mfma_f32_16x16x32_bf16 v[62:65], v[82:85], v[98:101], v[62:65]
	v_mfma_f32_16x16x32_bf16 v[58:61], v[90:93], v[98:101], v[58:61]
	v_mfma_f32_16x16x32_bf16 v[54:57], v[82:85], v[106:109], v[54:57]
	v_mfma_f32_16x16x32_bf16 v[50:53], v[90:93], v[106:109], v[50:53]
	v_mfma_f32_16x16x32_bf16 v[46:49], v[82:85], v[114:117], v[46:49]
	v_mfma_f32_16x16x32_bf16 v[42:45], v[90:93], v[114:117], v[42:45]
	v_mfma_f32_16x16x32_bf16 v[38:41], v[82:85], v[122:125], v[38:41]
	v_mfma_f32_16x16x32_bf16 v[34:37], v[90:93], v[122:125], v[34:37]
	v_mfma_f32_16x16x32_bf16 v[62:65], v[86:89], v[102:105], v[62:65]
	v_mfma_f32_16x16x32_bf16 v[58:61], v[94:97], v[102:105], v[58:61]
	v_mfma_f32_16x16x32_bf16 v[54:57], v[86:89], v[110:113], v[54:57]
	v_mfma_f32_16x16x32_bf16 v[50:53], v[94:97], v[110:113], v[50:53]
	v_mfma_f32_16x16x32_bf16 v[46:49], v[86:89], v[118:121], v[46:49]
	v_mfma_f32_16x16x32_bf16 v[42:45], v[94:97], v[118:121], v[42:45]
	v_mfma_f32_16x16x32_bf16 v[38:41], v[86:89], v[126:129], v[38:41]
	v_mfma_f32_16x16x32_bf16 v[34:37], v[94:97], v[126:129], v[34:37]
	s_barrier
	s_mov_b32 m0, s60
	v_lshl_add_u64 v[76:77], s[40:41], 0, v[70:71]
	ds_read_b128 v[98:101], v79 offset:16384
	ds_read_b128 v[102:105], v79 offset:17408
	ds_read_b128 v[106:109], v79 offset:18432
	ds_read_b128 v[110:113], v79 offset:19456
	ds_read_b128 v[114:117], v79 offset:20480
	ds_read_b128 v[118:121], v79 offset:21504
	ds_read_b128 v[122:125], v79 offset:22528
	ds_read_b128 v[126:129], v79 offset:23552
	global_load_lds_dwordx4 v[76:77], off
	v_lshl_add_u64 v[130:131], s[40:41], 0, v[66:67]
	s_mov_b32 m0, s61
	v_lshl_add_u64 v[132:133], s[42:43], 0, v[70:71]
	global_load_lds_dwordx4 v[130:131], off
	s_mov_b32 m0, s27
	v_lshl_add_u64 v[134:135], s[36:37], 0, v[68:69]
	global_load_lds_dwordx4 v[132:133], off
	v_lshl_add_u64 v[132:133], s[42:43], 0, v[66:67]
	s_mov_b32 m0, s34
	s_nop 0
	global_load_lds_dwordx4 v[132:133], off
	v_lshl_add_u64 v[132:133], s[36:37], 0, v[72:73]
	s_mov_b32 m0, s13
	s_nop 0
	global_load_lds_dwordx4 v[132:133], off
	s_mov_b32 m0, s35
	s_nop 0
	global_load_lds_dwordx4 v[134:135], off
	s_waitcnt vmcnt(8)
	s_waitcnt lgkmcnt(0)
	s_barrier
	s_waitcnt lgkmcnt(0)
	v_mfma_f32_16x16x32_bf16 v[30:33], v[82:85], v[98:101], v[30:33]
	v_mfma_f32_16x16x32_bf16 v[26:29], v[90:93], v[98:101], v[26:29]
	v_mfma_f32_16x16x32_bf16 v[22:25], v[82:85], v[106:109], v[22:25]
	v_mfma_f32_16x16x32_bf16 v[18:21], v[90:93], v[106:109], v[18:21]
	v_mfma_f32_16x16x32_bf16 v[14:17], v[82:85], v[114:117], v[14:17]
	v_mfma_f32_16x16x32_bf16 v[10:13], v[90:93], v[114:117], v[10:13]
	v_mfma_f32_16x16x32_bf16 v[6:9], v[82:85], v[122:125], v[6:9]
	v_mfma_f32_16x16x32_bf16 v[2:5], v[90:93], v[122:125], v[2:5]
	v_mfma_f32_16x16x32_bf16 v[30:33], v[86:89], v[102:105], v[30:33]
	v_mfma_f32_16x16x32_bf16 v[26:29], v[94:97], v[102:105], v[26:29]
	v_mfma_f32_16x16x32_bf16 v[22:25], v[86:89], v[110:113], v[22:25]
	v_mfma_f32_16x16x32_bf16 v[18:21], v[94:97], v[110:113], v[18:21]
	v_mfma_f32_16x16x32_bf16 v[14:17], v[86:89], v[118:121], v[14:17]
	v_mfma_f32_16x16x32_bf16 v[10:13], v[94:97], v[118:121], v[10:13]
	v_mfma_f32_16x16x32_bf16 v[6:9], v[86:89], v[126:129], v[6:9]
	v_mfma_f32_16x16x32_bf16 v[2:5], v[94:97], v[126:129], v[2:5]
	s_barrier
	ds_read_b128 v[82:85], v80
	ds_read_b128 v[86:89], v80 offset:1024
	ds_read_b128 v[90:93], v80 offset:2048
	ds_read_b128 v[94:97], v80 offset:3072
	s_mov_b32 m0, s46
	v_lshl_add_u64 v[136:137], s[30:31], 0, v[72:73]
	ds_read_b128 v[98:101], v79 offset:32768
	ds_read_b128 v[102:105], v79 offset:33792
	ds_read_b128 v[106:109], v79 offset:34816
	ds_read_b128 v[110:113], v79 offset:35840
	ds_read_b128 v[114:117], v79 offset:36864
	ds_read_b128 v[118:121], v79 offset:37888
	ds_read_b128 v[122:125], v79 offset:38912
	ds_read_b128 v[126:129], v79 offset:39936
	global_load_lds_dwordx4 v[136:137], off
	v_lshl_add_u64 v[136:137], s[30:31], 0, v[68:69]
	s_mov_b32 m0, s47
	s_nop 0
	global_load_lds_dwordx4 v[136:137], off
	s_waitcnt vmcnt(8)
	s_waitcnt lgkmcnt(0)
	s_barrier
	s_waitcnt lgkmcnt(0)
	v_mfma_f32_16x16x32_bf16 v[62:65], v[82:85], v[98:101], v[62:65]
	v_mfma_f32_16x16x32_bf16 v[58:61], v[90:93], v[98:101], v[58:61]
	v_mfma_f32_16x16x32_bf16 v[54:57], v[82:85], v[106:109], v[54:57]
	v_mfma_f32_16x16x32_bf16 v[50:53], v[90:93], v[106:109], v[50:53]
	v_mfma_f32_16x16x32_bf16 v[46:49], v[82:85], v[114:117], v[46:49]
	v_mfma_f32_16x16x32_bf16 v[42:45], v[90:93], v[114:117], v[42:45]
	v_mfma_f32_16x16x32_bf16 v[38:41], v[82:85], v[122:125], v[38:41]
	v_mfma_f32_16x16x32_bf16 v[34:37], v[90:93], v[122:125], v[34:37]
	v_mfma_f32_16x16x32_bf16 v[62:65], v[86:89], v[102:105], v[62:65]
	v_mfma_f32_16x16x32_bf16 v[58:61], v[94:97], v[102:105], v[58:61]
	v_mfma_f32_16x16x32_bf16 v[54:57], v[86:89], v[110:113], v[54:57]
	v_mfma_f32_16x16x32_bf16 v[50:53], v[94:97], v[110:113], v[50:53]
	v_mfma_f32_16x16x32_bf16 v[46:49], v[86:89], v[118:121], v[46:49]
	v_mfma_f32_16x16x32_bf16 v[42:45], v[94:97], v[118:121], v[42:45]
	v_mfma_f32_16x16x32_bf16 v[38:41], v[86:89], v[126:129], v[38:41]
	v_mfma_f32_16x16x32_bf16 v[34:37], v[94:97], v[126:129], v[34:37]
	s_barrier
	s_mov_b32 m0, s62
	v_lshl_add_u64 v[76:77], v[76:77], 0, s[6:7]
	ds_read_b128 v[98:101], v79 offset:49152
	ds_read_b128 v[102:105], v79 offset:50176
	ds_read_b128 v[106:109], v79 offset:51200
	ds_read_b128 v[110:113], v79 offset:52224
	ds_read_b128 v[114:117], v79 offset:53248
	ds_read_b128 v[118:121], v79 offset:54272
	ds_read_b128 v[122:125], v79 offset:55296
	ds_read_b128 v[126:129], v79 offset:56320
	global_load_lds_dwordx4 v[76:77], off
	v_lshl_add_u64 v[76:77], v[130:131], 0, s[6:7]
	s_mov_b32 m0, s63
	s_nop 0
	global_load_lds_dwordx4 v[76:77], off
	v_lshl_add_u64 v[76:77], s[38:39], 0, v[70:71]
	s_mov_b32 m0, s51
	s_nop 0
	global_load_lds_dwordx4 v[76:77], off
	v_lshl_add_u64 v[76:77], s[38:39], 0, v[66:67]
	s_mov_b32 m0, s52
	s_nop 0
	global_load_lds_dwordx4 v[76:77], off
	v_lshl_add_u64 v[76:77], v[132:133], 0, s[6:7]
	s_mov_b32 m0, s49
	s_nop 0
	global_load_lds_dwordx4 v[76:77], off
	v_lshl_add_u64 v[76:77], v[134:135], 0, s[6:7]
	s_mov_b32 m0, s50
	s_nop 0
	global_load_lds_dwordx4 v[76:77], off
	s_waitcnt vmcnt(8)
	s_waitcnt lgkmcnt(0)
	s_barrier
	s_waitcnt lgkmcnt(0)
	v_mfma_f32_16x16x32_bf16 v[30:33], v[82:85], v[98:101], v[30:33]
	v_mfma_f32_16x16x32_bf16 v[26:29], v[90:93], v[98:101], v[26:29]
	v_mfma_f32_16x16x32_bf16 v[22:25], v[82:85], v[106:109], v[22:25]
	v_mfma_f32_16x16x32_bf16 v[18:21], v[90:93], v[106:109], v[18:21]
	v_mfma_f32_16x16x32_bf16 v[14:17], v[82:85], v[114:117], v[14:17]
	v_mfma_f32_16x16x32_bf16 v[10:13], v[90:93], v[114:117], v[10:13]
	v_mfma_f32_16x16x32_bf16 v[6:9], v[82:85], v[122:125], v[6:9]
	v_mfma_f32_16x16x32_bf16 v[2:5], v[90:93], v[122:125], v[2:5]
	v_mfma_f32_16x16x32_bf16 v[30:33], v[86:89], v[102:105], v[30:33]
	v_mfma_f32_16x16x32_bf16 v[26:29], v[94:97], v[102:105], v[26:29]
	v_mfma_f32_16x16x32_bf16 v[22:25], v[86:89], v[110:113], v[22:25]
	v_mfma_f32_16x16x32_bf16 v[18:21], v[94:97], v[110:113], v[18:21]
	v_mfma_f32_16x16x32_bf16 v[14:17], v[86:89], v[118:121], v[14:17]
	v_mfma_f32_16x16x32_bf16 v[10:13], v[94:97], v[118:121], v[10:13]
	v_mfma_f32_16x16x32_bf16 v[6:9], v[86:89], v[126:129], v[6:9]
	v_mfma_f32_16x16x32_bf16 v[2:5], v[94:97], v[126:129], v[2:5]
	s_barrier
	s_movk_i32 s38, 0x100
	s_andn2_b64 vcc, exec, s[0:1]
	s_mov_b64 s[30:31], -1
	s_mov_b64 s[0:1], 0
	s_cbranch_vccz .LBB0_561
	s_and_b64 vcc, exec, s[8:9]
	s_cbranch_vccz .LBB0_564
	s_barrier

.LBB0_722:
	ds_read_b128 v[156:159], v149
	ds_read_b128 v[160:163], v149 offset:1024
	ds_read_b128 v[164:167], v149 offset:2048
	ds_read_b128 v[168:171], v149 offset:3072
	ds_read_b128 v[172:175], v150
	ds_read_b128 v[176:179], v150 offset:1024
	ds_read_b128 v[180:183], v150 offset:2048
	ds_read_b128 v[184:187], v150 offset:3072
	s_add_u32 s0, s28, 0xfffe8080
	s_addc_u32 s1, s29, -1
	s_cmp_eq_u32 s56, 2
	s_cselect_b32 s31, s19, s1
	s_cselect_b32 s30, s18, s0
	s_cselect_b32 s1, s23, s13
	s_cselect_b32 s0, s22, s2
	s_mov_b32 m0, s44
	v_lshl_add_u64 v[188:189], s[28:29], 0, v[140:141]
	ds_read_b128 v[192:195], v151
	ds_read_b128 v[196:199], v151 offset:1024
	ds_read_b128 v[200:203], v151 offset:2048
	ds_read_b128 v[204:207], v151 offset:3072
	ds_read_b128 v[208:211], v151 offset:4096
	ds_read_b128 v[212:215], v151 offset:5120
	ds_read_b128 v[216:219], v151 offset:6144
	ds_read_b128 v[220:223], v151 offset:7168
	global_load_lds_dwordx4 v[188:189], off
	v_lshl_add_u64 v[188:189], s[28:29], 0, v[142:143]
	s_mov_b32 m0, s45
	s_nop 0
	global_load_lds_dwordx4 v[188:189], off
	s_waitcnt vmcnt(8)
	s_waitcnt lgkmcnt(0)
	s_barrier
	s_waitcnt lgkmcnt(0)
	v_mfma_f32_16x16x32_bf16 v[126:129], v[156:159], v[192:195], v[126:129]
	v_mfma_f32_16x16x32_bf16 v[122:125], v[164:167], v[192:195], v[122:125]
	v_mfma_f32_16x16x32_bf16 v[110:113], v[156:159], v[200:203], v[110:113]
	v_mfma_f32_16x16x32_bf16 v[106:109], v[164:167], v[200:203], v[106:109]
	v_mfma_f32_16x16x32_bf16 v[94:97], v[156:159], v[208:211], v[94:97]
	v_mfma_f32_16x16x32_bf16 v[90:93], v[164:167], v[208:211], v[90:93]
	v_mfma_f32_16x16x32_bf16 v[78:81], v[156:159], v[216:219], v[78:81]
	v_mfma_f32_16x16x32_bf16 v[74:77], v[164:167], v[216:219], v[74:77]
	v_mfma_f32_16x16x32_bf16 v[126:129], v[160:163], v[196:199], v[126:129]
	v_mfma_f32_16x16x32_bf16 v[122:125], v[168:171], v[196:199], v[122:125]
	v_mfma_f32_16x16x32_bf16 v[110:113], v[160:163], v[204:207], v[110:113]
	v_mfma_f32_16x16x32_bf16 v[106:109], v[168:171], v[204:207], v[106:109]
	v_mfma_f32_16x16x32_bf16 v[94:97], v[160:163], v[212:215], v[94:97]
	v_mfma_f32_16x16x32_bf16 v[90:93], v[168:171], v[212:215], v[90:93]
	v_mfma_f32_16x16x32_bf16 v[78:81], v[160:163], v[220:223], v[78:81]
	v_mfma_f32_16x16x32_bf16 v[74:77], v[168:171], v[220:223], v[74:77]
	v_mfma_f32_16x16x32_bf16 v[118:121], v[172:175], v[192:195], v[118:121]
	v_mfma_f32_16x16x32_bf16 v[114:117], v[180:183], v[192:195], v[114:117]
	v_mfma_f32_16x16x32_bf16 v[102:105], v[172:175], v[200:203], v[102:105]
	v_mfma_f32_16x16x32_bf16 v[98:101], v[180:183], v[200:203], v[98:101]
	v_mfma_f32_16x16x32_bf16 v[86:89], v[172:175], v[208:211], v[86:89]
	v_mfma_f32_16x16x32_bf16 v[82:85], v[180:183], v[208:211], v[82:85]
	v_mfma_f32_16x16x32_bf16 v[70:73], v[172:175], v[216:219], v[70:73]
	v_mfma_f32_16x16x32_bf16 v[66:69], v[180:183], v[216:219], v[66:69]
	v_mfma_f32_16x16x32_bf16 v[118:121], v[176:179], v[196:199], v[118:121]
	v_mfma_f32_16x16x32_bf16 v[114:117], v[184:187], v[196:199], v[114:117]
	v_mfma_f32_16x16x32_bf16 v[102:105], v[176:179], v[204:207], v[102:105]
	v_mfma_f32_16x16x32_bf16 v[98:101], v[184:187], v[204:207], v[98:101]
	v_mfma_f32_16x16x32_bf16 v[86:89], v[176:179], v[212:215], v[86:89]
	v_mfma_f32_16x16x32_bf16 v[82:85], v[184:187], v[212:215], v[82:85]
	v_mfma_f32_16x16x32_bf16 v[70:73], v[176:179], v[220:223], v[70:73]
	v_mfma_f32_16x16x32_bf16 v[66:69], v[184:187], v[220:223], v[66:69]
	s_barrier
	s_mov_b32 m0, s46
	v_lshl_add_u64 v[188:189], s[0:1], 0, v[134:135]
	s_add_u32 s58, s0, 0x18000
	ds_read_b128 v[192:195], v151 offset:16384
	ds_read_b128 v[196:199], v151 offset:17408
	ds_read_b128 v[200:203], v151 offset:18432
	ds_read_b128 v[204:207], v151 offset:19456
	ds_read_b128 v[208:211], v151 offset:20480
	ds_read_b128 v[212:215], v151 offset:21504
	ds_read_b128 v[216:219], v151 offset:22528
	ds_read_b128 v[220:223], v151 offset:23552
	global_load_lds_dwordx4 v[188:189], off
	v_lshl_add_u64 v[224:225], s[0:1], 0, v[130:131]
	s_mov_b32 m0, s47
	s_addc_u32 s59, s1, 0
	global_load_lds_dwordx4 v[224:225], off
	v_lshl_add_u64 v[226:227], s[58:59], 0, v[134:135]
	s_mov_b32 m0, s48
	v_lshl_add_u64 v[228:229], s[30:31], 0, v[132:133]
	global_load_lds_dwordx4 v[226:227], off
	v_lshl_add_u64 v[226:227], s[58:59], 0, v[130:131]
	s_mov_b32 m0, s49
	s_nop 0
	global_load_lds_dwordx4 v[226:227], off
	v_lshl_add_u64 v[226:227], s[30:31], 0, v[136:137]
	s_mov_b32 m0, s27
	s_nop 0
	global_load_lds_dwordx4 v[226:227], off
	s_mov_b32 m0, s20
	s_nop 0
	global_load_lds_dwordx4 v[228:229], off
	s_waitcnt vmcnt(8)
	s_waitcnt lgkmcnt(0)
	s_barrier
	s_waitcnt lgkmcnt(0)
	v_mfma_f32_16x16x32_bf16 v[62:65], v[156:159], v[192:195], v[62:65]
	v_mfma_f32_16x16x32_bf16 v[58:61], v[164:167], v[192:195], v[58:61]
	v_mfma_f32_16x16x32_bf16 v[46:49], v[156:159], v[200:203], v[46:49]
	v_mfma_f32_16x16x32_bf16 v[42:45], v[164:167], v[200:203], v[42:45]
	v_mfma_f32_16x16x32_bf16 v[30:33], v[156:159], v[208:211], v[30:33]
	v_mfma_f32_16x16x32_bf16 v[26:29], v[164:167], v[208:211], v[26:29]
	v_mfma_f32_16x16x32_bf16 v[14:17], v[156:159], v[216:219], v[14:17]
	v_mfma_f32_16x16x32_bf16 v[10:13], v[164:167], v[216:219], v[10:13]
	v_mfma_f32_16x16x32_bf16 v[62:65], v[160:163], v[196:199], v[62:65]
	v_mfma_f32_16x16x32_bf16 v[58:61], v[168:171], v[196:199], v[58:61]
	v_mfma_f32_16x16x32_bf16 v[46:49], v[160:163], v[204:207], v[46:49]
	v_mfma_f32_16x16x32_bf16 v[42:45], v[168:171], v[204:207], v[42:45]
	v_mfma_f32_16x16x32_bf16 v[30:33], v[160:163], v[212:215], v[30:33]
	v_mfma_f32_16x16x32_bf16 v[26:29], v[168:171], v[212:215], v[26:29]
	v_mfma_f32_16x16x32_bf16 v[14:17], v[160:163], v[220:223], v[14:17]
	v_mfma_f32_16x16x32_bf16 v[10:13], v[168:171], v[220:223], v[10:13]
	v_mfma_f32_16x16x32_bf16 v[54:57], v[172:175], v[192:195], v[54:57]
	v_mfma_f32_16x16x32_bf16 v[50:53], v[180:183], v[192:195], v[50:53]
	v_mfma_f32_16x16x32_bf16 v[38:41], v[172:175], v[200:203], v[38:41]
	v_mfma_f32_16x16x32_bf16 v[34:37], v[180:183], v[200:203], v[34:37]
	v_mfma_f32_16x16x32_bf16 v[22:25], v[172:175], v[208:211], v[22:25]
	v_mfma_f32_16x16x32_bf16 v[18:21], v[180:183], v[208:211], v[18:21]
	v_mfma_f32_16x16x32_bf16 v[6:9], v[172:175], v[216:219], v[6:9]
	v_mfma_f32_16x16x32_bf16 v[2:5], v[180:183], v[216:219], v[2:5]
	v_mfma_f32_16x16x32_bf16 v[54:57], v[176:179], v[196:199], v[54:57]
	v_mfma_f32_16x16x32_bf16 v[50:53], v[184:187], v[196:199], v[50:53]
	v_mfma_f32_16x16x32_bf16 v[38:41], v[176:179], v[204:207], v[38:41]
	v_mfma_f32_16x16x32_bf16 v[34:37], v[184:187], v[204:207], v[34:37]
	v_mfma_f32_16x16x32_bf16 v[22:25], v[176:179], v[212:215], v[22:25]
	v_mfma_f32_16x16x32_bf16 v[18:21], v[184:187], v[212:215], v[18:21]
	v_mfma_f32_16x16x32_bf16 v[6:9], v[176:179], v[220:223], v[6:9]
	v_mfma_f32_16x16x32_bf16 v[2:5], v[184:187], v[220:223], v[2:5]
	s_barrier
	ds_read_b128 v[156:159], v152
	ds_read_b128 v[160:163], v152 offset:1024
	ds_read_b128 v[164:167], v152 offset:2048
	ds_read_b128 v[168:171], v152 offset:3072
	ds_read_b128 v[172:175], v153
	ds_read_b128 v[176:179], v153 offset:1024
	ds_read_b128 v[180:183], v153 offset:2048
	ds_read_b128 v[184:187], v153 offset:3072
	s_add_u32 s30, s30, 0x18000
	s_addc_u32 s31, s31, 0
	s_mov_b32 m0, s21
	v_lshl_add_u64 v[230:231], s[30:31], 0, v[136:137]
	ds_read_b128 v[192:195], v151 offset:32768
	ds_read_b128 v[196:199], v151 offset:33792
	ds_read_b128 v[200:203], v151 offset:34816
	ds_read_b128 v[204:207], v151 offset:35840
	ds_read_b128 v[208:211], v151 offset:36864
	ds_read_b128 v[212:215], v151 offset:37888
	ds_read_b128 v[216:219], v151 offset:38912
	ds_read_b128 v[220:223], v151 offset:39936
	global_load_lds_dwordx4 v[230:231], off
	v_lshl_add_u64 v[230:231], s[30:31], 0, v[132:133]
	s_mov_b32 m0, s34
	s_nop 0
	global_load_lds_dwordx4 v[230:231], off
	s_waitcnt vmcnt(8)
	s_waitcnt lgkmcnt(0)
	s_barrier
	s_waitcnt lgkmcnt(0)
	v_mfma_f32_16x16x32_bf16 v[126:129], v[156:159], v[192:195], v[126:129]
	v_mfma_f32_16x16x32_bf16 v[122:125], v[164:167], v[192:195], v[122:125]
	v_mfma_f32_16x16x32_bf16 v[110:113], v[156:159], v[200:203], v[110:113]
	v_mfma_f32_16x16x32_bf16 v[106:109], v[164:167], v[200:203], v[106:109]
	v_mfma_f32_16x16x32_bf16 v[94:97], v[156:159], v[208:211], v[94:97]
	v_mfma_f32_16x16x32_bf16 v[90:93], v[164:167], v[208:211], v[90:93]
	v_mfma_f32_16x16x32_bf16 v[78:81], v[156:159], v[216:219], v[78:81]
	v_mfma_f32_16x16x32_bf16 v[74:77], v[164:167], v[216:219], v[74:77]
	v_mfma_f32_16x16x32_bf16 v[126:129], v[160:163], v[196:199], v[126:129]
	v_mfma_f32_16x16x32_bf16 v[122:125], v[168:171], v[196:199], v[122:125]
	v_mfma_f32_16x16x32_bf16 v[110:113], v[160:163], v[204:207], v[110:113]
	v_mfma_f32_16x16x32_bf16 v[106:109], v[168:171], v[204:207], v[106:109]
	v_mfma_f32_16x16x32_bf16 v[94:97], v[160:163], v[212:215], v[94:97]
	v_mfma_f32_16x16x32_bf16 v[90:93], v[168:171], v[212:215], v[90:93]
	v_mfma_f32_16x16x32_bf16 v[78:81], v[160:163], v[220:223], v[78:81]
	v_mfma_f32_16x16x32_bf16 v[74:77], v[168:171], v[220:223], v[74:77]
	v_mfma_f32_16x16x32_bf16 v[118:121], v[172:175], v[192:195], v[118:121]
	v_mfma_f32_16x16x32_bf16 v[114:117], v[180:183], v[192:195], v[114:117]
	v_mfma_f32_16x16x32_bf16 v[102:105], v[172:175], v[200:203], v[102:105]
	v_mfma_f32_16x16x32_bf16 v[98:101], v[180:183], v[200:203], v[98:101]
	v_mfma_f32_16x16x32_bf16 v[86:89], v[172:175], v[208:211], v[86:89]
	v_mfma_f32_16x16x32_bf16 v[82:85], v[180:183], v[208:211], v[82:85]
	v_mfma_f32_16x16x32_bf16 v[70:73], v[172:175], v[216:219], v[70:73]
	v_mfma_f32_16x16x32_bf16 v[66:69], v[180:183], v[216:219], v[66:69]
	v_mfma_f32_16x16x32_bf16 v[118:121], v[176:179], v[196:199], v[118:121]
	v_mfma_f32_16x16x32_bf16 v[114:117], v[184:187], v[196:199], v[114:117]
	v_mfma_f32_16x16x32_bf16 v[102:105], v[176:179], v[204:207], v[102:105]
	v_mfma_f32_16x16x32_bf16 v[98:101], v[184:187], v[204:207], v[98:101]
	v_mfma_f32_16x16x32_bf16 v[86:89], v[176:179], v[212:215], v[86:89]
	v_mfma_f32_16x16x32_bf16 v[82:85], v[184:187], v[212:215], v[82:85]
	v_mfma_f32_16x16x32_bf16 v[70:73], v[176:179], v[220:223], v[70:73]
	v_mfma_f32_16x16x32_bf16 v[66:69], v[184:187], v[220:223], v[66:69]
	s_barrier
	s_mov_b32 m0, s50
	v_lshl_add_u64 v[188:189], v[188:189], 0, s[10:11]
	s_add_u32 s0, s0, 0x18080
	ds_read_b128 v[192:195], v151 offset:49152
	ds_read_b128 v[196:199], v151 offset:50176
	ds_read_b128 v[200:203], v151 offset:51200
	ds_read_b128 v[204:207], v151 offset:52224
	ds_read_b128 v[208:211], v151 offset:53248
	ds_read_b128 v[212:215], v151 offset:54272
	ds_read_b128 v[216:219], v151 offset:55296
	ds_read_b128 v[220:223], v151 offset:56320
	global_load_lds_dwordx4 v[188:189], off
	v_lshl_add_u64 v[188:189], v[224:225], 0, s[10:11]
	s_mov_b32 m0, s51
	s_addc_u32 s1, s1, 0
	global_load_lds_dwordx4 v[188:189], off
	v_lshl_add_u64 v[188:189], s[0:1], 0, v[134:135]
	s_mov_b32 m0, s52
	s_nop 0
	global_load_lds_dwordx4 v[188:189], off
	v_lshl_add_u64 v[188:189], s[0:1], 0, v[130:131]
	s_mov_b32 m0, s53
	s_nop 0
	global_load_lds_dwordx4 v[188:189], off
	v_lshl_add_u64 v[188:189], v[226:227], 0, s[10:11]
	s_mov_b32 m0, s36
	s_nop 0
	global_load_lds_dwordx4 v[188:189], off
	v_lshl_add_u64 v[188:189], v[228:229], 0, s[10:11]
	s_mov_b32 m0, s37
	s_nop 0
	global_load_lds_dwordx4 v[188:189], off
	s_waitcnt vmcnt(8)
	s_waitcnt lgkmcnt(0)
	s_barrier
	s_waitcnt lgkmcnt(0)
	v_mfma_f32_16x16x32_bf16 v[62:65], v[156:159], v[192:195], v[62:65]
	v_mfma_f32_16x16x32_bf16 v[58:61], v[164:167], v[192:195], v[58:61]
	v_mfma_f32_16x16x32_bf16 v[46:49], v[156:159], v[200:203], v[46:49]
	v_mfma_f32_16x16x32_bf16 v[42:45], v[164:167], v[200:203], v[42:45]
	v_mfma_f32_16x16x32_bf16 v[30:33], v[156:159], v[208:211], v[30:33]
	v_mfma_f32_16x16x32_bf16 v[26:29], v[164:167], v[208:211], v[26:29]
	v_mfma_f32_16x16x32_bf16 v[14:17], v[156:159], v[216:219], v[14:17]
	v_mfma_f32_16x16x32_bf16 v[10:13], v[164:167], v[216:219], v[10:13]
	v_mfma_f32_16x16x32_bf16 v[62:65], v[160:163], v[196:199], v[62:65]
	v_mfma_f32_16x16x32_bf16 v[58:61], v[168:171], v[196:199], v[58:61]
	v_mfma_f32_16x16x32_bf16 v[46:49], v[160:163], v[204:207], v[46:49]
	v_mfma_f32_16x16x32_bf16 v[42:45], v[168:171], v[204:207], v[42:45]
	v_mfma_f32_16x16x32_bf16 v[30:33], v[160:163], v[212:215], v[30:33]
	v_mfma_f32_16x16x32_bf16 v[26:29], v[168:171], v[212:215], v[26:29]
	v_mfma_f32_16x16x32_bf16 v[14:17], v[160:163], v[220:223], v[14:17]
	v_mfma_f32_16x16x32_bf16 v[10:13], v[168:171], v[220:223], v[10:13]
	v_mfma_f32_16x16x32_bf16 v[54:57], v[172:175], v[192:195], v[54:57]
	v_mfma_f32_16x16x32_bf16 v[50:53], v[180:183], v[192:195], v[50:53]
	v_mfma_f32_16x16x32_bf16 v[38:41], v[172:175], v[200:203], v[38:41]
	v_mfma_f32_16x16x32_bf16 v[34:37], v[180:183], v[200:203], v[34:37]
	v_mfma_f32_16x16x32_bf16 v[22:25], v[172:175], v[208:211], v[22:25]
	v_mfma_f32_16x16x32_bf16 v[18:21], v[180:183], v[208:211], v[18:21]
	v_mfma_f32_16x16x32_bf16 v[6:9], v[172:175], v[216:219], v[6:9]
	v_mfma_f32_16x16x32_bf16 v[2:5], v[180:183], v[216:219], v[2:5]
	v_mfma_f32_16x16x32_bf16 v[54:57], v[176:179], v[196:199], v[54:57]
	v_mfma_f32_16x16x32_bf16 v[50:53], v[184:187], v[196:199], v[50:53]
	v_mfma_f32_16x16x32_bf16 v[38:41], v[176:179], v[204:207], v[38:41]
	v_mfma_f32_16x16x32_bf16 v[34:37], v[184:187], v[204:207], v[34:37]
	v_mfma_f32_16x16x32_bf16 v[22:25], v[176:179], v[212:215], v[22:25]
	v_mfma_f32_16x16x32_bf16 v[18:21], v[184:187], v[212:215], v[18:21]
	v_mfma_f32_16x16x32_bf16 v[6:9], v[176:179], v[220:223], v[6:9]
	v_mfma_f32_16x16x32_bf16 v[2:5], v[184:187], v[220:223], v[2:5]
	s_barrier
	s_add_i32 s56, s56, 2
	s_add_u32 s28, s28, 0x100
	s_addc_u32 s29, s29, 0
	s_add_u32 s2, s2, 0x100
	s_addc_u32 s13, s13, 0
	s_cmp_gt_u32 s56, 3
	s_cbranch_scc0 .LBB0_722
	s_and_b64 vcc, exec, s[16:17]
	s_cbranch_vccz .LBB0_725
	s_barrier

.LBB0_761:
	s_mul_i32 s8, s2, 0x4c00
	v_add_u32_e32 v2, s8, v157
	s_add_i32 s1, s23, -1
	s_add_i32 s0, s2, 1
	ds_read_b128 v[104:107], v2
	ds_read_b128 v[108:111], v2 offset:16
	ds_read_b128 v[148:151], v2 offset:4608
	ds_read_b128 v[152:155], v2 offset:4624
	v_cvt_pk_fp8_f32 v116, v96, v1
	v_cvt_u32_f32 v1, v100
	v_cvt_u32_f32 v2, v101
	v_cvt_u32_f32 v96, v102
	v_cvt_pk_fp8_f32 v116, v98, v97 op_sel:[0,0,1]
	v_cvt_u32_f32 v97, v103
	s_waitcnt lgkmcnt(2)
	v_mfma_f32_32x32x64_f8f6f4 v[100:115], v[104:111], v[132:139], 0
	v_cvt_pk_fp8_f32 v117, v88, v89
	v_cvt_pk_fp8_f32 v118, v90, v91
	v_cvt_pk_fp8_f32 v119, v92, v93
	v_cvt_u32_f32 v98, v120
	v_cvt_pk_fp8_f32 v117, v84, v85 op_sel:[0,0,1]
	v_cvt_pk_fp8_f32 v118, v86, v87 op_sel:[0,0,1]
	v_cvt_pk_fp8_f32 v119, v94, v95 op_sel:[0,0,1]
	v_cvt_u32_f32 v84, v121
	v_cvt_u32_f32 v85, v122
	v_cvt_u32_f32 v86, v123
	v_cvt_pk_fp8_f32 v120, v176, v177
	v_cvt_pk_fp8_f32 v122, v1, v2
	v_cvt_pk_fp8_f32 v123, v98, v84
	v_cvt_pk_fp8_f32 v120, v99, v173 op_sel:[0,0,1]
	v_cvt_pk_fp8_f32 v122, v96, v97 op_sel:[0,0,1]
	v_cvt_pk_fp8_f32 v123, v85, v86 op_sel:[0,0,1]
	s_waitcnt lgkmcnt(0)
	v_mfma_f32_32x32x64_f8f6f4 v[84:99], v[148:155], v[132:139], 0
	v_cvt_pk_fp8_f32 v121, v178, v179
	v_cvt_pk_fp8_f32 v121, v174, v175 op_sel:[0,0,1]
	v_lshl_add_u64 v[170:171], s[10:11], 0, v[164:165]
	s_mov_b32 s9, 0x14430000
	v_add_co_u32_e32 v148, vcc, s9, v170
	v_lshl_add_u64 v[168:169], s[10:11], 0, v[166:167]
	s_nop 0
	v_addc_co_u32_e32 v149, vcc, 0, v171, vcc
	s_mov_b32 s9, 0x18406000
	v_add_co_u32_e32 v152, vcc, s9, v168
	s_nop 1
	v_addc_co_u32_e32 v153, vcc, 0, v169, vcc
	global_load_dwordx4 v[148:151], v[148:149], off
	s_nop 0
	global_load_dwordx4 v[152:155], v[152:153], off
	s_addk_i32 s8, 0xb400
	s_cmp_lg_u32 s2, 0
	s_cselect_b32 s8, s8, 0x9800
	v_add_u32_e32 v2, s8, v163
	ds_read_b128 v[200:203], v2 offset:9216
	ds_read_b128 v[204:207], v2 offset:9232
	ds_read_b128 v[208:211], v2 offset:11776
	ds_read_b128 v[212:215], v2 offset:11792
	v_max_f32_e32 v1, v100, v101
	v_max3_f32 v173, v84, v85, v86
	v_max3_f32 v1, v1, v102, v103
	v_max3_f32 v173, v173, v87, v88
	v_max3_f32 v1, v1, v104, v105
	v_max3_f32 v173, v173, v89, v90
	v_max3_f32 v1, v1, v106, v107
	v_max3_f32 v173, v173, v91, v92
	v_max3_f32 v1, v1, v108, v109
	v_max3_f32 v173, v173, v93, v94
	v_max3_f32 v1, v1, v110, v111
	v_max3_f32 v173, v173, v95, v96
	v_max3_f32 v1, v1, v112, v113
	v_max3_f32 v173, v173, v97, v98
	v_max3_f32 v1, v1, v114, v115
	v_max3_f32 v1, v1, v99, v173
	v_mov_b32_e32 v173, v1
	s_nop 1
	v_permlane32_swap_b32_e32 v1, v173
	s_cmp_gt_i32 s1, s35
	v_max_f32_e32 v1, v1, v173
	s_cselect_b64 vcc, -1, 0
	v_cndmask_b32_e32 v1, v1, v197, vcc
	v_sub_f32_e32 v173, v1, v172
	v_cmp_ge_f32_e64 s[8:9], s21, v173
	s_cmp_eq_u64 s[8:9], exec
	s_waitcnt lgkmcnt(2)
	s_nop 1
	v_mfma_f32_32x32x64_f8f6f4 v[52:67], v[116:123], v[200:207], v[52:67]
	ds_read_b128 v[200:203], v2 offset:14336
	ds_read_b128 v[204:207], v2 offset:14352
	v_max_f32_e32 v1, v172, v1
	s_cselect_b64 s[8:9], -1, 0
	v_cndmask_b32_e64 v1, v1, v172, s[8:9]
	v_fmamk_f32 v174, v1, 0xba38aa3b, v194
	v_sub_f32_e32 v172, v172, v1
	v_mul_f32_e32 v174, 0x4b000000, v174
	v_mul_f32_e32 v173, 0x3a38aa3b, v172
	v_cndmask_b32_e64 v172, v193, 0, vcc
	v_cndmask_b32_e32 v174, v174, v197, vcc
	s_waitcnt lgkmcnt(2)
	s_nop 1
	v_mfma_f32_32x32x64_f8f6f4 v[36:51], v[116:123], v[208:215], v[36:51]
	ds_read_b128 v[208:211], v2 offset:16896
	ds_read_b128 v[212:215], v2 offset:16912
	v_pk_fma_f32 v[176:177], v[100:101], v[172:173], v[174:175] op_sel_hi:[1,0,0]
	v_exp_f32_e32 v100, v173
	v_pk_fma_f32 v[190:191], v[84:85], v[172:173], v[174:175] op_sel_hi:[1,0,0]
	v_pk_fma_f32 v[218:219], v[88:89], v[172:173], v[174:175] op_sel_hi:[1,0,0]
	v_pk_fma_f32 v[88:89], v[106:107], v[172:173], v[174:175] op_sel_hi:[1,0,0]
	v_pk_fma_f32 v[102:103], v[102:103], v[172:173], v[174:175] op_sel_hi:[1,0,0]
	v_pk_fma_f32 v[216:217], v[86:87], v[172:173], v[174:175] op_sel_hi:[1,0,0]
	v_pk_fma_f32 v[104:105], v[104:105], v[172:173], v[174:175] op_sel_hi:[1,0,0]
	v_pk_fma_f32 v[106:107], v[90:91], v[172:173], v[174:175] op_sel_hi:[1,0,0]
	v_pk_fma_f32 v[108:109], v[108:109], v[172:173], v[174:175] op_sel_hi:[1,0,0]
	v_pk_fma_f32 v[110:111], v[110:111], v[172:173], v[174:175] op_sel_hi:[1,0,0]
	v_pk_fma_f32 v[112:113], v[112:113], v[172:173], v[174:175] op_sel_hi:[1,0,0]
	v_pk_fma_f32 v[114:115], v[114:115], v[172:173], v[174:175] op_sel_hi:[1,0,0]
	v_cvt_u32_f32 v85, v176
	v_cvt_u32_f32 v86, v177
	v_cvt_u32_f32 v2, v102
	v_cvt_u32_f32 v84, v103
	s_waitcnt lgkmcnt(2)
	s_nop 1
	v_mfma_f32_32x32x64_f8f6f4 v[20:35], v[116:123], v[200:207], v[20:35]
	v_cvt_u32_f32 v91, v104
	v_cvt_u32_f32 v178, v105
	v_cvt_u32_f32 v87, v88
	v_cvt_u32_f32 v88, v89
	v_cvt_u32_f32 v176, v108
	v_cvt_u32_f32 v179, v109
	v_cvt_u32_f32 v89, v110
	v_cvt_u32_f32 v90, v111
	v_cvt_u32_f32 v177, v112
	v_cvt_u32_f32 v182, v113
	s_waitcnt lgkmcnt(0)
	s_nop 1
	v_mfma_f32_32x32x64_f8f6f4 v[4:19], v[116:123], v[208:215], v[4:19]
	v_cvt_u32_f32 v184, v114
	v_cvt_u32_f32 v186, v115
	v_cvt_u32_f32 v185, v190
	v_cvt_u32_f32 v187, v191
	v_cvt_u32_f32 v183, v216
	s_cmp_lg_u32 s2, 2
	s_cselect_b32 s8, s0, 0
	s_nop 1
	v_mfma_f32_32x32x64_f8f6f4 v[68:83], v[116:123], v[124:131], v[68:83]
	v_cvt_u32_f32 v190, v217
	v_cvt_u32_f32 v200, v218
	v_cvt_u32_f32 v201, v219
	v_cvt_u32_f32 v191, v106
	v_cvt_u32_f32 v199, v107
	s_mul_i32 s9, s8, 0x4c00
	s_waitcnt vmcnt(2)
	s_add_i32 s0, s9, 0
	v_add_u32_e32 v101, s0, v158
	ds_write_b128 v101, v[140:143]
	v_add_u32_e32 v101, s0, v160
	v_cmp_gt_f32_e32 vcc, 1.0, v100
	ds_write_b128 v101, v[144:147] offset:9216
	s_cbranch_vccz .LBB0_765
	s_and_saveexec_b64 s[0:1], s[6:7]
	ds_write_b32 v180, v100 offset:58496
	s_or_b64 exec, exec, s[0:1]
	s_waitcnt lgkmcnt(0)
	s_nop 15
	s_nop 15
	v_add_u32_e32 v112, s47, v181
	ds_read_b128 v[100:103], v112 offset:58592
	ds_read_b128 v[104:107], v112 offset:58560
	ds_read_b128 v[108:111], v112 offset:58528
	ds_read_b128 v[112:115], v112 offset:58496
	s_waitcnt lgkmcnt(3)
	v_pk_mul_f32 v[64:65], v[64:65], v[100:101]
	s_waitcnt lgkmcnt(2)
	v_pk_mul_f32 v[60:61], v[60:61], v[104:105]
	s_waitcnt lgkmcnt(1)
	v_pk_mul_f32 v[56:57], v[56:57], v[108:109]
	v_pk_mul_f32 v[66:67], v[66:67], v[102:103]
	v_pk_mul_f32 v[62:63], v[62:63], v[106:107]
	v_pk_mul_f32 v[58:59], v[58:59], v[110:111]
	s_waitcnt lgkmcnt(0)
	v_pk_mul_f32 v[54:55], v[54:55], v[114:115]
	v_pk_mul_f32 v[52:53], v[52:53], v[112:113]
	v_pk_mul_f32 v[48:49], v[48:49], v[100:101]
	v_pk_mul_f32 v[44:45], v[44:45], v[104:105]
	v_pk_mul_f32 v[40:41], v[40:41], v[108:109]
	v_pk_mul_f32 v[50:51], v[50:51], v[102:103]
	v_pk_mul_f32 v[46:47], v[46:47], v[106:107]
	v_pk_mul_f32 v[42:43], v[42:43], v[110:111]
	v_pk_mul_f32 v[38:39], v[38:39], v[114:115]
	v_pk_mul_f32 v[36:37], v[36:37], v[112:113]
	v_pk_mul_f32 v[32:33], v[32:33], v[100:101]
	v_pk_mul_f32 v[28:29], v[28:29], v[104:105]
	v_pk_mul_f32 v[24:25], v[24:25], v[108:109]
	v_pk_mul_f32 v[34:35], v[34:35], v[102:103]
	v_pk_mul_f32 v[30:31], v[30:31], v[106:107]
	v_pk_mul_f32 v[26:27], v[26:27], v[110:111]
	v_pk_mul_f32 v[22:23], v[22:23], v[114:115]
	v_pk_mul_f32 v[20:21], v[20:21], v[112:113]
	v_pk_mul_f32 v[16:17], v[16:17], v[100:101]
	v_pk_mul_f32 v[12:13], v[12:13], v[104:105]
	v_pk_mul_f32 v[8:9], v[8:9], v[108:109]
	v_pk_mul_f32 v[18:19], v[18:19], v[102:103]
	v_pk_mul_f32 v[14:15], v[14:15], v[106:107]
	v_pk_mul_f32 v[10:11], v[10:11], v[110:111]
	v_pk_mul_f32 v[6:7], v[6:7], v[114:115]
	v_pk_mul_f32 v[4:5], v[4:5], v[112:113]
	v_pk_mul_f32 v[80:81], v[80:81], v[100:101]
	v_pk_mul_f32 v[76:77], v[76:77], v[104:105]
	v_pk_mul_f32 v[72:73], v[72:73], v[108:109]
	v_pk_mul_f32 v[82:83], v[82:83], v[102:103]
	v_pk_mul_f32 v[78:79], v[78:79], v[106:107]
	v_pk_mul_f32 v[74:75], v[74:75], v[110:111]
	v_pk_mul_f32 v[70:71], v[70:71], v[114:115]
	v_pk_mul_f32 v[68:69], v[68:69], v[112:113]
	s_nop 1

.LBB0_767:
	v_cvt_pk_fp8_f32 v206, v85, v86
	v_cvt_pk_fp8_f32 v207, v91, v178
	v_cvt_pk_fp8_f32 v208, v176, v179
	v_cvt_pk_fp8_f32 v209, v177, v182
	v_cvt_pk_fp8_f32 v210, v185, v187
	v_cvt_pk_fp8_f32 v211, v200, v201
	v_cvt_pk_fp8_f32 v212, v202, v204
	v_cvt_pk_fp8_f32 v213, v203, v205
	s_add_i32 s0, s8, 1
	s_cmp_lg_u32 s8, 2
	s_cselect_b32 s2, s0, 0
	v_cvt_pk_fp8_f32 v206, v2, v84 op_sel:[0,0,1]
	v_cvt_pk_fp8_f32 v207, v87, v88 op_sel:[0,0,1]
	v_cvt_pk_fp8_f32 v208, v89, v90 op_sel:[0,0,1]
	v_cvt_pk_fp8_f32 v209, v184, v186 op_sel:[0,0,1]
	v_cvt_pk_fp8_f32 v210, v183, v190 op_sel:[0,0,1]
	v_cvt_pk_fp8_f32 v211, v191, v199 op_sel:[0,0,1]
	v_cvt_pk_fp8_f32 v212, v172, v173 op_sel:[0,0,1]
	v_cvt_pk_fp8_f32 v213, v174, v175 op_sel:[0,0,1]
	s_addk_i32 s9, 0xb400
	s_cmp_lg_u32 s8, 0
	s_cselect_b32 s0, s9, 0x9800
	v_add_u32_e32 v2, s0, v163
	ds_read_b128 v[84:87], v2 offset:9216
	ds_read_b128 v[88:91], v2 offset:9232
	ds_read_b128 v[214:217], v2 offset:11776
	ds_read_b128 v[218:221], v2 offset:11792
	v_max_f32_e32 v168, v108, v109
	v_max3_f32 v169, v92, v93, v94
	v_max3_f32 v168, v168, v110, v111
	v_max3_f32 v169, v169, v95, v96
	v_max3_f32 v168, v168, v112, v113
	v_max3_f32 v169, v169, v97, v98
	v_max3_f32 v168, v168, v114, v115
	v_max3_f32 v169, v169, v99, v100
	v_max3_f32 v168, v168, v116, v117
	v_max3_f32 v169, v169, v101, v102
	v_max3_f32 v168, v168, v118, v119
	v_max3_f32 v169, v169, v103, v104
	v_max3_f32 v168, v168, v120, v121
	v_max3_f32 v169, v169, v105, v106
	v_max3_f32 v168, v168, v122, v123
	v_max3_f32 v168, v168, v107, v169
	v_mov_b32_e32 v169, v168
	s_nop 1
	v_permlane32_swap_b32_e32 v168, v169
	s_cmp_gt_i32 s23, s35
	v_max_f32_e32 v168, v168, v169
	s_cselect_b64 vcc, -1, 0
	v_cndmask_b32_e32 v168, v168, v197, vcc
	v_sub_f32_e32 v169, v168, v1
	v_cmp_ge_f32_e64 s[8:9], s21, v169
	s_cmp_eq_u64 s[8:9], exec
	s_waitcnt lgkmcnt(2)
	s_nop 1
	v_mfma_f32_32x32x64_f8f6f4 v[52:67], v[206:213], v[84:91], v[52:67]
	ds_read_b128 v[84:87], v2 offset:14336
	ds_read_b128 v[88:91], v2 offset:14352
	v_max_f32_e32 v168, v1, v168
	s_cselect_b64 s[8:9], -1, 0
	v_cndmask_b32_e64 v172, v168, v1, s[8:9]
	v_fmamk_f32 v169, v172, 0xba38aa3b, v194
	v_sub_f32_e32 v1, v1, v172
	v_mul_f32_e32 v169, 0x4b000000, v169
	v_mul_f32_e32 v1, 0x3a38aa3b, v1
	v_cndmask_b32_e64 v168, v193, 0, vcc
	v_cndmask_b32_e32 v170, v169, v197, vcc
	s_waitcnt lgkmcnt(2)
	s_nop 1
	v_mfma_f32_32x32x64_f8f6f4 v[36:51], v[206:213], v[214:221], v[36:51]
	ds_read_b128 v[214:217], v2 offset:16896
	ds_read_b128 v[218:221], v2 offset:16912
	v_exp_f32_e32 v2, v1
	v_pk_fma_f32 v[174:175], v[92:93], v[168:169], v[170:171] op_sel_hi:[1,0,0]
	v_pk_fma_f32 v[92:93], v[110:111], v[168:169], v[170:171] op_sel_hi:[1,0,0]
	v_pk_fma_f32 v[110:111], v[94:95], v[168:169], v[170:171] op_sel_hi:[1,0,0]
	v_pk_fma_f32 v[94:95], v[112:113], v[168:169], v[170:171] op_sel_hi:[1,0,0]
	v_pk_fma_f32 v[108:109], v[108:109], v[168:169], v[170:171] op_sel_hi:[1,0,0]
	v_pk_fma_f32 v[112:113], v[96:97], v[168:169], v[170:171] op_sel_hi:[1,0,0]
	v_pk_fma_f32 v[114:115], v[114:115], v[168:169], v[170:171] op_sel_hi:[1,0,0]
	v_pk_fma_f32 v[182:183], v[98:99], v[168:169], v[170:171] op_sel_hi:[1,0,0]
	v_pk_fma_f32 v[116:117], v[116:117], v[168:169], v[170:171] op_sel_hi:[1,0,0]
	v_pk_fma_f32 v[118:119], v[118:119], v[168:169], v[170:171] op_sel_hi:[1,0,0]
	v_pk_fma_f32 v[120:121], v[120:121], v[168:169], v[170:171] op_sel_hi:[1,0,0]
	v_pk_fma_f32 v[122:123], v[122:123], v[168:169], v[170:171] op_sel_hi:[1,0,0]
	v_cvt_u32_f32 v96, v108
	v_cvt_u32_f32 v1, v109
	v_cvt_u32_f32 v98, v92
	v_cvt_u32_f32 v97, v93
	s_waitcnt lgkmcnt(2)
	s_nop 1
	v_mfma_f32_32x32x64_f8f6f4 v[20:35], v[206:213], v[84:91], v[20:35]
	v_cvt_u32_f32 v88, v94
	v_cvt_u32_f32 v89, v95
	v_cvt_u32_f32 v84, v114
	v_cvt_u32_f32 v85, v115
	v_cvt_u32_f32 v90, v116
	v_cvt_u32_f32 v91, v117
	v_cvt_u32_f32 v86, v118
	v_cvt_u32_f32 v87, v119
	v_cvt_u32_f32 v92, v120
	v_cvt_u32_f32 v93, v121
	s_waitcnt lgkmcnt(0)
	s_nop 1
	v_mfma_f32_32x32x64_f8f6f4 v[4:19], v[206:213], v[214:221], v[4:19]
	v_cvt_u32_f32 v94, v122
	v_cvt_u32_f32 v95, v123
	v_cvt_u32_f32 v176, v174
	v_cvt_u32_f32 v177, v175
	v_cvt_u32_f32 v99, v110
	s_nop 1
	v_mfma_f32_32x32x64_f8f6f4 v[68:83], v[206:213], v[124:131], v[68:83]
	v_cvt_u32_f32 v173, v111
	v_cvt_u32_f32 v178, v112
	v_cvt_u32_f32 v179, v113
	v_cvt_u32_f32 v174, v182
	v_cvt_u32_f32 v175, v183
	s_mul_i32 s0, s2, 0x4c00
	s_waitcnt vmcnt(2)
	s_add_i32 s0, s0, 0
	v_add_u32_e32 v108, s0, v158
	ds_write_b128 v108, v[148:151]
	v_add_u32_e32 v108, s0, v160
	v_cmp_gt_f32_e32 vcc, 1.0, v2
	ds_write_b128 v108, v[152:155] offset:9216
	s_cbranch_vccz .LBB0_760
	s_and_saveexec_b64 s[0:1], s[6:7]
	s_cbranch_execz .LBB0_759
	ds_write_b32 v180, v2 offset:58496
	s_branch .LBB0_759
.Lattn_skip_ld:
	s_waitcnt vmcnt(0)
	s_branch .LBB0_767

.LBB0_825:
	s_waitcnt vmcnt(31)
	v_mul_f32_e32 v135, 0x41800000, v68
	v_mul_f32_e32 v136, 0x41800000, v69
	v_mov_b32_e32 v140, 0
	v_cvt_pk_fp8_f32 v140, v135, v136
	s_add_i32 s13, s12, 1
	s_cmp_lg_u32 s12, 2
	v_mul_f32_e32 v137, 0x41800000, v70
	v_mul_f32_e32 v139, 0x41800000, v71
	s_cselect_b32 s12, s13, 0
	v_cvt_pk_fp8_f32 v140, v137, v139 op_sel:[0,0,1]
	s_mul_i32 s13, s12, 0x4c00
	s_add_i32 s13, s13, 0
	v_add_u32_e32 v134, s13, v1
	s_waitcnt lgkmcnt(0)
	s_barrier
	ds_write_b32 v134, v140
	s_waitcnt vmcnt(30)
	v_mul_f32_e32 v135, 0x41800000, v72
	v_mul_f32_e32 v136, 0x41800000, v73
	v_mov_b32_e32 v140, 0
	v_cvt_pk_fp8_f32 v140, v135, v136
	v_mul_f32_e32 v137, 0x41800000, v74
	v_mul_f32_e32 v139, 0x41800000, v75
	s_waitcnt vmcnt(29)
	v_mul_f32_e32 v135, 0x41800000, v76
	v_cvt_pk_fp8_f32 v140, v137, v139 op_sel:[0,0,1]
	v_mul_f32_e32 v136, 0x41800000, v77
	v_mul_f32_e32 v137, 0x41800000, v78
	v_mul_f32_e32 v139, 0x41800000, v79
	ds_write_b32 v134, v140 offset:1152
	v_mov_b32_e32 v140, 0
	v_cvt_pk_fp8_f32 v140, v135, v136
	s_waitcnt vmcnt(28)
	v_mul_f32_e32 v135, 0x41800000, v80
	v_mul_f32_e32 v136, 0x41800000, v81
	v_mov_b32_e32 v141, 0
	v_cvt_pk_fp8_f32 v140, v137, v139 op_sel:[0,0,1]
	v_mul_f32_e32 v137, 0x41800000, v82
	v_mul_f32_e32 v139, 0x41800000, v83
	v_mov_b32_e32 v142, 0
	ds_write_b32 v134, v140 offset:2304
	v_mov_b32_e32 v140, 0
	v_cvt_pk_fp8_f32 v140, v135, v136
	s_waitcnt vmcnt(27)
	v_mul_f32_e32 v135, 0x41800000, v84
	v_mul_f32_e32 v136, 0x41800000, v85
	v_mov_b32_e32 v143, 0
	v_cvt_pk_fp8_f32 v140, v137, v139 op_sel:[0,0,1]
	v_mul_f32_e32 v137, 0x41800000, v86
	v_mul_f32_e32 v139, 0x41800000, v87
	v_mov_b32_e32 v144, 0
	ds_write_b32 v134, v140 offset:3456
	v_mov_b32_e32 v140, 0
	v_cvt_pk_fp8_f32 v140, v135, v136
	s_waitcnt vmcnt(26)
	v_mul_f32_e32 v135, 0x41800000, v88
	v_mul_f32_e32 v136, 0x41800000, v89
	s_cmp_gt_u32 s9, 29
	v_cvt_pk_fp8_f32 v140, v137, v139 op_sel:[0,0,1]
	v_mul_f32_e32 v137, 0x41800000, v90
	v_mul_f32_e32 v139, 0x41800000, v91
	ds_write_b32 v134, v140 offset:4608
	v_mov_b32_e32 v140, 0
	v_cvt_pk_fp8_f32 v140, v135, v136
	s_waitcnt vmcnt(25)
	v_mul_f32_e32 v135, 0x41800000, v92
	v_mul_f32_e32 v136, 0x41800000, v93
	v_cvt_pk_fp8_f32 v140, v137, v139 op_sel:[0,0,1]
	v_mul_f32_e32 v137, 0x41800000, v94
	v_mul_f32_e32 v139, 0x41800000, v95
	ds_write_b32 v134, v140 offset:5760
	v_mov_b32_e32 v140, 0
	v_cvt_pk_fp8_f32 v140, v135, v136
	s_waitcnt vmcnt(24)
	v_mul_f32_e32 v135, 0x41800000, v96
	v_mul_f32_e32 v136, 0x41800000, v97
	v_cvt_pk_fp8_f32 v140, v137, v139 op_sel:[0,0,1]
	v_mul_f32_e32 v137, 0x41800000, v98
	v_mul_f32_e32 v139, 0x41800000, v99
	ds_write_b32 v134, v140 offset:6912
	v_mov_b32_e32 v140, 0
	v_cvt_pk_fp8_f32 v140, v135, v136
	s_waitcnt vmcnt(23)
	v_mul_f32_e32 v135, 0x41800000, v100
	s_waitcnt vmcnt(22)
	v_mul_f32_e32 v136, 0x41800000, v104
	v_cvt_pk_fp8_f32 v140, v137, v139 op_sel:[0,0,1]
	s_waitcnt vmcnt(21)
	v_mul_f32_e32 v137, 0x41800000, v108
	s_waitcnt vmcnt(20)
	v_mul_f32_e32 v139, 0x41800000, v112
	ds_write_b32 v134, v140 offset:8064
	v_mov_b32_e32 v140, 0
	v_cvt_pk_fp8_f32 v140, v135, v136
	v_mul_f32_e32 v135, 0x41800000, v101
	v_mul_f32_e32 v136, 0x41800000, v105
	v_cvt_pk_fp8_f32 v141, v135, v136
	v_mul_f32_e32 v135, 0x41800000, v102
	v_mul_f32_e32 v136, 0x41800000, v106
	v_cvt_pk_fp8_f32 v142, v135, v136
	v_mul_f32_e32 v135, 0x41800000, v103
	v_mul_f32_e32 v136, 0x41800000, v107
	v_cvt_pk_fp8_f32 v143, v135, v136
	s_waitcnt vmcnt(19)
	v_mul_f32_e32 v135, 0x41800000, v116
	s_waitcnt vmcnt(18)
	v_mul_f32_e32 v136, 0x41800000, v120
	v_cvt_pk_fp8_f32 v140, v137, v139 op_sel:[0,0,1]
	v_mul_f32_e32 v137, 0x41800000, v109
	v_mul_f32_e32 v139, 0x41800000, v113
	v_cvt_pk_fp8_f32 v144, v135, v136
	v_cvt_pk_fp8_f32 v141, v137, v139 op_sel:[0,0,1]
	v_mul_f32_e32 v137, 0x41800000, v110
	v_mul_f32_e32 v139, 0x41800000, v114
	v_cvt_pk_fp8_f32 v142, v137, v139 op_sel:[0,0,1]
	v_mul_f32_e32 v137, 0x41800000, v111
	v_mul_f32_e32 v139, 0x41800000, v115
	v_cvt_pk_fp8_f32 v143, v137, v139 op_sel:[0,0,1]
	s_waitcnt vmcnt(17)
	v_mul_f32_e32 v137, 0x41800000, v124
	s_waitcnt vmcnt(16)
	v_mul_f32_e32 v139, 0x41800000, v128
	v_cvt_pk_fp8_f32 v144, v137, v139 op_sel:[0,0,1]
	v_add_u32_e32 v134, s13, v138
	v_add_u32_e32 v134, 0x2400, v134
	v_mul_f32_e32 v135, 0x41800000, v117
	ds_write2_b32 v134, v140, v144 offset1:8
	v_mul_f32_e32 v136, 0x41800000, v121
	v_mov_b32_e32 v140, 0
	v_cvt_pk_fp8_f32 v140, v135, v136
	v_mul_f32_e32 v137, 0x41800000, v125
	v_mul_f32_e32 v139, 0x41800000, v129
	v_mul_f32_e32 v135, 0x41800000, v118
	v_cvt_pk_fp8_f32 v140, v137, v139 op_sel:[0,0,1]
	v_mul_f32_e32 v136, 0x41800000, v122
	v_mul_f32_e32 v137, 0x41800000, v126
	v_mul_f32_e32 v139, 0x41800000, v130
	ds_write2_b32 v134, v141, v140 offset0:20 offset1:28
	v_mov_b32_e32 v140, 0
	v_cvt_pk_fp8_f32 v140, v135, v136
	v_mul_f32_e32 v135, 0x41800000, v119
	v_mul_f32_e32 v136, 0x41800000, v123
	v_cvt_pk_fp8_f32 v140, v137, v139 op_sel:[0,0,1]
	v_mul_f32_e32 v137, 0x41800000, v127
	v_mul_f32_e32 v139, 0x41800000, v131
	ds_write2_b32 v134, v142, v140 offset0:40 offset1:48
	v_mov_b32_e32 v140, 0
	v_cvt_pk_fp8_f32 v140, v135, v136
	v_cvt_pk_fp8_f32 v140, v137, v139 op_sel:[0,0,1]
	ds_write2_b32 v134, v143, v140 offset0:60 offset1:68
	s_cbranch_scc1 .LBB0_822
	s_add_u32 s13, s0, s95
	s_addc_u32 s14, s1, 0
	s_add_u32 s13, s13, 0x140000
	s_addc_u32 s14, s14, 0
	s_add_u32 s15, s2, s95
	s_addc_u32 s23, s8, 0
	s_add_u32 s34, s15, 0x140000
	s_addc_u32 s23, s23, 0
	s_cmp_lt_u32 s9, 28
	s_cselect_b32 s15, s14, s25
	s_cselect_b32 s14, s13, s3
	v_lshl_add_u64 v[92:93], s[14:15], 0, v[2:3]
	v_add_co_u32_e32 v72, vcc, s90, v92
	s_cselect_b32 s15, s23, s51
	s_nop 0
	v_addc_co_u32_e32 v73, vcc, 0, v93, vcc
	v_add_co_u32_e32 v76, vcc, s37, v92
	s_cselect_b32 s14, s34, s39
	s_nop 0
	v_addc_co_u32_e32 v77, vcc, 0, v93, vcc
	v_add_co_u32_e32 v80, vcc, s38, v92
	v_lshl_add_u64 v[124:125], s[14:15], 0, v[132:133]
	s_nop 0
	v_addc_co_u32_e32 v81, vcc, 0, v93, vcc
	v_add_co_u32_e32 v84, vcc, s53, v92
	global_load_dwordx4 v[68:71], v[92:93], off
	s_nop 0
	global_load_dwordx4 v[72:75], v[72:73], off
	v_addc_co_u32_e32 v85, vcc, 0, v93, vcc
	v_add_co_u32_e32 v88, vcc, s55, v92
	global_load_dwordx4 v[76:79], v[76:77], off
	s_nop 0
	global_load_dwordx4 v[80:83], v[80:81], off
	v_addc_co_u32_e32 v89, vcc, 0, v93, vcc
	v_add_co_u32_e32 v94, vcc, s91, v92
	global_load_dwordx4 v[84:87], v[84:85], off
	s_nop 0
	global_load_dwordx4 v[88:91], v[88:89], off
	v_addc_co_u32_e32 v95, vcc, 0, v93, vcc
	v_add_co_u32_e32 v96, vcc, s93, v92
	s_nop 1
	v_addc_co_u32_e32 v97, vcc, 0, v93, vcc
	v_add_co_u32_e32 v104, vcc, s27, v124
	global_load_dwordx4 v[92:95], v[94:95], off
	s_nop 0
	global_load_dwordx4 v[96:99], v[96:97], off
	v_addc_co_u32_e32 v105, vcc, 0, v125, vcc
	v_add_co_u32_e32 v108, vcc, 0x2000, v124
	global_load_dwordx4 v[100:103], v[124:125], off
	s_nop 0
	global_load_dwordx4 v[104:107], v[104:105], off
	v_addc_co_u32_e32 v109, vcc, 0, v125, vcc
	v_add_co_u32_e32 v112, vcc, 0x3000, v124
	s_nop 1
	v_addc_co_u32_e32 v113, vcc, 0, v125, vcc
	v_add_co_u32_e32 v116, vcc, 0x4000, v124
	global_load_dwordx4 v[108:111], v[108:109], off
	s_nop 0
	global_load_dwordx4 v[112:115], v[112:113], off
	v_addc_co_u32_e32 v117, vcc, 0, v125, vcc
	v_add_co_u32_e32 v120, vcc, 0x5000, v124
	s_nop 1
	v_addc_co_u32_e32 v121, vcc, 0, v125, vcc
	v_add_co_u32_e32 v126, vcc, 0x6000, v124
	global_load_dwordx4 v[116:119], v[116:117], off
	s_nop 0
	global_load_dwordx4 v[120:123], v[120:121], off
	v_addc_co_u32_e32 v127, vcc, 0, v125, vcc
	v_add_co_u32_e32 v128, vcc, 0x7000, v124
	s_nop 1
	v_addc_co_u32_e32 v129, vcc, 0, v125, vcc
	global_load_dwordx4 v[124:127], v[126:127], off
	s_nop 0
	global_load_dwordx4 v[128:131], v[128:129], off
	s_branch .LBB0_822

.LBB0_892:
	ds_read_b128 v[26:29], v188
	ds_read_b128 v[30:33], v188 offset:1024
	ds_read_b128 v[18:21], v188 offset:2048
	ds_read_b128 v[22:25], v188 offset:3072
	ds_read_b128 v[10:13], v189
	ds_read_b128 v[14:17], v189 offset:1024
	ds_read_b128 v[2:5], v189 offset:2048
	ds_read_b128 v[6:9], v189 offset:3072
	s_add_u32 s0, s42, 0xfffe0080
	s_addc_u32 s1, s43, -1
	s_cmp_eq_u32 s57, 4
	s_cselect_b32 s45, s31, s1
	s_cselect_b32 s44, s53, s0
	s_cselect_b32 s1, s29, s56
	s_cselect_b32 s0, s54, s55
	v_lshl_add_u64 v[216:217], s[42:43], 0, v[170:171]
	s_add_i32 m0, s25, 0xc000
	ds_read_b128 v[178:181], v190
	ds_read_b128 v[182:185], v190 offset:1024
	ds_read_b128 v[192:195], v190 offset:2048
	ds_read_b128 v[196:199], v190 offset:3072
	ds_read_b128 v[200:203], v190 offset:4096
	ds_read_b128 v[204:207], v190 offset:5120
	ds_read_b128 v[208:211], v190 offset:6144
	ds_read_b128 v[212:215], v190 offset:7168
	global_load_lds_dwordx4 v[216:217], off
	v_lshl_add_u64 v[216:217], s[42:43], 0, v[172:173]
	s_add_i32 m0, s25, 0xe000
	s_nop 0
	global_load_lds_dwordx4 v[216:217], off
	s_waitcnt vmcnt(8)
	s_waitcnt lgkmcnt(0)
	s_barrier
	s_waitcnt lgkmcnt(0)
	v_mfma_f32_16x16x128_f8f6f4 v[158:161], v[26:33], v[178:185], v[158:161]
	v_mfma_f32_16x16x128_f8f6f4 v[154:157], v[18:25], v[178:185], v[154:157]
	v_mfma_f32_16x16x128_f8f6f4 v[142:145], v[26:33], v[192:199], v[142:145]
	v_mfma_f32_16x16x128_f8f6f4 v[138:141], v[18:25], v[192:199], v[138:141]
	v_mfma_f32_16x16x128_f8f6f4 v[126:129], v[26:33], v[200:207], v[126:129]
	v_mfma_f32_16x16x128_f8f6f4 v[122:125], v[18:25], v[200:207], v[122:125]
	v_mfma_f32_16x16x128_f8f6f4 v[110:113], v[26:33], v[208:215], v[110:113]
	v_mfma_f32_16x16x128_f8f6f4 v[106:109], v[18:25], v[208:215], v[106:109]
	v_mfma_f32_16x16x128_f8f6f4 v[150:153], v[10:17], v[178:185], v[150:153]
	v_mfma_f32_16x16x128_f8f6f4 v[146:149], v[2:9], v[178:185], v[146:149]
	v_mfma_f32_16x16x128_f8f6f4 v[134:137], v[10:17], v[192:199], v[134:137]
	v_mfma_f32_16x16x128_f8f6f4 v[130:133], v[2:9], v[192:199], v[130:133]
	v_mfma_f32_16x16x128_f8f6f4 v[118:121], v[10:17], v[200:207], v[118:121]
	v_mfma_f32_16x16x128_f8f6f4 v[114:117], v[2:9], v[200:207], v[114:117]
	v_mfma_f32_16x16x128_f8f6f4 v[102:105], v[10:17], v[208:215], v[102:105]
	v_mfma_f32_16x16x128_f8f6f4 v[98:101], v[2:9], v[208:215], v[98:101]
	s_barrier
	s_add_i32 s58, s46, s2
	v_lshl_add_u64 v[178:179], s[0:1], 0, v[166:167]
	s_mov_b32 m0, s58
	ds_read_b128 v[192:195], v190 offset:16384
	ds_read_b128 v[196:199], v190 offset:17408
	ds_read_b128 v[200:203], v190 offset:18432
	ds_read_b128 v[204:207], v190 offset:19456
	ds_read_b128 v[208:211], v190 offset:20480
	ds_read_b128 v[212:215], v190 offset:21504
	ds_read_b128 v[216:219], v190 offset:22528
	ds_read_b128 v[220:223], v190 offset:23552
	global_load_lds_dwordx4 v[178:179], off
	s_add_i32 m0, s58, 0x2000
	s_add_u32 s58, s0, 0x20000
	v_lshl_add_u64 v[180:181], s[0:1], 0, v[162:163]
	s_addc_u32 s59, s1, 0
	s_add_i32 s60, s47, s2
	global_load_lds_dwordx4 v[180:181], off
	v_lshl_add_u64 v[182:183], s[58:59], 0, v[166:167]
	s_mov_b32 m0, s60
	v_lshl_add_u64 v[184:185], s[44:45], 0, v[164:165]
	global_load_lds_dwordx4 v[182:183], off
	v_lshl_add_u64 v[182:183], s[58:59], 0, v[162:163]
	s_add_i32 m0, s60, 0x2000
	s_nop 0
	global_load_lds_dwordx4 v[182:183], off
	v_lshl_add_u64 v[182:183], s[44:45], 0, v[168:169]
	s_mov_b32 m0, s25
	s_nop 0
	global_load_lds_dwordx4 v[182:183], off
	s_mov_b32 m0, s26
	s_nop 0
	global_load_lds_dwordx4 v[184:185], off
	s_waitcnt vmcnt(8)
	s_waitcnt lgkmcnt(0)
	s_barrier
	s_waitcnt lgkmcnt(0)
	v_mfma_f32_16x16x128_f8f6f4 v[94:97], v[26:33], v[192:199], v[94:97]
	v_mfma_f32_16x16x128_f8f6f4 v[90:93], v[18:25], v[192:199], v[90:93]
	v_mfma_f32_16x16x128_f8f6f4 v[78:81], v[26:33], v[200:207], v[78:81]
	v_mfma_f32_16x16x128_f8f6f4 v[74:77], v[18:25], v[200:207], v[74:77]
	v_mfma_f32_16x16x128_f8f6f4 v[62:65], v[26:33], v[208:215], v[62:65]
	v_mfma_f32_16x16x128_f8f6f4 v[58:61], v[18:25], v[208:215], v[58:61]
	v_mfma_f32_16x16x128_f8f6f4 v[46:49], v[26:33], v[216:223], v[46:49]
	v_mfma_f32_16x16x128_f8f6f4 v[42:45], v[18:25], v[216:223], v[42:45]
	v_mfma_f32_16x16x128_f8f6f4 v[86:89], v[10:17], v[192:199], v[86:89]
	v_mfma_f32_16x16x128_f8f6f4 v[82:85], v[2:9], v[192:199], v[82:85]
	v_mfma_f32_16x16x128_f8f6f4 v[70:73], v[10:17], v[200:207], v[70:73]
	v_mfma_f32_16x16x128_f8f6f4 v[66:69], v[2:9], v[200:207], v[66:69]
	v_mfma_f32_16x16x128_f8f6f4 v[54:57], v[10:17], v[208:215], v[54:57]
	v_mfma_f32_16x16x128_f8f6f4 v[50:53], v[2:9], v[208:215], v[50:53]
	v_mfma_f32_16x16x128_f8f6f4 v[38:41], v[10:17], v[216:223], v[38:41]
	v_mfma_f32_16x16x128_f8f6f4 v[34:37], v[2:9], v[216:223], v[34:37]
	s_barrier
	s_add_i32 s58, 0, 0x18000
	s_add_i32 s59, 0, 0x1c000
	v_add_u32_e32 v14, s58, v186
	v_add_u32_e32 v30, s59, v186
	ds_read_b128 v[2:5], v14
	ds_read_b128 v[6:9], v14 offset:1024
	ds_read_b128 v[10:13], v14 offset:2048
	ds_read_b128 v[14:17], v14 offset:3072
	ds_read_b128 v[18:21], v30
	ds_read_b128 v[22:25], v30 offset:1024
	ds_read_b128 v[26:29], v30 offset:2048
	ds_read_b128 v[30:33], v30 offset:3072
	s_add_u32 s44, s44, 0x20000
	s_addc_u32 s45, s45, 0
	s_mov_b32 m0, s27
	v_lshl_add_u64 v[224:225], s[44:45], 0, v[168:169]
	ds_read_b128 v[192:195], v190 offset:32768
	ds_read_b128 v[196:199], v190 offset:33792
	ds_read_b128 v[200:203], v190 offset:34816
	ds_read_b128 v[204:207], v190 offset:35840
	ds_read_b128 v[208:211], v190 offset:36864
	ds_read_b128 v[212:215], v190 offset:37888
	ds_read_b128 v[216:219], v190 offset:38912
	ds_read_b128 v[220:223], v190 offset:39936
	global_load_lds_dwordx4 v[224:225], off
	v_lshl_add_u64 v[224:225], s[44:45], 0, v[164:165]
	s_mov_b32 m0, s33
	s_nop 0
	global_load_lds_dwordx4 v[224:225], off
	s_waitcnt vmcnt(8)
	s_waitcnt lgkmcnt(0)
	s_barrier
	s_waitcnt lgkmcnt(0)
	v_mfma_f32_16x16x128_f8f6f4 v[158:161], v[2:9], v[192:199], v[158:161]
	v_mfma_f32_16x16x128_f8f6f4 v[154:157], v[10:17], v[192:199], v[154:157]
	v_mfma_f32_16x16x128_f8f6f4 v[142:145], v[2:9], v[200:207], v[142:145]
	v_mfma_f32_16x16x128_f8f6f4 v[138:141], v[10:17], v[200:207], v[138:141]
	v_mfma_f32_16x16x128_f8f6f4 v[126:129], v[2:9], v[208:215], v[126:129]
	v_mfma_f32_16x16x128_f8f6f4 v[122:125], v[10:17], v[208:215], v[122:125]
	v_mfma_f32_16x16x128_f8f6f4 v[110:113], v[2:9], v[216:223], v[110:113]
	v_mfma_f32_16x16x128_f8f6f4 v[106:109], v[10:17], v[216:223], v[106:109]
	v_mfma_f32_16x16x128_f8f6f4 v[150:153], v[18:25], v[192:199], v[150:153]
	v_mfma_f32_16x16x128_f8f6f4 v[146:149], v[26:33], v[192:199], v[146:149]
	v_mfma_f32_16x16x128_f8f6f4 v[134:137], v[18:25], v[200:207], v[134:137]
	v_mfma_f32_16x16x128_f8f6f4 v[130:133], v[26:33], v[200:207], v[130:133]
	v_mfma_f32_16x16x128_f8f6f4 v[118:121], v[18:25], v[208:215], v[118:121]
	v_mfma_f32_16x16x128_f8f6f4 v[114:117], v[26:33], v[208:215], v[114:117]
	v_mfma_f32_16x16x128_f8f6f4 v[102:105], v[18:25], v[216:223], v[102:105]
	v_mfma_f32_16x16x128_f8f6f4 v[98:101], v[26:33], v[216:223], v[98:101]
	s_barrier
	s_add_i32 s44, s58, s2
	v_lshl_add_u64 v[178:179], v[178:179], 0, s[14:15]
	s_mov_b32 m0, s44
	ds_read_b128 v[192:195], v190 offset:49152
	ds_read_b128 v[196:199], v190 offset:50176
	ds_read_b128 v[200:203], v190 offset:51200
	ds_read_b128 v[204:207], v190 offset:52224
	ds_read_b128 v[208:211], v190 offset:53248
	ds_read_b128 v[212:215], v190 offset:54272
	ds_read_b128 v[216:219], v190 offset:55296
	ds_read_b128 v[220:223], v190 offset:56320
	global_load_lds_dwordx4 v[178:179], off
	s_add_i32 m0, s44, 0x2000
	s_add_u32 s0, s0, 0x20080
	v_lshl_add_u64 v[178:179], v[180:181], 0, s[14:15]
	s_addc_u32 s1, s1, 0
	s_add_i32 s44, s59, s2
	global_load_lds_dwordx4 v[178:179], off
	v_lshl_add_u64 v[178:179], s[0:1], 0, v[166:167]
	s_mov_b32 m0, s44
	s_nop 0
	global_load_lds_dwordx4 v[178:179], off
	v_lshl_add_u64 v[178:179], s[0:1], 0, v[162:163]
	s_add_i32 m0, s44, 0x2000
	s_nop 0
	global_load_lds_dwordx4 v[178:179], off
	v_lshl_add_u64 v[178:179], v[182:183], 0, s[14:15]
	s_mov_b32 m0, s35
	s_nop 0
	global_load_lds_dwordx4 v[178:179], off
	v_lshl_add_u64 v[178:179], v[184:185], 0, s[14:15]
	s_mov_b32 m0, s41
	s_nop 0
	global_load_lds_dwordx4 v[178:179], off
	s_waitcnt vmcnt(8)
	s_waitcnt lgkmcnt(0)
	s_barrier
	s_waitcnt lgkmcnt(0)
	v_mfma_f32_16x16x128_f8f6f4 v[94:97], v[2:9], v[192:199], v[94:97]
	v_mfma_f32_16x16x128_f8f6f4 v[90:93], v[10:17], v[192:199], v[90:93]
	v_mfma_f32_16x16x128_f8f6f4 v[78:81], v[2:9], v[200:207], v[78:81]
	v_mfma_f32_16x16x128_f8f6f4 v[74:77], v[10:17], v[200:207], v[74:77]
	v_mfma_f32_16x16x128_f8f6f4 v[62:65], v[2:9], v[208:215], v[62:65]
	v_mfma_f32_16x16x128_f8f6f4 v[58:61], v[10:17], v[208:215], v[58:61]
	v_mfma_f32_16x16x128_f8f6f4 v[46:49], v[2:9], v[216:223], v[46:49]
	v_mfma_f32_16x16x128_f8f6f4 v[42:45], v[10:17], v[216:223], v[42:45]
	v_mfma_f32_16x16x128_f8f6f4 v[86:89], v[18:25], v[192:199], v[86:89]
	v_mfma_f32_16x16x128_f8f6f4 v[82:85], v[26:33], v[192:199], v[82:85]
	v_mfma_f32_16x16x128_f8f6f4 v[70:73], v[18:25], v[200:207], v[70:73]
	v_mfma_f32_16x16x128_f8f6f4 v[66:69], v[26:33], v[200:207], v[66:69]
	v_mfma_f32_16x16x128_f8f6f4 v[54:57], v[18:25], v[208:215], v[54:57]
	v_mfma_f32_16x16x128_f8f6f4 v[50:53], v[26:33], v[208:215], v[50:53]
	v_mfma_f32_16x16x128_f8f6f4 v[38:41], v[18:25], v[216:223], v[38:41]
	v_mfma_f32_16x16x128_f8f6f4 v[34:37], v[26:33], v[216:223], v[34:37]
	s_barrier
	s_add_i32 s57, s57, 2
	s_add_u32 s42, s42, 0x100
	s_addc_u32 s43, s43, 0
	s_add_u32 s55, s55, 0x100
	s_addc_u32 s56, s56, 0
	s_cmp_gt_u32 s57, 5
	s_cbranch_scc0 .LBB0_892
	s_and_b64 vcc, exec, s[16:17]
	s_cbranch_vccz .LBB0_895
	s_barrier

.LBB0_967:
	ds_read_b128 v[26:29], v197
	ds_read_b128 v[30:33], v197 offset:1024
	ds_read_b128 v[18:21], v197 offset:2048
	ds_read_b128 v[22:25], v197 offset:3072
	ds_read_b128 v[10:13], v198
	ds_read_b128 v[14:17], v198 offset:1024
	ds_read_b128 v[2:5], v198 offset:2048
	ds_read_b128 v[6:9], v198 offset:3072
	s_add_u32 s0, s58, 0xfffc0080
	s_addc_u32 s1, s59, -1
	s_cmp_eq_u32 s77, 12
	s_cselect_b32 s61, s51, s1
	s_cselect_b32 s60, s57, s0
	s_cselect_b32 s1, s49, s76
	s_cselect_b32 s0, s74, s75
	v_lshl_add_u64 v[188:189], s[58:59], 0, v[172:173]
	s_add_i32 m0, s26, 0xc000
	ds_read_b128 v[180:183], v199
	ds_read_b128 v[184:187], v199 offset:1024
	ds_read_b128 v[202:205], v199 offset:2048
	ds_read_b128 v[206:209], v199 offset:3072
	ds_read_b128 v[210:213], v199 offset:4096
	ds_read_b128 v[214:217], v199 offset:5120
	ds_read_b128 v[218:221], v199 offset:6144
	ds_read_b128 v[222:225], v199 offset:7168
	global_load_lds_dwordx4 v[188:189], off
	v_lshl_add_u64 v[188:189], s[58:59], 0, v[174:175]
	s_add_i32 m0, s26, 0xe000
	s_nop 0
	global_load_lds_dwordx4 v[188:189], off
	s_waitcnt vmcnt(8)
	s_waitcnt lgkmcnt(0)
	s_barrier
	s_waitcnt lgkmcnt(0)
	v_mfma_f32_16x16x128_f8f6f4 v[158:161], v[26:33], v[180:187], v[158:161]
	v_mfma_f32_16x16x128_f8f6f4 v[154:157], v[18:25], v[180:187], v[154:157]
	v_mfma_f32_16x16x128_f8f6f4 v[142:145], v[26:33], v[202:209], v[142:145]
	v_mfma_f32_16x16x128_f8f6f4 v[138:141], v[18:25], v[202:209], v[138:141]
	v_mfma_f32_16x16x128_f8f6f4 v[126:129], v[26:33], v[210:217], v[126:129]
	v_mfma_f32_16x16x128_f8f6f4 v[122:125], v[18:25], v[210:217], v[122:125]
	v_mfma_f32_16x16x128_f8f6f4 v[110:113], v[26:33], v[218:225], v[110:113]
	v_mfma_f32_16x16x128_f8f6f4 v[106:109], v[18:25], v[218:225], v[106:109]
	v_mfma_f32_16x16x128_f8f6f4 v[150:153], v[10:17], v[180:187], v[150:153]
	v_mfma_f32_16x16x128_f8f6f4 v[146:149], v[2:9], v[180:187], v[146:149]
	v_mfma_f32_16x16x128_f8f6f4 v[134:137], v[10:17], v[202:209], v[134:137]
	v_mfma_f32_16x16x128_f8f6f4 v[130:133], v[2:9], v[202:209], v[130:133]
	v_mfma_f32_16x16x128_f8f6f4 v[118:121], v[10:17], v[210:217], v[118:121]
	v_mfma_f32_16x16x128_f8f6f4 v[114:117], v[2:9], v[210:217], v[114:117]
	v_mfma_f32_16x16x128_f8f6f4 v[102:105], v[10:17], v[218:225], v[102:105]
	v_mfma_f32_16x16x128_f8f6f4 v[98:101], v[2:9], v[218:225], v[98:101]
	s_barrier
	s_add_i32 s78, s70, s3
	v_lshl_add_u64 v[180:181], s[0:1], 0, v[164:165]
	s_mov_b32 m0, s78
	ds_read_b128 v[202:205], v199 offset:16384
	ds_read_b128 v[206:209], v199 offset:17408
	ds_read_b128 v[210:213], v199 offset:18432
	ds_read_b128 v[214:217], v199 offset:19456
	ds_read_b128 v[218:221], v199 offset:20480
	ds_read_b128 v[222:225], v199 offset:21504
	ds_read_b128 v[226:229], v199 offset:22528
	ds_read_b128 v[230:233], v199 offset:23552
	global_load_lds_dwordx4 v[180:181], off
	s_add_i32 m0, s78, 0x2000
	s_add_u32 s78, s0, 0x40000
	v_lshl_add_u64 v[182:183], s[0:1], 0, v[168:169]
	s_addc_u32 s79, s1, 0
	s_add_i32 s80, s71, s3
	global_load_lds_dwordx4 v[182:183], off
	v_lshl_add_u64 v[184:185], s[78:79], 0, v[164:165]
	s_mov_b32 m0, s80
	v_lshl_add_u64 v[186:187], s[60:61], 0, v[166:167]
	global_load_lds_dwordx4 v[184:185], off
	v_lshl_add_u64 v[184:185], s[78:79], 0, v[168:169]
	s_add_i32 m0, s80, 0x2000
	s_nop 0
	global_load_lds_dwordx4 v[184:185], off
	v_lshl_add_u64 v[184:185], s[60:61], 0, v[162:163]
	s_mov_b32 m0, s26
	s_nop 0
	global_load_lds_dwordx4 v[184:185], off
	s_mov_b32 m0, s27
	s_nop 0
	global_load_lds_dwordx4 v[186:187], off
	s_waitcnt vmcnt(8)
	s_waitcnt lgkmcnt(0)
	s_barrier
	s_waitcnt lgkmcnt(0)
	v_mfma_f32_16x16x128_f8f6f4 v[94:97], v[26:33], v[202:209], v[94:97]
	v_mfma_f32_16x16x128_f8f6f4 v[90:93], v[18:25], v[202:209], v[90:93]
	v_mfma_f32_16x16x128_f8f6f4 v[78:81], v[26:33], v[210:217], v[78:81]
	v_mfma_f32_16x16x128_f8f6f4 v[74:77], v[18:25], v[210:217], v[74:77]
	v_mfma_f32_16x16x128_f8f6f4 v[62:65], v[26:33], v[218:225], v[62:65]
	v_mfma_f32_16x16x128_f8f6f4 v[58:61], v[18:25], v[218:225], v[58:61]
	v_mfma_f32_16x16x128_f8f6f4 v[46:49], v[26:33], v[226:233], v[46:49]
	v_mfma_f32_16x16x128_f8f6f4 v[42:45], v[18:25], v[226:233], v[42:45]
	v_mfma_f32_16x16x128_f8f6f4 v[86:89], v[10:17], v[202:209], v[86:89]
	v_mfma_f32_16x16x128_f8f6f4 v[82:85], v[2:9], v[202:209], v[82:85]
	v_mfma_f32_16x16x128_f8f6f4 v[70:73], v[10:17], v[210:217], v[70:73]
	v_mfma_f32_16x16x128_f8f6f4 v[66:69], v[2:9], v[210:217], v[66:69]
	v_mfma_f32_16x16x128_f8f6f4 v[54:57], v[10:17], v[218:225], v[54:57]
	v_mfma_f32_16x16x128_f8f6f4 v[50:53], v[2:9], v[218:225], v[50:53]
	v_mfma_f32_16x16x128_f8f6f4 v[38:41], v[10:17], v[226:233], v[38:41]
	v_mfma_f32_16x16x128_f8f6f4 v[34:37], v[2:9], v[226:233], v[34:37]
	s_barrier
	s_add_i32 s78, 0, 0x18000
	s_add_i32 s79, 0, 0x1c000
	v_add_u32_e32 v14, s78, v195
	v_add_u32_e32 v30, s79, v195
	ds_read_b128 v[2:5], v14
	ds_read_b128 v[6:9], v14 offset:1024
	ds_read_b128 v[10:13], v14 offset:2048
	ds_read_b128 v[14:17], v14 offset:3072
	ds_read_b128 v[18:21], v30
	ds_read_b128 v[22:25], v30 offset:1024
	ds_read_b128 v[26:29], v30 offset:2048
	ds_read_b128 v[30:33], v30 offset:3072
	s_add_u32 s60, s60, 0x40000
	s_addc_u32 s61, s61, 0
	s_mov_b32 m0, s33
	v_lshl_add_u64 v[188:189], s[60:61], 0, v[162:163]
	ds_read_b128 v[202:205], v199 offset:32768
	ds_read_b128 v[206:209], v199 offset:33792
	ds_read_b128 v[210:213], v199 offset:34816
	ds_read_b128 v[214:217], v199 offset:35840
	ds_read_b128 v[218:221], v199 offset:36864
	ds_read_b128 v[222:225], v199 offset:37888
	ds_read_b128 v[226:229], v199 offset:38912
	ds_read_b128 v[230:233], v199 offset:39936
	global_load_lds_dwordx4 v[188:189], off
	v_lshl_add_u64 v[188:189], s[60:61], 0, v[166:167]
	s_mov_b32 m0, s34
	s_nop 0
	global_load_lds_dwordx4 v[188:189], off
	s_waitcnt vmcnt(8)
	s_waitcnt lgkmcnt(0)
	s_barrier
	s_waitcnt lgkmcnt(0)
	v_mfma_f32_16x16x128_f8f6f4 v[158:161], v[2:9], v[202:209], v[158:161]
	v_mfma_f32_16x16x128_f8f6f4 v[154:157], v[10:17], v[202:209], v[154:157]
	v_mfma_f32_16x16x128_f8f6f4 v[142:145], v[2:9], v[210:217], v[142:145]
	v_mfma_f32_16x16x128_f8f6f4 v[138:141], v[10:17], v[210:217], v[138:141]
	v_mfma_f32_16x16x128_f8f6f4 v[126:129], v[2:9], v[218:225], v[126:129]
	v_mfma_f32_16x16x128_f8f6f4 v[122:125], v[10:17], v[218:225], v[122:125]
	v_mfma_f32_16x16x128_f8f6f4 v[110:113], v[2:9], v[226:233], v[110:113]
	v_mfma_f32_16x16x128_f8f6f4 v[106:109], v[10:17], v[226:233], v[106:109]
	v_mfma_f32_16x16x128_f8f6f4 v[150:153], v[18:25], v[202:209], v[150:153]
	v_mfma_f32_16x16x128_f8f6f4 v[146:149], v[26:33], v[202:209], v[146:149]
	v_mfma_f32_16x16x128_f8f6f4 v[134:137], v[18:25], v[210:217], v[134:137]
	v_mfma_f32_16x16x128_f8f6f4 v[130:133], v[26:33], v[210:217], v[130:133]
	v_mfma_f32_16x16x128_f8f6f4 v[118:121], v[18:25], v[218:225], v[118:121]
	v_mfma_f32_16x16x128_f8f6f4 v[114:117], v[26:33], v[218:225], v[114:117]
	v_mfma_f32_16x16x128_f8f6f4 v[102:105], v[18:25], v[226:233], v[102:105]
	v_mfma_f32_16x16x128_f8f6f4 v[98:101], v[26:33], v[226:233], v[98:101]
	s_barrier
	s_add_i32 s60, s78, s3
	v_lshl_add_u64 v[180:181], v[180:181], 0, s[36:37]
	s_mov_b32 m0, s60
	ds_read_b128 v[202:205], v199 offset:49152
	ds_read_b128 v[206:209], v199 offset:50176
	ds_read_b128 v[210:213], v199 offset:51200
	ds_read_b128 v[214:217], v199 offset:52224
	ds_read_b128 v[218:221], v199 offset:53248
	ds_read_b128 v[222:225], v199 offset:54272
	ds_read_b128 v[226:229], v199 offset:55296
	ds_read_b128 v[230:233], v199 offset:56320
	global_load_lds_dwordx4 v[180:181], off
	s_add_i32 m0, s60, 0x2000
	s_add_u32 s0, s0, 0x40080
	v_lshl_add_u64 v[180:181], v[182:183], 0, s[36:37]
	s_addc_u32 s1, s1, 0
	s_add_i32 s60, s79, s3
	global_load_lds_dwordx4 v[180:181], off
	v_lshl_add_u64 v[180:181], s[0:1], 0, v[164:165]
	s_mov_b32 m0, s60
	s_nop 0
	global_load_lds_dwordx4 v[180:181], off
	v_lshl_add_u64 v[180:181], s[0:1], 0, v[168:169]
	s_add_i32 m0, s60, 0x2000
	s_nop 0
	global_load_lds_dwordx4 v[180:181], off
	v_lshl_add_u64 v[180:181], v[184:185], 0, s[36:37]
	s_mov_b32 m0, s64
	s_nop 0
	global_load_lds_dwordx4 v[180:181], off
	v_lshl_add_u64 v[180:181], v[186:187], 0, s[36:37]
	s_mov_b32 m0, s65
	s_nop 0
	global_load_lds_dwordx4 v[180:181], off
	s_waitcnt vmcnt(8)
	s_waitcnt lgkmcnt(0)
	s_barrier
	s_waitcnt lgkmcnt(0)
	v_mfma_f32_16x16x128_f8f6f4 v[94:97], v[2:9], v[202:209], v[94:97]
	v_mfma_f32_16x16x128_f8f6f4 v[90:93], v[10:17], v[202:209], v[90:93]
	v_mfma_f32_16x16x128_f8f6f4 v[78:81], v[2:9], v[210:217], v[78:81]
	v_mfma_f32_16x16x128_f8f6f4 v[74:77], v[10:17], v[210:217], v[74:77]
	v_mfma_f32_16x16x128_f8f6f4 v[62:65], v[2:9], v[218:225], v[62:65]
	v_mfma_f32_16x16x128_f8f6f4 v[58:61], v[10:17], v[218:225], v[58:61]
	v_mfma_f32_16x16x128_f8f6f4 v[46:49], v[2:9], v[226:233], v[46:49]
	v_mfma_f32_16x16x128_f8f6f4 v[42:45], v[10:17], v[226:233], v[42:45]
	v_mfma_f32_16x16x128_f8f6f4 v[86:89], v[18:25], v[202:209], v[86:89]
	v_mfma_f32_16x16x128_f8f6f4 v[82:85], v[26:33], v[202:209], v[82:85]
	v_mfma_f32_16x16x128_f8f6f4 v[70:73], v[18:25], v[210:217], v[70:73]
	v_mfma_f32_16x16x128_f8f6f4 v[66:69], v[26:33], v[210:217], v[66:69]
	v_mfma_f32_16x16x128_f8f6f4 v[54:57], v[18:25], v[218:225], v[54:57]
	v_mfma_f32_16x16x128_f8f6f4 v[50:53], v[26:33], v[218:225], v[50:53]
	v_mfma_f32_16x16x128_f8f6f4 v[38:41], v[18:25], v[226:233], v[38:41]
	v_mfma_f32_16x16x128_f8f6f4 v[34:37], v[26:33], v[226:233], v[34:37]
	s_barrier
	s_add_i32 s77, s77, 2
	s_add_u32 s58, s58, 0x100
	s_addc_u32 s59, s59, 0
	s_add_u32 s75, s75, 0x100
	s_addc_u32 s76, s76, 0
	s_cmp_gt_u32 s77, 13
	s_cbranch_scc0 .LBB0_967
	s_and_b64 vcc, exec, s[38:39]
	s_cbranch_vccz .LBB0_970
	s_barrier

.LBB0_1072:
	ds_read_b128 v[26:29], v190
	ds_read_b128 v[30:33], v190 offset:1024
	ds_read_b128 v[18:21], v190 offset:2048
	ds_read_b128 v[22:25], v190 offset:3072
	ds_read_b128 v[10:13], v191
	ds_read_b128 v[14:17], v191 offset:1024
	ds_read_b128 v[2:5], v191 offset:2048
	ds_read_b128 v[6:9], v191 offset:3072
	s_add_u32 s0, s36, 0xfffc0080
	s_addc_u32 s1, s37, -1
	s_cmp_eq_u32 s52, 12
	s_cselect_b32 s39, s23, s1
	s_cselect_b32 s38, s48, s0
	s_cselect_b32 s1, s19, s51
	s_cselect_b32 s0, s49, s50
	v_lshl_add_u64 v[220:221], s[36:37], 0, v[172:173]
	s_add_i32 m0, s25, 0xc000
	ds_read_b128 v[180:183], v192
	ds_read_b128 v[184:187], v192 offset:1024
	ds_read_b128 v[196:199], v192 offset:2048
	ds_read_b128 v[200:203], v192 offset:3072
	ds_read_b128 v[204:207], v192 offset:4096
	ds_read_b128 v[208:211], v192 offset:5120
	ds_read_b128 v[212:215], v192 offset:6144
	ds_read_b128 v[216:219], v192 offset:7168
	global_load_lds_dwordx4 v[220:221], off
	v_lshl_add_u64 v[220:221], s[36:37], 0, v[174:175]
	s_add_i32 m0, s25, 0xe000
	s_nop 0
	global_load_lds_dwordx4 v[220:221], off
	s_waitcnt vmcnt(8)
	s_waitcnt lgkmcnt(0)
	s_barrier
	s_waitcnt lgkmcnt(0)
	v_mfma_f32_16x16x128_f8f6f4 v[158:161], v[26:33], v[180:187], v[158:161]
	v_mfma_f32_16x16x128_f8f6f4 v[154:157], v[18:25], v[180:187], v[154:157]
	v_mfma_f32_16x16x128_f8f6f4 v[142:145], v[26:33], v[196:203], v[142:145]
	v_mfma_f32_16x16x128_f8f6f4 v[138:141], v[18:25], v[196:203], v[138:141]
	v_mfma_f32_16x16x128_f8f6f4 v[126:129], v[26:33], v[204:211], v[126:129]
	v_mfma_f32_16x16x128_f8f6f4 v[122:125], v[18:25], v[204:211], v[122:125]
	v_mfma_f32_16x16x128_f8f6f4 v[110:113], v[26:33], v[212:219], v[110:113]
	v_mfma_f32_16x16x128_f8f6f4 v[106:109], v[18:25], v[212:219], v[106:109]
	v_mfma_f32_16x16x128_f8f6f4 v[150:153], v[10:17], v[180:187], v[150:153]
	v_mfma_f32_16x16x128_f8f6f4 v[146:149], v[2:9], v[180:187], v[146:149]
	v_mfma_f32_16x16x128_f8f6f4 v[134:137], v[10:17], v[196:203], v[134:137]
	v_mfma_f32_16x16x128_f8f6f4 v[130:133], v[2:9], v[196:203], v[130:133]
	v_mfma_f32_16x16x128_f8f6f4 v[118:121], v[10:17], v[204:211], v[118:121]
	v_mfma_f32_16x16x128_f8f6f4 v[114:117], v[2:9], v[204:211], v[114:117]
	v_mfma_f32_16x16x128_f8f6f4 v[102:105], v[10:17], v[212:219], v[102:105]
	v_mfma_f32_16x16x128_f8f6f4 v[98:101], v[2:9], v[212:219], v[98:101]
	s_barrier
	s_add_i32 s53, s45, s21
	v_lshl_add_u64 v[180:181], s[0:1], 0, v[166:167]
	s_mov_b32 m0, s53
	ds_read_b128 v[196:199], v192 offset:16384
	ds_read_b128 v[200:203], v192 offset:17408
	ds_read_b128 v[204:207], v192 offset:18432
	ds_read_b128 v[208:211], v192 offset:19456
	ds_read_b128 v[212:215], v192 offset:20480
	ds_read_b128 v[216:219], v192 offset:21504
	ds_read_b128 v[220:223], v192 offset:22528
	ds_read_b128 v[224:227], v192 offset:23552
	global_load_lds_dwordx4 v[180:181], off
	s_add_i32 m0, s53, 0x2000
	s_add_u32 s54, s0, 0x40000
	v_lshl_add_u64 v[182:183], s[0:1], 0, v[162:163]
	s_addc_u32 s55, s1, 0
	s_add_i32 s53, s46, s21
	global_load_lds_dwordx4 v[182:183], off
	v_lshl_add_u64 v[184:185], s[54:55], 0, v[166:167]
	s_mov_b32 m0, s53
	v_lshl_add_u64 v[186:187], s[38:39], 0, v[164:165]
	global_load_lds_dwordx4 v[184:185], off
	v_lshl_add_u64 v[184:185], s[54:55], 0, v[162:163]
	s_add_i32 m0, s53, 0x2000
	s_nop 0
	global_load_lds_dwordx4 v[184:185], off
	v_lshl_add_u64 v[184:185], s[38:39], 0, v[168:169]
	s_mov_b32 m0, s25
	s_nop 0
	global_load_lds_dwordx4 v[184:185], off
	s_mov_b32 m0, s26
	s_nop 0
	global_load_lds_dwordx4 v[186:187], off
	s_waitcnt vmcnt(8)
	s_waitcnt lgkmcnt(0)
	s_barrier
	s_waitcnt lgkmcnt(0)
	v_mfma_f32_16x16x128_f8f6f4 v[94:97], v[26:33], v[196:203], v[94:97]
	v_mfma_f32_16x16x128_f8f6f4 v[90:93], v[18:25], v[196:203], v[90:93]
	v_mfma_f32_16x16x128_f8f6f4 v[78:81], v[26:33], v[204:211], v[78:81]
	v_mfma_f32_16x16x128_f8f6f4 v[74:77], v[18:25], v[204:211], v[74:77]
	v_mfma_f32_16x16x128_f8f6f4 v[62:65], v[26:33], v[212:219], v[62:65]
	v_mfma_f32_16x16x128_f8f6f4 v[58:61], v[18:25], v[212:219], v[58:61]
	v_mfma_f32_16x16x128_f8f6f4 v[46:49], v[26:33], v[220:227], v[46:49]
	v_mfma_f32_16x16x128_f8f6f4 v[42:45], v[18:25], v[220:227], v[42:45]
	v_mfma_f32_16x16x128_f8f6f4 v[86:89], v[10:17], v[196:203], v[86:89]
	v_mfma_f32_16x16x128_f8f6f4 v[82:85], v[2:9], v[196:203], v[82:85]
	v_mfma_f32_16x16x128_f8f6f4 v[70:73], v[10:17], v[204:211], v[70:73]
	v_mfma_f32_16x16x128_f8f6f4 v[66:69], v[2:9], v[204:211], v[66:69]
	v_mfma_f32_16x16x128_f8f6f4 v[54:57], v[10:17], v[212:219], v[54:57]
	v_mfma_f32_16x16x128_f8f6f4 v[50:53], v[2:9], v[212:219], v[50:53]
	v_mfma_f32_16x16x128_f8f6f4 v[38:41], v[10:17], v[220:227], v[38:41]
	v_mfma_f32_16x16x128_f8f6f4 v[34:37], v[2:9], v[220:227], v[34:37]
	s_barrier
	s_add_i32 s53, 0, 0x18000
	s_add_i32 s54, 0, 0x1c000
	v_add_u32_e32 v14, s53, v188
	v_add_u32_e32 v30, s54, v188
	ds_read_b128 v[2:5], v14
	ds_read_b128 v[6:9], v14 offset:1024
	ds_read_b128 v[10:13], v14 offset:2048
	ds_read_b128 v[14:17], v14 offset:3072
	ds_read_b128 v[18:21], v30
	ds_read_b128 v[22:25], v30 offset:1024
	ds_read_b128 v[26:29], v30 offset:2048
	ds_read_b128 v[30:33], v30 offset:3072
	s_add_u32 s38, s38, 0x40000
	s_addc_u32 s39, s39, 0
	s_mov_b32 m0, s27
	v_lshl_add_u64 v[228:229], s[38:39], 0, v[168:169]
	ds_read_b128 v[196:199], v192 offset:32768
	ds_read_b128 v[200:203], v192 offset:33792
	ds_read_b128 v[204:207], v192 offset:34816
	ds_read_b128 v[208:211], v192 offset:35840
	ds_read_b128 v[212:215], v192 offset:36864
	ds_read_b128 v[216:219], v192 offset:37888
	ds_read_b128 v[220:223], v192 offset:38912
	ds_read_b128 v[224:227], v192 offset:39936
	global_load_lds_dwordx4 v[228:229], off
	v_lshl_add_u64 v[228:229], s[38:39], 0, v[164:165]
	s_mov_b32 m0, s33
	s_nop 0
	global_load_lds_dwordx4 v[228:229], off
	s_waitcnt vmcnt(8)
	s_waitcnt lgkmcnt(0)
	s_barrier
	s_waitcnt lgkmcnt(0)
	v_mfma_f32_16x16x128_f8f6f4 v[158:161], v[2:9], v[196:203], v[158:161]
	v_mfma_f32_16x16x128_f8f6f4 v[154:157], v[10:17], v[196:203], v[154:157]
	v_mfma_f32_16x16x128_f8f6f4 v[142:145], v[2:9], v[204:211], v[142:145]
	v_mfma_f32_16x16x128_f8f6f4 v[138:141], v[10:17], v[204:211], v[138:141]
	v_mfma_f32_16x16x128_f8f6f4 v[126:129], v[2:9], v[212:219], v[126:129]
	v_mfma_f32_16x16x128_f8f6f4 v[122:125], v[10:17], v[212:219], v[122:125]
	v_mfma_f32_16x16x128_f8f6f4 v[110:113], v[2:9], v[220:227], v[110:113]
	v_mfma_f32_16x16x128_f8f6f4 v[106:109], v[10:17], v[220:227], v[106:109]
	v_mfma_f32_16x16x128_f8f6f4 v[150:153], v[18:25], v[196:203], v[150:153]
	v_mfma_f32_16x16x128_f8f6f4 v[146:149], v[26:33], v[196:203], v[146:149]
	v_mfma_f32_16x16x128_f8f6f4 v[134:137], v[18:25], v[204:211], v[134:137]
	v_mfma_f32_16x16x128_f8f6f4 v[130:133], v[26:33], v[204:211], v[130:133]
	v_mfma_f32_16x16x128_f8f6f4 v[118:121], v[18:25], v[212:219], v[118:121]
	v_mfma_f32_16x16x128_f8f6f4 v[114:117], v[26:33], v[212:219], v[114:117]
	v_mfma_f32_16x16x128_f8f6f4 v[102:105], v[18:25], v[220:227], v[102:105]
	v_mfma_f32_16x16x128_f8f6f4 v[98:101], v[26:33], v[220:227], v[98:101]
	s_barrier
	s_add_i32 s38, s53, s21
	v_lshl_add_u64 v[180:181], v[180:181], 0, s[12:13]
	s_mov_b32 m0, s38
	ds_read_b128 v[196:199], v192 offset:49152
	ds_read_b128 v[200:203], v192 offset:50176
	ds_read_b128 v[204:207], v192 offset:51200
	ds_read_b128 v[208:211], v192 offset:52224
	ds_read_b128 v[212:215], v192 offset:53248
	ds_read_b128 v[216:219], v192 offset:54272
	ds_read_b128 v[220:223], v192 offset:55296
	ds_read_b128 v[224:227], v192 offset:56320
	global_load_lds_dwordx4 v[180:181], off
	s_add_i32 m0, s38, 0x2000
	s_add_u32 s0, s0, 0x40080
	v_lshl_add_u64 v[180:181], v[182:183], 0, s[12:13]
	s_addc_u32 s1, s1, 0
	s_add_i32 s38, s54, s21
	global_load_lds_dwordx4 v[180:181], off
	v_lshl_add_u64 v[180:181], s[0:1], 0, v[166:167]
	s_mov_b32 m0, s38
	s_nop 0
	global_load_lds_dwordx4 v[180:181], off
	v_lshl_add_u64 v[180:181], s[0:1], 0, v[162:163]
	s_add_i32 m0, s38, 0x2000
	s_nop 0
	global_load_lds_dwordx4 v[180:181], off
	v_lshl_add_u64 v[180:181], v[184:185], 0, s[12:13]
	s_mov_b32 m0, s41
	s_nop 0
	global_load_lds_dwordx4 v[180:181], off
	v_lshl_add_u64 v[180:181], v[186:187], 0, s[12:13]
	s_mov_b32 m0, s42
	s_nop 0
	global_load_lds_dwordx4 v[180:181], off
	s_waitcnt vmcnt(8)
	s_waitcnt lgkmcnt(0)
	s_barrier
	s_waitcnt lgkmcnt(0)
	v_mfma_f32_16x16x128_f8f6f4 v[94:97], v[2:9], v[196:203], v[94:97]
	v_mfma_f32_16x16x128_f8f6f4 v[90:93], v[10:17], v[196:203], v[90:93]
	v_mfma_f32_16x16x128_f8f6f4 v[78:81], v[2:9], v[204:211], v[78:81]
	v_mfma_f32_16x16x128_f8f6f4 v[74:77], v[10:17], v[204:211], v[74:77]
	v_mfma_f32_16x16x128_f8f6f4 v[62:65], v[2:9], v[212:219], v[62:65]
	v_mfma_f32_16x16x128_f8f6f4 v[58:61], v[10:17], v[212:219], v[58:61]
	v_mfma_f32_16x16x128_f8f6f4 v[46:49], v[2:9], v[220:227], v[46:49]
	v_mfma_f32_16x16x128_f8f6f4 v[42:45], v[10:17], v[220:227], v[42:45]
	v_mfma_f32_16x16x128_f8f6f4 v[86:89], v[18:25], v[196:203], v[86:89]
	v_mfma_f32_16x16x128_f8f6f4 v[82:85], v[26:33], v[196:203], v[82:85]
	v_mfma_f32_16x16x128_f8f6f4 v[70:73], v[18:25], v[204:211], v[70:73]
	v_mfma_f32_16x16x128_f8f6f4 v[66:69], v[26:33], v[204:211], v[66:69]
	v_mfma_f32_16x16x128_f8f6f4 v[54:57], v[18:25], v[212:219], v[54:57]
	v_mfma_f32_16x16x128_f8f6f4 v[50:53], v[26:33], v[212:219], v[50:53]
	v_mfma_f32_16x16x128_f8f6f4 v[38:41], v[18:25], v[220:227], v[38:41]
	v_mfma_f32_16x16x128_f8f6f4 v[34:37], v[26:33], v[220:227], v[34:37]
	s_barrier
	s_add_i32 s52, s52, 2
	s_add_u32 s36, s36, 0x100
	s_addc_u32 s37, s37, 0
	s_add_u32 s50, s50, 0x100
	s_addc_u32 s51, s51, 0
	s_cmp_gt_u32 s52, 13
	s_cbranch_scc0 .LBB0_1072
	s_and_b64 vcc, exec, s[14:15]
	s_cbranch_vccz .LBB0_1075
	s_barrier
.LBB0_1075:
	s_nop 15
	s_nop 15
	v_lshl_add_u32 v8, s6, 8, v1
	v_ashrrev_i32_e32 v9, 31, v8
	v_lshlrev_b64 v[2:3], 7, v[8:9]
	v_lshl_add_u64 v[2:3], v[170:171], 0, v[2:3]
	global_load_dwordx4 v[12:15], v[2:3], off
	global_load_dwordx4 v[16:19], v[2:3], off offset:16
	v_mov_b64_e32 v[242:243], v[2:3]
	s_mov_b64 s[100:101], 0x1000
	v_lshl_add_u64 v[240:241], v[2:3], 0, s[100:101]
	global_load_dwordx4 v[208:211], v[240:241], off offset:-2032
	global_load_dwordx4 v[212:215], v[240:241], off
	global_load_dwordx4 v[216:219], v[240:241], off offset:16
	global_load_dwordx4 v[220:223], v[240:241], off offset:2048
	global_load_dwordx4 v[224:227], v[240:241], off offset:2064
	v_or_b32_e32 v28, 16, v8
	v_ashrrev_i32_e32 v29, 31, v28
	v_lshlrev_b64 v[2:3], 7, v[28:29]
	v_lshl_add_u64 v[24:25], v[170:171], 0, v[2:3]
	global_load_dwordx4 v[2:5], v[24:25], off
	s_lshl_b32 s0, s6, 2
	v_lshl_or_b32 v6, s7, 8, v189
	s_ashr_i32 s1, s6, 5
	s_add_i32 s7, s43, s0
	s_add_i32 s19, s44, s0
	s_cmpk_lt_i32 s6, 0x80
	s_cselect_b32 s0, s1, s7
	s_cselect_b32 s6, s1, s19
	s_ashr_i32 s1, s0, 31
	s_ashr_i32 s7, s6, 31
	s_lshl_b64 s[36:37], s[0:1], 15
	s_lshl_b64 s[0:1], s[6:7], 15
	v_ashrrev_i32_e32 v7, 31, v6
	s_add_u32 s0, s35, s0
	s_addc_u32 s1, s40, s1
	v_lshlrev_b64 v[10:11], 2, v[6:7]
	v_lshl_add_u64 v[26:27], s[0:1], 0, v[10:11]
	global_load_dwordx4 v[20:23], v[26:27], off
	global_load_dwordx4 v[30:33], v[26:27], off offset:16
	global_load_dwordx4 v[180:183], v[26:27], off offset:512
	global_load_dwordx4 v[184:187], v[26:27], off offset:528
	v_lshlrev_b64 v[26:27], 13, v[8:9]
	v_lshl_add_u64 v[26:27], s[10:11], 0, v[26:27]
	v_lshl_add_u64 v[204:205], v[26:27], 0, v[6:7]
	v_mov_b32_e32 v200, 0
	v_mov_b32_e32 v201, 0
	v_mov_b32_e32 v202, 0
	v_mov_b32_e32 v203, 0
	v_lshlrev_b64 v[28:29], 13, v[28:29]
	v_lshl_add_u64 v[28:29], s[10:11], 0, v[28:29]
	v_lshl_add_u64 v[28:29], v[28:29], 0, v[6:7]
	s_waitcnt vmcnt(0)
	v_mov_b32_e32 v196, v12
	v_mov_b32_e32 v197, v16
	v_mov_b32_e32 v16, v13
	v_mov_b32_e32 v12, v14
	v_mov_b32_e32 v13, v18
	v_mov_b32_e32 v18, v15
	v_pk_add_f32 v[14:15], v[196:197], v[16:17]
	v_mov_b64_e32 v[196:197], v[208:209]
	v_mov_b64_e32 v[198:199], v[210:211]
	v_pk_add_f32 v[12:13], v[12:13], v[18:19]
	v_mov_b32_e32 v206, v2
	v_pk_add_f32 v[12:13], v[14:15], v[12:13]
	v_pk_mul_f32 v[24:25], v[22:23], s[16:17] op_sel_hi:[1,0]
	v_add_f32_e32 v9, v12, v13
	ds_bpermute_b32 v12, v238, v9
	v_pk_mul_f32 v[22:23], v[30:31], s[16:17] op_sel_hi:[1,0]
	v_pk_mul_f32 v[26:27], v[20:21], s[16:17] op_sel_hi:[1,0]
	v_pk_mul_f32 v[20:21], v[32:33], s[16:17] op_sel_hi:[1,0]
	v_pk_mul_f32 v[16:17], v[180:181], s[16:17] op_sel_hi:[1,0]
	s_waitcnt lgkmcnt(0)
	v_add_f32_e32 v2, v9, v12
	ds_bpermute_b32 v9, v239, v2
	v_pk_mul_f32 v[14:15], v[182:183], s[16:17] op_sel_hi:[1,0]
	v_pk_mul_f32 v[12:13], v[186:187], s[16:17] op_sel_hi:[1,0]
	s_waitcnt lgkmcnt(0)
	v_add_f32_e32 v2, v2, v9
	v_fmamk_f32 v2, v2, 0x3a000000, v193
	v_mul_f32_e32 v9, 0x4f800000, v2
	v_cmp_gt_f32_e32 vcc, s47, v2
	v_mov_b32_e32 v207, v196
	v_cndmask_b32_e32 v2, v2, v9, vcc
	v_sqrt_f32_e32 v9, v2
	v_mov_b32_e32 v196, v3
	v_add_u32_e32 v18, -1, v9
	v_add_u32_e32 v19, 1, v9
	v_fma_f32 v30, -v18, v9, v2
	v_fma_f32 v31, -v19, v9, v2
	v_cmp_ge_f32_e64 s[6:7], 0, v30
	s_nop 1
	v_cndmask_b32_e64 v9, v9, v18, s[6:7]
	v_cmp_lt_f32_e64 s[6:7], 0, v31
	s_nop 1
	v_cndmask_b32_e64 v9, v9, v19, s[6:7]
	v_mul_f32_e32 v18, 0x37800000, v9
	v_cndmask_b32_e32 v9, v9, v18, vcc
	v_cmp_class_f32_e32 vcc, v2, v194
	v_pk_mul_f32 v[18:19], v[184:185], s[16:17] op_sel_hi:[1,0]
	s_nop 0
	v_cndmask_b32_e32 v2, v9, v2, vcc
	v_div_scale_f32 v9, s[0:1], v2, v2, 1.0
	v_rcp_f32_e32 v30, v9
	v_div_scale_f32 v31, vcc, 1.0, v2, 1.0
	v_fma_f32 v32, -v9, v30, 1.0
	v_fmac_f32_e32 v30, v32, v30
	v_mul_f32_e32 v32, v31, v30
	v_fma_f32 v33, -v9, v32, v31
	v_fmac_f32_e32 v32, v33, v30
	v_fma_f32 v9, -v9, v32, v31
	v_div_fmas_f32 v9, v9, v30, v32
	v_div_fixup_f32 v2, v9, v2, 1.0
	v_mul_f32_e32 v2, 0x3bb504f3, v2
	v_pk_fma_f32 v[32:33], v[158:159], v[2:3], v[26:27] op_sel_hi:[1,0,1]
	v_pk_fma_f32 v[30:31], v[160:161], v[2:3], v[24:25] op_sel_hi:[1,0,1]
	v_med3_f32 v32, v32, 0, v195
	v_med3_f32 v33, v33, 0, v195
	v_pk_mul_f32 v[32:33], v[32:33], v[32:33]
	v_med3_f32 v30, v30, 0, v195
	v_cvt_pk_fp8_f32 v200, v32, v33
	v_med3_f32 v31, v31, 0, v195
	v_pk_fma_f32 v[154:155], v[154:155], v[2:3], v[22:23] op_sel_hi:[1,0,1]
	v_pk_mul_f32 v[30:31], v[30:31], v[30:31]
	v_pk_fma_f32 v[150:151], v[150:151], v[2:3], v[16:17] op_sel_hi:[1,0,1]
	v_pk_fma_f32 v[146:147], v[146:147], v[2:3], v[18:19] op_sel_hi:[1,0,1]
	v_med3_f32 v154, v154, 0, v195
	v_med3_f32 v155, v155, 0, v195
	v_cvt_pk_fp8_f32 v200, v30, v31 op_sel:[0,0,1]
	v_mov_b32_e32 v30, v4
	v_mov_b32_e32 v31, v198
	v_mov_b32_e32 v198, v5
	v_pk_fma_f32 v[156:157], v[156:157], v[2:3], v[20:21] op_sel_hi:[1,0,1]
	v_pk_fma_f32 v[152:153], v[152:153], v[2:3], v[14:15] op_sel_hi:[1,0,1]
	v_pk_fma_f32 v[148:149], v[148:149], v[2:3], v[12:13] op_sel_hi:[1,0,1]
	v_med3_f32 v150, v150, 0, v195
	v_med3_f32 v146, v146, 0, v195
	v_med3_f32 v151, v151, 0, v195
	v_med3_f32 v147, v147, 0, v195
	v_pk_mul_f32 v[154:155], v[154:155], v[154:155]
	v_pk_add_f32 v[2:3], v[206:207], v[196:197]
	v_pk_add_f32 v[4:5], v[30:31], v[198:199]
	v_pk_mul_f32 v[150:151], v[150:151], v[150:151]
	v_pk_mul_f32 v[146:147], v[146:147], v[146:147]
	v_cvt_pk_fp8_f32 v201, v154, v155
	v_pk_add_f32 v[2:3], v[2:3], v[4:5]
	v_cvt_pk_fp8_f32 v202, v150, v151
	v_cvt_pk_fp8_f32 v203, v146, v147
	v_add_f32_e32 v2, v2, v3
	v_med3_f32 v156, v156, 0, v195
	v_med3_f32 v157, v157, 0, v195
	ds_bpermute_b32 v3, v238, v2
	v_med3_f32 v152, v152, 0, v195
	v_med3_f32 v148, v148, 0, v195
	v_med3_f32 v153, v153, 0, v195
	v_med3_f32 v149, v149, 0, v195
	v_pk_mul_f32 v[156:157], v[156:157], v[156:157]
	v_pk_mul_f32 v[152:153], v[152:153], v[152:153]
	v_pk_mul_f32 v[148:149], v[148:149], v[148:149]
	v_cvt_pk_fp8_f32 v201, v156, v157 op_sel:[0,0,1]
	v_cvt_pk_fp8_f32 v202, v152, v153 op_sel:[0,0,1]
	v_cvt_pk_fp8_f32 v203, v148, v149 op_sel:[0,0,1]
	v_or_b32_e32 v146, 32, v8
	v_ashrrev_i32_e32 v147, 31, v146
	s_waitcnt lgkmcnt(0)
	v_add_f32_e32 v9, v2, v3
	v_lshlrev_b64 v[2:3], 7, v[146:147]
	global_store_dwordx2 v[204:205], v[200:201], off
	global_store_dwordx2 v[204:205], v[202:203], off offset:128
	v_lshl_add_u64 v[30:31], v[170:171], 0, v[2:3]
	v_mov_b64_e32 v[2:3], v[212:213]
	v_mov_b64_e32 v[4:5], v[214:215]
	s_nop 0
	v_mov_b64_e32 v[30:31], v[216:217]
	v_mov_b64_e32 v[32:33], v[218:219]
	ds_bpermute_b32 v148, v239, v9
	s_waitcnt lgkmcnt(0)
	v_add_f32_e32 v9, v9, v148
	v_fmamk_f32 v9, v9, 0x3a000000, v193
	v_mul_f32_e32 v148, 0x4f800000, v9
	v_cmp_gt_f32_e32 vcc, s47, v9
	s_nop 1
	v_cndmask_b32_e32 v9, v9, v148, vcc
	v_sqrt_f32_e32 v148, v9
	s_nop 0
	v_add_u32_e32 v149, -1, v148
	v_fma_f32 v150, -v149, v148, v9
	v_cmp_ge_f32_e64 s[6:7], 0, v150
	v_add_u32_e32 v150, 1, v148
	s_nop 0
	v_cndmask_b32_e64 v149, v148, v149, s[6:7]
	v_fma_f32 v148, -v150, v148, v9
	v_cmp_lt_f32_e64 s[6:7], 0, v148
	s_nop 1
	v_cndmask_b32_e64 v148, v149, v150, s[6:7]
	v_mul_f32_e32 v149, 0x37800000, v148
	v_cndmask_b32_e32 v148, v148, v149, vcc
	v_cmp_class_f32_e32 vcc, v9, v194
	s_nop 1
	v_cndmask_b32_e32 v9, v148, v9, vcc
	v_div_scale_f32 v148, s[0:1], v9, v9, 1.0
	v_rcp_f32_e32 v149, v148
	s_nop 0
	v_fma_f32 v150, -v148, v149, 1.0
	v_fmac_f32_e32 v149, v150, v149
	v_div_scale_f32 v150, vcc, 1.0, v9, 1.0
	v_mul_f32_e32 v151, v150, v149
	v_fma_f32 v152, -v148, v151, v150
	v_fmac_f32_e32 v151, v152, v149
	v_fma_f32 v148, -v148, v151, v150
	v_div_fmas_f32 v148, v148, v149, v151
	v_div_fixup_f32 v9, v148, v9, 1.0
	v_mul_f32_e32 v148, 0x3bb504f3, v9
	v_pk_fma_f32 v[142:143], v[142:143], v[148:149], v[26:27] op_sel_hi:[1,0,1]
	v_mov_b32_e32 v150, 0
	v_med3_f32 v142, v142, 0, v195
	v_med3_f32 v143, v143, 0, v195
	v_pk_mul_f32 v[142:143], v[142:143], v[142:143]
	v_pk_fma_f32 v[138:139], v[138:139], v[148:149], v[22:23] op_sel_hi:[1,0,1]
	v_cvt_pk_fp8_f32 v150, v142, v143
	v_pk_fma_f32 v[144:145], v[144:145], v[148:149], v[24:25] op_sel_hi:[1,0,1]
	v_med3_f32 v138, v138, 0, v195
	v_med3_f32 v139, v139, 0, v195
	v_med3_f32 v144, v144, 0, v195
	v_med3_f32 v145, v145, 0, v195
	v_pk_mul_f32 v[138:139], v[138:139], v[138:139]
	v_mov_b32_e32 v151, 0
	v_pk_fma_f32 v[130:131], v[130:131], v[148:149], v[18:19] op_sel_hi:[1,0,1]
	v_cvt_pk_fp8_f32 v151, v138, v139
	v_pk_mul_f32 v[138:139], v[144:145], v[144:145]
	v_med3_f32 v130, v130, 0, v195
	v_med3_f32 v131, v131, 0, v195
	v_cvt_pk_fp8_f32 v150, v138, v139 op_sel:[0,0,1]
	v_pk_mul_f32 v[130:131], v[130:131], v[130:131]
	v_mov_b32_e32 v139, 0
	v_cvt_pk_fp8_f32 v139, v130, v131
	v_pk_fma_f32 v[134:135], v[134:135], v[148:149], v[16:17] op_sel_hi:[1,0,1]
	v_mov_b32_e32 v138, 0
	v_med3_f32 v134, v134, 0, v195
	v_med3_f32 v135, v135, 0, v195
	v_pk_mul_f32 v[134:135], v[134:135], v[134:135]
	v_mov_b32_e32 v130, v2
	v_mov_b32_e32 v131, v30
	v_mov_b32_e32 v30, v3
	v_pk_add_f32 v[2:3], v[130:131], v[30:31]
	v_mov_b32_e32 v30, v4
	v_mov_b32_e32 v31, v32
	v_mov_b32_e32 v32, v5
	v_pk_add_f32 v[4:5], v[30:31], v[32:33]
	v_cvt_pk_fp8_f32 v138, v134, v135
	v_pk_add_f32 v[2:3], v[2:3], v[4:5]
	v_pk_fma_f32 v[140:141], v[140:141], v[148:149], v[20:21] op_sel_hi:[1,0,1]
	v_add_f32_e32 v4, v2, v3
	ds_bpermute_b32 v5, v238, v4
	v_pk_fma_f32 v[136:137], v[136:137], v[148:149], v[14:15] op_sel_hi:[1,0,1]
	v_pk_fma_f32 v[132:133], v[132:133], v[148:149], v[12:13] op_sel_hi:[1,0,1]
	v_med3_f32 v140, v140, 0, v195
	v_med3_f32 v141, v141, 0, v195
	s_waitcnt lgkmcnt(0)
	v_add_f32_e32 v4, v4, v5
	ds_bpermute_b32 v5, v239, v4
	v_med3_f32 v136, v136, 0, v195
	v_med3_f32 v132, v132, 0, v195
	v_med3_f32 v137, v137, 0, v195
	v_med3_f32 v133, v133, 0, v195
	v_pk_mul_f32 v[140:141], v[140:141], v[140:141]
	v_pk_mul_f32 v[136:137], v[136:137], v[136:137]
	v_pk_mul_f32 v[2:3], v[132:133], v[132:133]
	v_cvt_pk_fp8_f32 v151, v140, v141 op_sel:[0,0,1]
	v_cvt_pk_fp8_f32 v138, v136, v137 op_sel:[0,0,1]
	v_cvt_pk_fp8_f32 v139, v2, v3 op_sel:[0,0,1]
	v_or_b32_e32 v32, 48, v8
	v_ashrrev_i32_e32 v33, 31, v32
	s_waitcnt lgkmcnt(0)
	v_add_f32_e32 v4, v4, v5
	v_lshlrev_b64 v[2:3], 7, v[32:33]
	v_fmamk_f32 v4, v4, 0x3a000000, v193
	global_store_dwordx2 v[28:29], v[150:151], off
	global_store_dwordx2 v[28:29], v[138:139], off offset:128
	v_mul_f32_e32 v5, 0x4f800000, v4
	v_cmp_gt_f32_e32 vcc, s47, v4
	v_lshl_add_u64 v[28:29], v[170:171], 0, v[2:3]
	s_nop 0
	v_cndmask_b32_e32 v9, v4, v5, vcc
	v_mov_b64_e32 v[2:3], v[220:221]
	v_mov_b64_e32 v[4:5], v[222:223]
	s_nop 0
	v_mov_b64_e32 v[28:29], v[224:225]
	v_mov_b64_e32 v[30:31], v[226:227]
	v_sqrt_f32_e32 v130, v9
	s_nop 0
	v_add_u32_e32 v131, -1, v130
	v_fma_f32 v132, -v131, v130, v9
	v_cmp_ge_f32_e64 s[6:7], 0, v132
	v_add_u32_e32 v132, 1, v130
	s_nop 0
	v_cndmask_b32_e64 v131, v130, v131, s[6:7]
	v_fma_f32 v130, -v132, v130, v9
	v_cmp_lt_f32_e64 s[6:7], 0, v130
	s_nop 1
	v_cndmask_b32_e64 v130, v131, v132, s[6:7]
	v_mul_f32_e32 v131, 0x37800000, v130
	v_cndmask_b32_e32 v130, v130, v131, vcc
	v_cmp_class_f32_e32 vcc, v9, v194
	s_nop 1
	v_cndmask_b32_e32 v9, v130, v9, vcc
	v_div_scale_f32 v132, s[0:1], v9, v9, 1.0
	v_rcp_f32_e32 v133, v132
	v_lshlrev_b64 v[130:131], 13, v[146:147]
	s_add_u32 s0, s35, s36
	s_addc_u32 s1, s40, s37
	v_fma_f32 v134, -v132, v133, 1.0
	v_fmac_f32_e32 v133, v134, v133
	v_div_scale_f32 v134, vcc, 1.0, v9, 1.0
	v_mul_f32_e32 v135, v134, v133
	v_fma_f32 v136, -v132, v135, v134
	v_fmac_f32_e32 v135, v136, v133
	v_fma_f32 v132, -v132, v135, v134
	v_div_fmas_f32 v132, v132, v133, v135
	v_div_fixup_f32 v9, v132, v9, 1.0
	v_mul_f32_e32 v132, 0x3bb504f3, v9
	v_pk_fma_f32 v[126:127], v[126:127], v[132:133], v[26:27] op_sel_hi:[1,0,1]
	v_mov_b32_e32 v134, 0
	v_med3_f32 v126, v126, 0, v195
	v_med3_f32 v127, v127, 0, v195
	v_pk_mul_f32 v[126:127], v[126:127], v[126:127]
	v_pk_fma_f32 v[122:123], v[122:123], v[132:133], v[22:23] op_sel_hi:[1,0,1]
	v_cvt_pk_fp8_f32 v134, v126, v127
	v_pk_fma_f32 v[128:129], v[128:129], v[132:133], v[24:25] op_sel_hi:[1,0,1]
	v_med3_f32 v122, v122, 0, v195
	v_med3_f32 v123, v123, 0, v195
	v_med3_f32 v128, v128, 0, v195
	v_med3_f32 v129, v129, 0, v195
	v_pk_mul_f32 v[122:123], v[122:123], v[122:123]
	v_mov_b32_e32 v135, 0
	v_pk_fma_f32 v[118:119], v[118:119], v[132:133], v[16:17] op_sel_hi:[1,0,1]
	v_pk_fma_f32 v[114:115], v[114:115], v[132:133], v[18:19] op_sel_hi:[1,0,1]
	v_cvt_pk_fp8_f32 v135, v122, v123
	v_pk_mul_f32 v[122:123], v[128:129], v[128:129]
	v_med3_f32 v118, v118, 0, v195
	v_med3_f32 v114, v114, 0, v195
	v_med3_f32 v119, v119, 0, v195
	v_med3_f32 v115, v115, 0, v195
	v_cvt_pk_fp8_f32 v134, v122, v123 op_sel:[0,0,1]
	v_pk_mul_f32 v[118:119], v[118:119], v[118:119]
	v_pk_mul_f32 v[114:115], v[114:115], v[114:115]
	v_mov_b32_e32 v122, 0
	v_mov_b32_e32 v123, 0
	v_pk_fma_f32 v[124:125], v[124:125], v[132:133], v[20:21] op_sel_hi:[1,0,1]
	v_cvt_pk_fp8_f32 v122, v118, v119
	v_cvt_pk_fp8_f32 v123, v114, v115
	v_med3_f32 v124, v124, 0, v195
	v_med3_f32 v125, v125, 0, v195
	v_pk_fma_f32 v[120:121], v[120:121], v[132:133], v[14:15] op_sel_hi:[1,0,1]
	v_pk_fma_f32 v[116:117], v[116:117], v[132:133], v[12:13] op_sel_hi:[1,0,1]
	v_pk_mul_f32 v[124:125], v[124:125], v[124:125]
	v_med3_f32 v120, v120, 0, v195
	v_med3_f32 v116, v116, 0, v195
	v_med3_f32 v121, v121, 0, v195
	v_med3_f32 v117, v117, 0, v195
	v_cvt_pk_fp8_f32 v135, v124, v125 op_sel:[0,0,1]
	v_pk_mul_f32 v[114:115], v[120:121], v[120:121]
	v_pk_mul_f32 v[116:117], v[116:117], v[116:117]
	v_cvt_pk_fp8_f32 v122, v114, v115 op_sel:[0,0,1]
	v_cvt_pk_fp8_f32 v123, v116, v117 op_sel:[0,0,1]
	v_lshl_add_u64 v[114:115], s[10:11], 0, v[130:131]
	v_lshl_add_u64 v[114:115], v[114:115], 0, v[6:7]
	global_store_dwordx2 v[114:115], v[134:135], off
	global_store_dwordx2 v[114:115], v[122:123], off offset:128
	v_mov_b32_e32 v114, v2
	v_mov_b32_e32 v115, v28
	v_mov_b32_e32 v28, v3
	v_pk_add_f32 v[2:3], v[114:115], v[28:29]
	v_mov_b32_e32 v28, v4
	v_mov_b32_e32 v29, v30
	v_mov_b32_e32 v30, v5
	v_pk_add_f32 v[4:5], v[28:29], v[30:31]
	v_add_u32_e32 v130, 0x80, v8
	v_pk_add_f32 v[2:3], v[2:3], v[4:5]
	v_ashrrev_i32_e32 v131, 31, v130
	v_add_f32_e32 v4, v2, v3
	ds_bpermute_b32 v5, v238, v4
	v_lshlrev_b64 v[2:3], 7, v[130:131]
	v_lshl_add_u64 v[28:29], v[170:171], 0, v[2:3]
	v_lshl_add_u64 v[10:11], s[0:1], 0, v[10:11]
	s_waitcnt lgkmcnt(0)
	v_add_f32_e32 v9, v4, v5
	global_load_dwordx4 v[2:5], v[28:29], off
	s_nop 0
	global_load_dwordx4 v[28:31], v[28:29], off offset:16
	ds_bpermute_b32 v114, v239, v9
	s_waitcnt lgkmcnt(0)
	v_add_f32_e32 v9, v9, v114
	v_fmamk_f32 v9, v9, 0x3a000000, v193
	v_mul_f32_e32 v114, 0x4f800000, v9
	v_cmp_gt_f32_e32 vcc, s47, v9
	s_nop 1
	v_cndmask_b32_e32 v9, v9, v114, vcc
	v_sqrt_f32_e32 v122, v9
	global_load_dwordx4 v[114:117], v[10:11], off offset:16
	global_load_dwordx4 v[118:121], v[10:11], off
	v_add_u32_e32 v123, -1, v122
	v_fma_f32 v124, -v123, v122, v9
	v_cmp_ge_f32_e64 s[6:7], 0, v124
	v_add_u32_e32 v124, 1, v122
	s_nop 0
	v_cndmask_b32_e64 v123, v122, v123, s[6:7]
	v_fma_f32 v122, -v124, v122, v9
	v_cmp_lt_f32_e64 s[6:7], 0, v122
	s_nop 1
	v_cndmask_b32_e64 v122, v123, v124, s[6:7]
	v_mul_f32_e32 v123, 0x37800000, v122
	v_cndmask_b32_e32 v122, v122, v123, vcc
	v_cmp_class_f32_e32 vcc, v9, v194
	s_nop 1
	v_cndmask_b32_e32 v9, v122, v9, vcc
	v_div_scale_f32 v132, s[0:1], v9, v9, 1.0
	v_rcp_f32_e32 v133, v132
	global_load_dwordx4 v[122:125], v[10:11], off offset:528
	global_load_dwordx4 v[126:129], v[10:11], off offset:512
	s_mov_b64 s[100:101], 0x5000
	v_lshl_add_u64 v[240:241], v[242:243], 0, s[100:101]
	global_load_dwordx4 v[208:211], v[240:241], off offset:-2048
	global_load_dwordx4 v[212:215], v[240:241], off offset:-2032
	global_load_dwordx4 v[216:219], v[240:241], off
	global_load_dwordx4 v[220:223], v[240:241], off offset:16
	global_load_dwordx4 v[224:227], v[240:241], off offset:2048
	global_load_dwordx4 v[228:231], v[240:241], off offset:2064
	v_lshlrev_b64 v[10:11], 13, v[32:33]
	v_fma_f32 v32, -v132, v133, 1.0
	v_fmac_f32_e32 v133, v32, v133
	v_div_scale_f32 v32, vcc, 1.0, v9, 1.0
	v_mul_f32_e32 v33, v32, v133
	v_fma_f32 v134, -v132, v33, v32
	v_fmac_f32_e32 v33, v134, v133
	v_fma_f32 v32, -v132, v33, v32
	v_div_fmas_f32 v32, v32, v133, v33
	v_div_fixup_f32 v9, v32, v9, 1.0
	v_mul_f32_e32 v32, 0x3bb504f3, v9
	v_pk_fma_f32 v[22:23], v[106:107], v[32:33], v[22:23] op_sel_hi:[1,0,1]
	v_mov_b32_e32 v107, 0
	v_med3_f32 v22, v22, 0, v195
	v_med3_f32 v23, v23, 0, v195
	v_pk_mul_f32 v[22:23], v[22:23], v[22:23]
	v_pk_fma_f32 v[20:21], v[108:109], v[32:33], v[20:21] op_sel_hi:[1,0,1]
	v_cvt_pk_fp8_f32 v107, v22, v23
	v_med3_f32 v20, v20, 0, v195
	v_med3_f32 v21, v21, 0, v195
	v_pk_fma_f32 v[18:19], v[98:99], v[32:33], v[18:19] op_sel_hi:[1,0,1]
	v_pk_mul_f32 v[20:21], v[20:21], v[20:21]
	v_med3_f32 v18, v18, 0, v195
	v_med3_f32 v19, v19, 0, v195
	v_pk_fma_f32 v[26:27], v[110:111], v[32:33], v[26:27] op_sel_hi:[1,0,1]
	v_cvt_pk_fp8_f32 v107, v20, v21 op_sel:[0,0,1]
	v_pk_mul_f32 v[18:19], v[18:19], v[18:19]
	v_mov_b32_e32 v21, 0
	v_med3_f32 v26, v26, 0, v195
	v_med3_f32 v27, v27, 0, v195
	v_pk_fma_f32 v[16:17], v[102:103], v[32:33], v[16:17] op_sel_hi:[1,0,1]
	v_cvt_pk_fp8_f32 v21, v18, v19
	v_pk_mul_f32 v[26:27], v[26:27], v[26:27]
	v_mov_b32_e32 v106, 0
	v_pk_fma_f32 v[12:13], v[100:101], v[32:33], v[12:13] op_sel_hi:[1,0,1]
	v_med3_f32 v16, v16, 0, v195
	v_med3_f32 v17, v17, 0, v195
	v_cvt_pk_fp8_f32 v106, v26, v27
	v_med3_f32 v12, v12, 0, v195
	v_med3_f32 v13, v13, 0, v195
	v_pk_mul_f32 v[16:17], v[16:17], v[16:17]
	v_mov_b32_e32 v20, 0
	v_pk_fma_f32 v[24:25], v[112:113], v[32:33], v[24:25] op_sel_hi:[1,0,1]
	v_cvt_pk_fp8_f32 v20, v16, v17
	v_pk_mul_f32 v[12:13], v[12:13], v[12:13]
	v_med3_f32 v24, v24, 0, v195
	v_med3_f32 v25, v25, 0, v195
	v_pk_fma_f32 v[14:15], v[104:105], v[32:33], v[14:15] op_sel_hi:[1,0,1]
	v_cvt_pk_fp8_f32 v21, v12, v13 op_sel:[0,0,1]
	s_waitcnt vmcnt(0)
	v_mov_b32_e32 v12, v2
	v_mov_b32_e32 v13, v28
	v_mov_b32_e32 v28, v3
	v_pk_mul_f32 v[22:23], v[24:25], v[24:25]
	v_med3_f32 v14, v14, 0, v195
	v_med3_f32 v15, v15, 0, v195
	v_pk_add_f32 v[2:3], v[12:13], v[28:29]
	v_mov_b32_e32 v12, v4
	v_mov_b32_e32 v13, v30
	v_mov_b32_e32 v30, v5
	v_cvt_pk_fp8_f32 v106, v22, v23 op_sel:[0,0,1]
	v_pk_mul_f32 v[14:15], v[14:15], v[14:15]
	v_pk_add_f32 v[4:5], v[12:13], v[30:31]
	v_cvt_pk_fp8_f32 v20, v14, v15 op_sel:[0,0,1]
	v_pk_add_f32 v[2:3], v[2:3], v[4:5]
	v_add_u32_e32 v30, 0x90, v8
	v_add_f32_e32 v4, v2, v3
	v_lshl_add_u64 v[2:3], s[10:11], 0, v[10:11]
	v_lshl_add_u64 v[2:3], v[2:3], 0, v[6:7]
	v_ashrrev_i32_e32 v31, 31, v30
	global_store_dwordx2 v[2:3], v[106:107], off
	global_store_dwordx2 v[2:3], v[20:21], off offset:128
	v_lshlrev_b64 v[2:3], 7, v[30:31]
	v_lshl_add_u64 v[2:3], v[170:171], 0, v[2:3]
	v_mov_b64_e32 v[22:23], v[208:209]
	v_mov_b64_e32 v[24:25], v[210:211]
	v_mov_b64_e32 v[26:27], v[212:213]
	v_mov_b64_e32 v[28:29], v[214:215]
	ds_bpermute_b32 v5, v238, v4
	v_pk_mul_f32 v[12:13], v[114:115], s[16:17] op_sel_hi:[1,0]
	v_lshlrev_b64 v[30:31], 13, v[30:31]
	v_lshl_add_u64 v[30:31], s[10:11], 0, v[30:31]
	s_waitcnt lgkmcnt(0)
	v_add_f32_e32 v4, v4, v5
	ds_bpermute_b32 v5, v239, v4
	v_lshl_add_u64 v[30:31], v[30:31], 0, v[6:7]
	s_waitcnt lgkmcnt(0)
	v_add_f32_e32 v4, v4, v5
	v_fmamk_f32 v4, v4, 0x3a000000, v193
	v_mul_f32_e32 v5, 0x4f800000, v4
	v_cmp_gt_f32_e32 vcc, s47, v4
	s_nop 1
	v_cndmask_b32_e32 v4, v4, v5, vcc
	v_sqrt_f32_e32 v5, v4
	s_nop 0
	v_add_u32_e32 v2, -1, v5
	v_fma_f32 v3, -v2, v5, v4
	v_cmp_ge_f32_e64 s[6:7], 0, v3
	v_add_u32_e32 v3, 1, v5
	s_nop 0
	v_cndmask_b32_e64 v2, v5, v2, s[6:7]
	v_fma_f32 v5, -v3, v5, v4
	v_cmp_lt_f32_e64 s[6:7], 0, v5
	s_nop 1
	v_cndmask_b32_e64 v2, v2, v3, s[6:7]
	v_mul_f32_e32 v3, 0x37800000, v2
	v_cndmask_b32_e32 v2, v2, v3, vcc
	v_cmp_class_f32_e32 vcc, v4, v194
	s_nop 1
	v_cndmask_b32_e32 v4, v2, v4, vcc
	v_div_scale_f32 v5, s[0:1], v4, v4, 1.0
	v_rcp_f32_e32 v9, v5
	v_lshlrev_b64 v[2:3], 13, v[130:131]
	v_lshl_add_u64 v[2:3], s[10:11], 0, v[2:3]
	v_lshl_add_u64 v[32:33], v[2:3], 0, v[6:7]
	v_fma_f32 v2, -v5, v9, 1.0
	v_fmac_f32_e32 v9, v2, v9
	v_div_scale_f32 v2, vcc, 1.0, v4, 1.0
	v_mul_f32_e32 v3, v2, v9
	v_fma_f32 v10, -v5, v3, v2
	v_fmac_f32_e32 v3, v10, v9
	v_fma_f32 v2, -v5, v3, v2
	v_div_fmas_f32 v2, v2, v9, v3
	v_div_fixup_f32 v2, v2, v4, 1.0
	v_mul_f32_e32 v98, 0x3bb504f3, v2
	v_pk_fma_f32 v[20:21], v[90:91], v[98:99], v[12:13] op_sel_hi:[1,0,1]
	v_mov_b32_e32 v91, 0
	v_med3_f32 v20, v20, 0, v195
	v_med3_f32 v21, v21, 0, v195
	v_pk_mul_f32 v[20:21], v[20:21], v[20:21]
	v_pk_mul_f32 v[4:5], v[118:119], s[16:17] op_sel_hi:[1,0]
	v_cvt_pk_fp8_f32 v91, v20, v21
	v_pk_mul_f32 v[20:21], v[122:123], s[16:17] op_sel_hi:[1,0]
	v_pk_mul_f32 v[10:11], v[116:117], s[16:17] op_sel_hi:[1,0]
	v_pk_fma_f32 v[82:83], v[82:83], v[98:99], v[20:21] op_sel_hi:[1,0,1]
	v_pk_fma_f32 v[16:17], v[94:95], v[98:99], v[4:5] op_sel_hi:[1,0,1]
	v_med3_f32 v82, v82, 0, v195
	v_med3_f32 v83, v83, 0, v195
	v_pk_fma_f32 v[18:19], v[92:93], v[98:99], v[10:11] op_sel_hi:[1,0,1]
	v_pk_mul_f32 v[82:83], v[82:83], v[82:83]
	v_mov_b32_e32 v93, 0
	v_med3_f32 v16, v16, 0, v195
	v_med3_f32 v17, v17, 0, v195
	v_cvt_pk_fp8_f32 v93, v82, v83
	v_med3_f32 v18, v18, 0, v195
	v_med3_f32 v19, v19, 0, v195
	v_pk_mul_f32 v[16:17], v[16:17], v[16:17]
	v_mov_b32_e32 v82, v22
	v_mov_b32_e32 v83, v26
	v_mov_b32_e32 v26, v23
	v_mov_b32_e32 v90, 0
	v_pk_add_f32 v[22:23], v[82:83], v[26:27]
	v_mov_b32_e32 v26, v24
	v_mov_b32_e32 v27, v28
	v_mov_b32_e32 v28, v25
	v_cvt_pk_fp8_f32 v90, v16, v17
	v_pk_mul_f32 v[16:17], v[18:19], v[18:19]
	v_pk_add_f32 v[24:25], v[26:27], v[28:29]
	v_pk_mul_f32 v[2:3], v[120:121], s[16:17] op_sel_hi:[1,0]
	v_cvt_pk_fp8_f32 v91, v16, v17 op_sel:[0,0,1]
	v_pk_mul_f32 v[16:17], v[126:127], s[16:17] op_sel_hi:[1,0]
	v_pk_add_f32 v[22:23], v[22:23], v[24:25]
	v_pk_fma_f32 v[14:15], v[96:97], v[98:99], v[2:3] op_sel_hi:[1,0,1]
	v_pk_fma_f32 v[86:87], v[86:87], v[98:99], v[16:17] op_sel_hi:[1,0,1]
	v_add_f32_e32 v9, v22, v23
	v_med3_f32 v14, v14, 0, v195
	v_med3_f32 v15, v15, 0, v195
	v_med3_f32 v86, v86, 0, v195
	v_med3_f32 v87, v87, 0, v195
	ds_bpermute_b32 v24, v238, v9
	v_pk_mul_f32 v[14:15], v[14:15], v[14:15]
	v_pk_mul_f32 v[86:87], v[86:87], v[86:87]
	v_mov_b32_e32 v92, 0
	v_cvt_pk_fp8_f32 v90, v14, v15 op_sel:[0,0,1]
	v_pk_mul_f32 v[14:15], v[128:129], s[16:17] op_sel_hi:[1,0]
	v_pk_mul_f32 v[18:19], v[124:125], s[16:17] op_sel_hi:[1,0]
	v_cvt_pk_fp8_f32 v92, v86, v87
	v_pk_fma_f32 v[88:89], v[88:89], v[98:99], v[14:15] op_sel_hi:[1,0,1]
	v_pk_fma_f32 v[84:85], v[84:85], v[98:99], v[18:19] op_sel_hi:[1,0,1]
	v_med3_f32 v88, v88, 0, v195
	v_med3_f32 v84, v84, 0, v195
	v_med3_f32 v89, v89, 0, v195
	v_med3_f32 v85, v85, 0, v195
	v_pk_mul_f32 v[88:89], v[88:89], v[88:89]
	v_pk_mul_f32 v[22:23], v[84:85], v[84:85]
	s_waitcnt lgkmcnt(0)
	v_add_f32_e32 v9, v9, v24
	v_cvt_pk_fp8_f32 v92, v88, v89 op_sel:[0,0,1]
	v_cvt_pk_fp8_f32 v93, v22, v23 op_sel:[0,0,1]
	ds_bpermute_b32 v24, v239, v9
	global_store_dwordx2 v[32:33], v[90:91], off
	global_store_dwordx2 v[32:33], v[92:93], off offset:128
	v_add_u32_e32 v32, 0xa0, v8
	v_ashrrev_i32_e32 v33, 31, v32
	s_waitcnt lgkmcnt(0)
	v_add_f32_e32 v9, v9, v24
	v_lshlrev_b64 v[22:23], 7, v[32:33]
	v_fmamk_f32 v9, v9, 0x3a000000, v193
	v_mul_f32_e32 v24, 0x4f800000, v9
	v_cmp_gt_f32_e32 vcc, s47, v9
	v_lshl_add_u64 v[26:27], v[170:171], 0, v[22:23]
	v_add_u32_e32 v8, 0xb0, v8
	v_cndmask_b32_e32 v9, v9, v24, vcc
	v_mov_b64_e32 v[22:23], v[216:217]
	v_mov_b64_e32 v[24:25], v[218:219]
	s_nop 0
	v_mov_b64_e32 v[26:27], v[220:221]
	v_mov_b64_e32 v[28:29], v[222:223]
	v_sqrt_f32_e32 v82, v9
	v_lshlrev_b64 v[32:33], 13, v[32:33]
	v_lshl_add_u64 v[32:33], s[10:11], 0, v[32:33]
	v_add_u32_e32 v83, -1, v82
	v_fma_f32 v84, -v83, v82, v9
	v_cmp_ge_f32_e64 s[6:7], 0, v84
	v_add_u32_e32 v84, 1, v82
	v_lshl_add_u64 v[32:33], v[32:33], 0, v[6:7]
	v_cndmask_b32_e64 v83, v82, v83, s[6:7]
	v_fma_f32 v82, -v84, v82, v9
	v_cmp_lt_f32_e64 s[6:7], 0, v82
	s_nop 1
	v_cndmask_b32_e64 v82, v83, v84, s[6:7]
	v_mul_f32_e32 v83, 0x37800000, v82
	v_cndmask_b32_e32 v82, v82, v83, vcc
	v_cmp_class_f32_e32 vcc, v9, v194
	s_nop 1
	v_cndmask_b32_e32 v9, v82, v9, vcc
	v_div_scale_f32 v82, s[0:1], v9, v9, 1.0
	v_rcp_f32_e32 v83, v82
	s_nop 0
	v_fma_f32 v84, -v82, v83, 1.0
	v_fmac_f32_e32 v83, v84, v83
	v_div_scale_f32 v84, vcc, 1.0, v9, 1.0
	v_mul_f32_e32 v85, v84, v83
	v_fma_f32 v86, -v82, v85, v84
	v_fmac_f32_e32 v85, v86, v83
	v_fma_f32 v82, -v82, v85, v84
	v_div_fmas_f32 v82, v82, v83, v85
	v_div_fixup_f32 v9, v82, v9, 1.0
	v_mul_f32_e32 v82, 0x3bb504f3, v9
	v_pk_fma_f32 v[78:79], v[78:79], v[82:83], v[4:5] op_sel_hi:[1,0,1]
	v_mov_b32_e32 v84, 0
	v_med3_f32 v78, v78, 0, v195
	v_med3_f32 v79, v79, 0, v195
	v_pk_mul_f32 v[78:79], v[78:79], v[78:79]
	v_pk_fma_f32 v[74:75], v[74:75], v[82:83], v[12:13] op_sel_hi:[1,0,1]
	v_cvt_pk_fp8_f32 v84, v78, v79
	v_pk_fma_f32 v[80:81], v[80:81], v[82:83], v[2:3] op_sel_hi:[1,0,1]
	v_med3_f32 v74, v74, 0, v195
	v_med3_f32 v75, v75, 0, v195
	v_med3_f32 v80, v80, 0, v195
	v_med3_f32 v81, v81, 0, v195
	v_pk_mul_f32 v[74:75], v[74:75], v[74:75]
	v_mov_b32_e32 v85, 0
	v_pk_fma_f32 v[70:71], v[70:71], v[82:83], v[16:17] op_sel_hi:[1,0,1]
	v_pk_fma_f32 v[66:67], v[66:67], v[82:83], v[20:21] op_sel_hi:[1,0,1]
	v_cvt_pk_fp8_f32 v85, v74, v75
	v_pk_mul_f32 v[74:75], v[80:81], v[80:81]
	v_med3_f32 v70, v70, 0, v195
	v_med3_f32 v66, v66, 0, v195
	v_med3_f32 v71, v71, 0, v195
	v_med3_f32 v67, v67, 0, v195
	v_cvt_pk_fp8_f32 v84, v74, v75 op_sel:[0,0,1]
	v_pk_mul_f32 v[70:71], v[70:71], v[70:71]
	v_pk_mul_f32 v[66:67], v[66:67], v[66:67]
	v_mov_b32_e32 v74, 0
	v_mov_b32_e32 v75, 0
	v_pk_fma_f32 v[76:77], v[76:77], v[82:83], v[10:11] op_sel_hi:[1,0,1]
	v_cvt_pk_fp8_f32 v74, v70, v71
	v_cvt_pk_fp8_f32 v75, v66, v67
	v_med3_f32 v76, v76, 0, v195
	v_med3_f32 v77, v77, 0, v195
	v_pk_fma_f32 v[72:73], v[72:73], v[82:83], v[14:15] op_sel_hi:[1,0,1]
	v_pk_fma_f32 v[68:69], v[68:69], v[82:83], v[18:19] op_sel_hi:[1,0,1]
	v_pk_mul_f32 v[76:77], v[76:77], v[76:77]
	v_med3_f32 v72, v72, 0, v195
	v_med3_f32 v68, v68, 0, v195
	v_med3_f32 v73, v73, 0, v195
	v_med3_f32 v69, v69, 0, v195
	v_cvt_pk_fp8_f32 v85, v76, v77 op_sel:[0,0,1]
	v_pk_mul_f32 v[66:67], v[72:73], v[72:73]
	v_pk_mul_f32 v[68:69], v[68:69], v[68:69]
	v_cvt_pk_fp8_f32 v74, v66, v67 op_sel:[0,0,1]
	v_cvt_pk_fp8_f32 v75, v68, v69 op_sel:[0,0,1]
	global_store_dwordx2 v[30:31], v[84:85], off
	global_store_dwordx2 v[30:31], v[74:75], off offset:128
	v_mov_b32_e32 v30, v22
	v_mov_b32_e32 v31, v26
	v_mov_b32_e32 v26, v23
	v_pk_add_f32 v[22:23], v[30:31], v[26:27]
	v_mov_b32_e32 v26, v24
	v_mov_b32_e32 v27, v28
	v_mov_b32_e32 v28, v25
	v_pk_add_f32 v[24:25], v[26:27], v[28:29]
	v_ashrrev_i32_e32 v9, 31, v8
	v_pk_add_f32 v[22:23], v[22:23], v[24:25]
	s_nop 0
	v_add_f32_e32 v24, v22, v23
	ds_bpermute_b32 v25, v238, v24
	v_lshlrev_b64 v[22:23], 7, v[8:9]
	v_lshl_add_u64 v[26:27], v[170:171], 0, v[22:23]
	v_lshlrev_b64 v[8:9], 13, v[8:9]
	s_waitcnt lgkmcnt(0)
	v_add_f32_e32 v30, v24, v25
	v_mov_b64_e32 v[22:23], v[224:225]
	v_mov_b64_e32 v[24:25], v[226:227]
	s_nop 0
	v_mov_b64_e32 v[26:27], v[228:229]
	v_mov_b64_e32 v[28:29], v[230:231]
	ds_bpermute_b32 v31, v239, v30
	s_waitcnt lgkmcnt(0)
	v_add_f32_e32 v30, v30, v31
	v_fmamk_f32 v30, v30, 0x3a000000, v193
	v_mul_f32_e32 v31, 0x4f800000, v30
	v_cmp_gt_f32_e32 vcc, s47, v30
	s_nop 1
	v_cndmask_b32_e32 v30, v30, v31, vcc
	v_sqrt_f32_e32 v31, v30
	s_nop 0
	v_add_u32_e32 v66, -1, v31
	v_fma_f32 v67, -v66, v31, v30
	v_cmp_ge_f32_e64 s[6:7], 0, v67
	v_add_u32_e32 v67, 1, v31
	s_nop 0
	v_cndmask_b32_e64 v66, v31, v66, s[6:7]
	v_fma_f32 v31, -v67, v31, v30
	v_cmp_lt_f32_e64 s[6:7], 0, v31
	s_nop 1
	v_cndmask_b32_e64 v31, v66, v67, s[6:7]
	v_mul_f32_e32 v66, 0x37800000, v31
	v_cndmask_b32_e32 v31, v31, v66, vcc
	v_cmp_class_f32_e32 vcc, v30, v194
	s_nop 1
	v_cndmask_b32_e32 v30, v31, v30, vcc
	v_div_scale_f32 v31, s[0:1], v30, v30, 1.0
	v_rcp_f32_e32 v66, v31
	s_nop 0
	v_fma_f32 v67, -v31, v66, 1.0
	v_fmac_f32_e32 v66, v67, v66
	v_div_scale_f32 v67, vcc, 1.0, v30, 1.0
	v_mul_f32_e32 v68, v67, v66
	v_fma_f32 v69, -v31, v68, v67
	v_fmac_f32_e32 v68, v69, v66
	v_fma_f32 v31, -v31, v68, v67
	v_div_fmas_f32 v31, v31, v66, v68
	v_div_fixup_f32 v30, v31, v30, 1.0
	v_mul_f32_e32 v30, 0x3bb504f3, v30
	v_pk_fma_f32 v[56:57], v[56:57], v[30:31], v[14:15] op_sel_hi:[1,0,1]
	v_pk_fma_f32 v[54:55], v[54:55], v[30:31], v[16:17] op_sel_hi:[1,0,1]
	v_pk_fma_f32 v[64:65], v[64:65], v[30:31], v[2:3] op_sel_hi:[1,0,1]
	v_pk_fma_f32 v[62:63], v[62:63], v[30:31], v[4:5] op_sel_hi:[1,0,1]
	v_pk_fma_f32 v[60:61], v[60:61], v[30:31], v[10:11] op_sel_hi:[1,0,1]
	v_pk_fma_f32 v[58:59], v[58:59], v[30:31], v[12:13] op_sel_hi:[1,0,1]
	v_pk_fma_f32 v[52:53], v[52:53], v[30:31], v[18:19] op_sel_hi:[1,0,1]
	v_pk_fma_f32 v[30:31], v[50:51], v[30:31], v[20:21] op_sel_hi:[1,0,1]
	v_med3_f32 v50, v54, 0, v195
	v_med3_f32 v51, v55, 0, v195
	v_med3_f32 v54, v56, 0, v195
	v_med3_f32 v55, v57, 0, v195
	v_med3_f32 v30, v30, 0, v195
	v_med3_f32 v31, v31, 0, v195
	v_med3_f32 v52, v52, 0, v195
	v_med3_f32 v53, v53, 0, v195
	v_med3_f32 v62, v62, 0, v195
	v_med3_f32 v58, v58, 0, v195
	v_med3_f32 v63, v63, 0, v195
	v_med3_f32 v59, v59, 0, v195
	v_pk_mul_f32 v[62:63], v[62:63], v[62:63]
	v_pk_mul_f32 v[58:59], v[58:59], v[58:59]
	v_mov_b32_e32 v66, 0
	v_mov_b32_e32 v67, 0
	v_cvt_pk_fp8_f32 v66, v62, v63
	v_cvt_pk_fp8_f32 v67, v58, v59
	v_med3_f32 v64, v64, 0, v195
	v_med3_f32 v60, v60, 0, v195
	v_mov_b32_e32 v56, v22
	v_mov_b32_e32 v57, v26
	v_mov_b32_e32 v26, v23
	v_pk_add_f32 v[22:23], v[56:57], v[26:27]
	v_mov_b32_e32 v26, v24
	v_mov_b32_e32 v27, v28
	v_mov_b32_e32 v28, v25
	v_pk_add_f32 v[24:25], v[26:27], v[28:29]
	v_pk_mul_f32 v[26:27], v[30:31], v[30:31]
	v_pk_add_f32 v[22:23], v[22:23], v[24:25]
	v_pk_mul_f32 v[24:25], v[50:51], v[50:51]
	v_add_f32_e32 v28, v22, v23
	ds_bpermute_b32 v29, v238, v28
	v_pk_mul_f32 v[22:23], v[54:55], v[54:55]
	v_med3_f32 v65, v65, 0, v195
	v_med3_f32 v61, v61, 0, v195
	v_pk_mul_f32 v[58:59], v[64:65], v[64:65]
	s_waitcnt lgkmcnt(0)
	v_add_f32_e32 v30, v28, v29
	ds_bpermute_b32 v31, v239, v30
	v_mov_b32_e32 v28, 0
	v_cvt_pk_fp8_f32 v28, v24, v25
	v_mov_b32_e32 v29, 0
	v_cvt_pk_fp8_f32 v29, v26, v27
	s_waitcnt lgkmcnt(0)
	v_add_f32_e32 v24, v30, v31
	v_fmamk_f32 v24, v24, 0x3a000000, v193
	v_mul_f32_e32 v25, 0x4f800000, v24
	v_cmp_gt_f32_e32 vcc, s47, v24
	v_cvt_pk_fp8_f32 v28, v22, v23 op_sel:[0,0,1]
	v_pk_mul_f32 v[60:61], v[60:61], v[60:61]
	v_cndmask_b32_e32 v26, v24, v25, vcc
	v_sqrt_f32_e32 v27, v26
	v_pk_mul_f32 v[24:25], v[52:53], v[52:53]
	v_cvt_pk_fp8_f32 v66, v58, v59 op_sel:[0,0,1]
	v_cvt_pk_fp8_f32 v29, v24, v25 op_sel:[0,0,1]
	v_add_u32_e32 v22, -1, v27
	v_fma_f32 v23, -v22, v27, v26
	v_cmp_ge_f32_e64 s[6:7], 0, v23
	v_add_u32_e32 v23, 1, v27
	v_fma_f32 v24, -v23, v27, v26
	v_cndmask_b32_e64 v22, v27, v22, s[6:7]
	v_cmp_lt_f32_e64 s[6:7], 0, v24
	v_cvt_pk_fp8_f32 v67, v60, v61 op_sel:[0,0,1]
	global_store_dwordx2 v[32:33], v[28:29], off offset:128
	v_cndmask_b32_e64 v22, v22, v23, s[6:7]
	v_mul_f32_e32 v23, 0x37800000, v22
	v_cndmask_b32_e32 v22, v22, v23, vcc
	v_cmp_class_f32_e32 vcc, v26, v194
	global_store_dwordx2 v[32:33], v[66:67], off
	s_nop 0
	v_cndmask_b32_e32 v22, v22, v26, vcc
	v_div_scale_f32 v23, s[0:1], v22, v22, 1.0
	v_rcp_f32_e32 v24, v23
	s_mov_b64 s[0:1], -1
	v_fma_f32 v25, -v23, v24, 1.0
	v_fmac_f32_e32 v24, v25, v24
	v_div_scale_f32 v25, vcc, 1.0, v22, 1.0
	v_mul_f32_e32 v26, v25, v24
	v_fma_f32 v27, -v23, v26, v25
	v_fmac_f32_e32 v26, v27, v24
	v_fma_f32 v23, -v23, v26, v25
	v_div_fmas_f32 v23, v23, v24, v26
	v_div_fixup_f32 v22, v23, v22, 1.0
	v_mul_f32_e32 v22, 0x3bb504f3, v22
	v_pk_fma_f32 v[12:13], v[42:43], v[22:23], v[12:13] op_sel_hi:[1,0,1]
	v_pk_fma_f32 v[4:5], v[46:47], v[22:23], v[4:5] op_sel_hi:[1,0,1]
	v_med3_f32 v12, v12, 0, v195
	v_med3_f32 v13, v13, 0, v195
	v_pk_mul_f32 v[12:13], v[12:13], v[12:13]
	v_mov_b32_e32 v25, 0
	v_med3_f32 v4, v4, 0, v195
	v_med3_f32 v5, v5, 0, v195
	v_cvt_pk_fp8_f32 v25, v12, v13
	v_pk_fma_f32 v[10:11], v[44:45], v[22:23], v[10:11] op_sel_hi:[1,0,1]
	v_pk_mul_f32 v[4:5], v[4:5], v[4:5]
	v_mov_b32_e32 v24, 0
	v_med3_f32 v10, v10, 0, v195
	v_med3_f32 v11, v11, 0, v195
	v_cvt_pk_fp8_f32 v24, v4, v5
	v_pk_fma_f32 v[2:3], v[48:49], v[22:23], v[2:3] op_sel_hi:[1,0,1]
	v_pk_mul_f32 v[4:5], v[10:11], v[10:11]
	v_med3_f32 v2, v2, 0, v195
	v_med3_f32 v3, v3, 0, v195
	v_cvt_pk_fp8_f32 v25, v4, v5 op_sel:[0,0,1]
	v_pk_fma_f32 v[4:5], v[38:39], v[22:23], v[16:17] op_sel_hi:[1,0,1]
	v_pk_fma_f32 v[12:13], v[34:35], v[22:23], v[20:21] op_sel_hi:[1,0,1]
	v_pk_mul_f32 v[2:3], v[2:3], v[2:3]
	v_med3_f32 v4, v4, 0, v195
	v_med3_f32 v12, v12, 0, v195
	v_med3_f32 v5, v5, 0, v195
	v_med3_f32 v13, v13, 0, v195
	v_cvt_pk_fp8_f32 v24, v2, v3 op_sel:[0,0,1]
	v_pk_fma_f32 v[2:3], v[40:41], v[22:23], v[14:15] op_sel_hi:[1,0,1]
	v_pk_mul_f32 v[4:5], v[4:5], v[4:5]
	v_pk_mul_f32 v[12:13], v[12:13], v[12:13]
	v_mov_b32_e32 v14, 0
	v_mov_b32_e32 v15, 0
	v_cvt_pk_fp8_f32 v14, v4, v5
	v_cvt_pk_fp8_f32 v15, v12, v13
	v_pk_fma_f32 v[10:11], v[36:37], v[22:23], v[18:19] op_sel_hi:[1,0,1]
	v_med3_f32 v2, v2, 0, v195
	v_med3_f32 v10, v10, 0, v195
	v_med3_f32 v3, v3, 0, v195
	v_med3_f32 v11, v11, 0, v195
	v_pk_mul_f32 v[2:3], v[2:3], v[2:3]
	v_pk_mul_f32 v[4:5], v[10:11], v[10:11]
	v_cvt_pk_fp8_f32 v14, v2, v3 op_sel:[0,0,1]
	v_cvt_pk_fp8_f32 v15, v4, v5 op_sel:[0,0,1]
	v_lshl_add_u64 v[2:3], s[10:11], 0, v[8:9]
	v_lshl_add_u64 v[2:3], v[2:3], 0, v[6:7]
	s_andn2_b64 vcc, exec, s[4:5]
	global_store_dwordx2 v[2:3], v[24:25], off
	global_store_dwordx2 v[2:3], v[14:15], off offset:128
	s_cbranch_vccnz .LBB0_1068
	s_andn2_b64 vcc, exec, s[8:9]
	s_cbranch_vccnz .LBB0_1067
	s_barrier
	s_branch .LBB0_1067

.LBB0_1159:
	ds_read_b128 v[26:29], v242
	ds_read_b128 v[30:33], v242 offset:1024
	ds_read_b128 v[18:21], v242 offset:2048
	ds_read_b128 v[22:25], v242 offset:3072
	ds_read_b128 v[10:13], v243
	ds_read_b128 v[14:17], v243 offset:1024
	ds_read_b128 v[2:5], v243 offset:2048
	ds_read_b128 v[6:9], v243 offset:3072
	s_add_i32 s20, s0, 2
	s_add_u32 s1, s10, 0xfff00080
	s_addc_u32 s12, s11, -1
	s_cmp_eq_u32 s15, s0
	s_cselect_b32 s0, s14, s18
	s_cselect_b32 s13, s5, s12
	s_cselect_b32 s12, s7, s1
	s_cselect_b32 s1, s9, s19
	v_lshl_add_u64 v[208:209], s[10:11], 0, v[194:195]
	s_add_i32 m0, s45, 0xc000
	ds_read_b128 v[162:165], v244
	ds_read_b128 v[166:169], v244 offset:1024
	ds_read_b128 v[170:173], v244 offset:2048
	ds_read_b128 v[174:177], v244 offset:3072
	ds_read_b128 v[178:181], v244 offset:4096
	ds_read_b128 v[182:185], v244 offset:5120
	ds_read_b128 v[200:203], v244 offset:6144
	ds_read_b128 v[204:207], v244 offset:7168
	global_load_lds_dwordx4 v[208:209], off
	v_lshl_add_u64 v[208:209], s[10:11], 0, v[196:197]
	s_add_i32 m0, s45, 0xe000
	s_nop 0
	global_load_lds_dwordx4 v[208:209], off
	s_waitcnt vmcnt(8)
	s_waitcnt lgkmcnt(0)
	s_barrier
	s_waitcnt lgkmcnt(0)
	v_mfma_f32_16x16x128_f8f6f4 v[158:161], v[26:33], v[162:169], v[158:161]
	v_mfma_f32_16x16x128_f8f6f4 v[154:157], v[18:25], v[162:169], v[154:157]
	v_mfma_f32_16x16x128_f8f6f4 v[142:145], v[26:33], v[170:177], v[142:145]
	v_mfma_f32_16x16x128_f8f6f4 v[138:141], v[18:25], v[170:177], v[138:141]
	v_mfma_f32_16x16x128_f8f6f4 v[126:129], v[26:33], v[178:185], v[126:129]
	v_mfma_f32_16x16x128_f8f6f4 v[122:125], v[18:25], v[178:185], v[122:125]
	v_mfma_f32_16x16x128_f8f6f4 v[110:113], v[26:33], v[200:207], v[110:113]
	v_mfma_f32_16x16x128_f8f6f4 v[106:109], v[18:25], v[200:207], v[106:109]
	v_mfma_f32_16x16x128_f8f6f4 v[150:153], v[10:17], v[162:169], v[150:153]
	v_mfma_f32_16x16x128_f8f6f4 v[146:149], v[2:9], v[162:169], v[146:149]
	v_mfma_f32_16x16x128_f8f6f4 v[134:137], v[10:17], v[170:177], v[134:137]
	v_mfma_f32_16x16x128_f8f6f4 v[130:133], v[2:9], v[170:177], v[130:133]
	v_mfma_f32_16x16x128_f8f6f4 v[118:121], v[10:17], v[178:185], v[118:121]
	v_mfma_f32_16x16x128_f8f6f4 v[114:117], v[2:9], v[178:185], v[114:117]
	v_mfma_f32_16x16x128_f8f6f4 v[102:105], v[10:17], v[200:207], v[102:105]
	v_mfma_f32_16x16x128_f8f6f4 v[98:101], v[2:9], v[200:207], v[98:101]
	s_barrier
	s_add_i32 s21, s84, s24
	v_lshl_add_u64 v[162:163], s[0:1], 0, v[188:189]
	s_mov_b32 m0, s21
	ds_read_b128 v[170:173], v244 offset:16384
	ds_read_b128 v[174:177], v244 offset:17408
	ds_read_b128 v[178:181], v244 offset:18432
	ds_read_b128 v[182:185], v244 offset:19456
	ds_read_b128 v[200:203], v244 offset:20480
	ds_read_b128 v[204:207], v244 offset:21504
	ds_read_b128 v[208:211], v244 offset:22528
	ds_read_b128 v[212:215], v244 offset:23552
	global_load_lds_dwordx4 v[162:163], off
	s_add_i32 m0, s21, 0x2000
	s_add_u32 s62, s0, 0x100000
	v_lshl_add_u64 v[164:165], s[0:1], 0, v[192:193]
	s_addc_u32 s63, s1, 0
	s_add_i32 s21, s85, s24
	global_load_lds_dwordx4 v[164:165], off
	v_lshl_add_u64 v[166:167], s[62:63], 0, v[188:189]
	s_mov_b32 m0, s21
	v_lshl_add_u64 v[168:169], s[12:13], 0, v[190:191]
	global_load_lds_dwordx4 v[166:167], off
	v_lshl_add_u64 v[166:167], s[62:63], 0, v[192:193]
	s_add_i32 m0, s21, 0x2000
	s_nop 0
	global_load_lds_dwordx4 v[166:167], off
	v_lshl_add_u64 v[166:167], s[12:13], 0, v[186:187]
	s_mov_b32 m0, s45
	s_nop 0
	global_load_lds_dwordx4 v[166:167], off
	s_mov_b32 m0, s68
	s_nop 0
	global_load_lds_dwordx4 v[168:169], off
	s_waitcnt vmcnt(8)
	s_waitcnt lgkmcnt(0)
	s_barrier
	s_waitcnt lgkmcnt(0)
	v_mfma_f32_16x16x128_f8f6f4 v[94:97], v[26:33], v[170:177], v[94:97]
	v_mfma_f32_16x16x128_f8f6f4 v[90:93], v[18:25], v[170:177], v[90:93]
	v_mfma_f32_16x16x128_f8f6f4 v[78:81], v[26:33], v[178:185], v[78:81]
	v_mfma_f32_16x16x128_f8f6f4 v[74:77], v[18:25], v[178:185], v[74:77]
	v_mfma_f32_16x16x128_f8f6f4 v[62:65], v[26:33], v[200:207], v[62:65]
	v_mfma_f32_16x16x128_f8f6f4 v[58:61], v[18:25], v[200:207], v[58:61]
	v_mfma_f32_16x16x128_f8f6f4 v[46:49], v[26:33], v[208:215], v[46:49]
	v_mfma_f32_16x16x128_f8f6f4 v[42:45], v[18:25], v[208:215], v[42:45]
	v_mfma_f32_16x16x128_f8f6f4 v[86:89], v[10:17], v[170:177], v[86:89]
	v_mfma_f32_16x16x128_f8f6f4 v[82:85], v[2:9], v[170:177], v[82:85]
	v_mfma_f32_16x16x128_f8f6f4 v[70:73], v[10:17], v[178:185], v[70:73]
	v_mfma_f32_16x16x128_f8f6f4 v[66:69], v[2:9], v[178:185], v[66:69]
	v_mfma_f32_16x16x128_f8f6f4 v[54:57], v[10:17], v[200:207], v[54:57]
	v_mfma_f32_16x16x128_f8f6f4 v[50:53], v[2:9], v[200:207], v[50:53]
	v_mfma_f32_16x16x128_f8f6f4 v[38:41], v[10:17], v[208:215], v[38:41]
	v_mfma_f32_16x16x128_f8f6f4 v[34:37], v[2:9], v[208:215], v[34:37]
	s_barrier
	s_add_i32 s21, 0, 0x18000
	s_add_i32 s51, 0, 0x1c000
	v_add_u32_e32 v14, s21, v240
	v_add_u32_e32 v30, s51, v240
	ds_read_b128 v[2:5], v14
	ds_read_b128 v[6:9], v14 offset:1024
	ds_read_b128 v[10:13], v14 offset:2048
	ds_read_b128 v[14:17], v14 offset:3072
	ds_read_b128 v[18:21], v30
	ds_read_b128 v[22:25], v30 offset:1024
	ds_read_b128 v[26:29], v30 offset:2048
	ds_read_b128 v[30:33], v30 offset:3072
	s_add_u32 s12, s12, 0x100000
	s_addc_u32 s13, s13, 0
	s_mov_b32 m0, s69
	v_lshl_add_u64 v[216:217], s[12:13], 0, v[186:187]
	ds_read_b128 v[170:173], v244 offset:32768
	ds_read_b128 v[174:177], v244 offset:33792
	ds_read_b128 v[178:181], v244 offset:34816
	ds_read_b128 v[182:185], v244 offset:35840
	ds_read_b128 v[200:203], v244 offset:36864
	ds_read_b128 v[204:207], v244 offset:37888
	ds_read_b128 v[208:211], v244 offset:38912
	ds_read_b128 v[212:215], v244 offset:39936
	global_load_lds_dwordx4 v[216:217], off
	v_lshl_add_u64 v[216:217], s[12:13], 0, v[190:191]
	s_mov_b32 m0, s70
	s_nop 0
	global_load_lds_dwordx4 v[216:217], off
	s_waitcnt vmcnt(8)
	s_waitcnt lgkmcnt(0)
	s_barrier
	s_waitcnt lgkmcnt(0)
	v_mfma_f32_16x16x128_f8f6f4 v[158:161], v[2:9], v[170:177], v[158:161]
	v_mfma_f32_16x16x128_f8f6f4 v[154:157], v[10:17], v[170:177], v[154:157]
	v_mfma_f32_16x16x128_f8f6f4 v[142:145], v[2:9], v[178:185], v[142:145]
	v_mfma_f32_16x16x128_f8f6f4 v[138:141], v[10:17], v[178:185], v[138:141]
	v_mfma_f32_16x16x128_f8f6f4 v[126:129], v[2:9], v[200:207], v[126:129]
	v_mfma_f32_16x16x128_f8f6f4 v[122:125], v[10:17], v[200:207], v[122:125]
	v_mfma_f32_16x16x128_f8f6f4 v[110:113], v[2:9], v[208:215], v[110:113]
	v_mfma_f32_16x16x128_f8f6f4 v[106:109], v[10:17], v[208:215], v[106:109]
	v_mfma_f32_16x16x128_f8f6f4 v[150:153], v[18:25], v[170:177], v[150:153]
	v_mfma_f32_16x16x128_f8f6f4 v[146:149], v[26:33], v[170:177], v[146:149]
	v_mfma_f32_16x16x128_f8f6f4 v[134:137], v[18:25], v[178:185], v[134:137]
	v_mfma_f32_16x16x128_f8f6f4 v[130:133], v[26:33], v[178:185], v[130:133]
	v_mfma_f32_16x16x128_f8f6f4 v[118:121], v[18:25], v[200:207], v[118:121]
	v_mfma_f32_16x16x128_f8f6f4 v[114:117], v[26:33], v[200:207], v[114:117]
	v_mfma_f32_16x16x128_f8f6f4 v[102:105], v[18:25], v[208:215], v[102:105]
	v_mfma_f32_16x16x128_f8f6f4 v[98:101], v[26:33], v[208:215], v[98:101]
	s_barrier
	s_add_i32 s12, s21, s24
	v_lshl_add_u64 v[162:163], v[162:163], 0, s[36:37]
	s_mov_b32 m0, s12
	ds_read_b128 v[170:173], v244 offset:49152
	ds_read_b128 v[174:177], v244 offset:50176
	ds_read_b128 v[178:181], v244 offset:51200
	ds_read_b128 v[182:185], v244 offset:52224
	ds_read_b128 v[200:203], v244 offset:53248
	ds_read_b128 v[204:207], v244 offset:54272
	ds_read_b128 v[208:211], v244 offset:55296
	ds_read_b128 v[212:215], v244 offset:56320
	global_load_lds_dwordx4 v[162:163], off
	s_add_i32 m0, s12, 0x2000
	s_add_u32 s0, s0, 0x100080
	v_lshl_add_u64 v[162:163], v[164:165], 0, s[36:37]
	s_addc_u32 s1, s1, 0
	s_add_i32 s12, s51, s24
	global_load_lds_dwordx4 v[162:163], off
	v_lshl_add_u64 v[162:163], s[0:1], 0, v[188:189]
	s_mov_b32 m0, s12
	s_nop 0
	global_load_lds_dwordx4 v[162:163], off
	v_lshl_add_u64 v[162:163], s[0:1], 0, v[192:193]
	s_add_i32 m0, s12, 0x2000
	s_nop 0
	global_load_lds_dwordx4 v[162:163], off
	v_lshl_add_u64 v[162:163], v[166:167], 0, s[36:37]
	s_mov_b32 m0, s77
	s_nop 0
	global_load_lds_dwordx4 v[162:163], off
	v_lshl_add_u64 v[162:163], v[168:169], 0, s[36:37]
	s_mov_b32 m0, s78
	s_nop 0
	global_load_lds_dwordx4 v[162:163], off
	s_waitcnt vmcnt(8)
	s_waitcnt lgkmcnt(0)
	s_barrier
	s_waitcnt lgkmcnt(0)
	v_mfma_f32_16x16x128_f8f6f4 v[94:97], v[2:9], v[170:177], v[94:97]
	v_mfma_f32_16x16x128_f8f6f4 v[90:93], v[10:17], v[170:177], v[90:93]
	v_mfma_f32_16x16x128_f8f6f4 v[78:81], v[2:9], v[178:185], v[78:81]
	v_mfma_f32_16x16x128_f8f6f4 v[74:77], v[10:17], v[178:185], v[74:77]
	v_mfma_f32_16x16x128_f8f6f4 v[62:65], v[2:9], v[200:207], v[62:65]
	v_mfma_f32_16x16x128_f8f6f4 v[58:61], v[10:17], v[200:207], v[58:61]
	v_mfma_f32_16x16x128_f8f6f4 v[46:49], v[2:9], v[208:215], v[46:49]
	v_mfma_f32_16x16x128_f8f6f4 v[42:45], v[10:17], v[208:215], v[42:45]
	v_mfma_f32_16x16x128_f8f6f4 v[86:89], v[18:25], v[170:177], v[86:89]
	v_mfma_f32_16x16x128_f8f6f4 v[82:85], v[26:33], v[170:177], v[82:85]
	v_mfma_f32_16x16x128_f8f6f4 v[70:73], v[18:25], v[178:185], v[70:73]
	v_mfma_f32_16x16x128_f8f6f4 v[66:69], v[26:33], v[178:185], v[66:69]
	v_mfma_f32_16x16x128_f8f6f4 v[54:57], v[18:25], v[200:207], v[54:57]
	v_mfma_f32_16x16x128_f8f6f4 v[50:53], v[26:33], v[200:207], v[50:53]
	v_mfma_f32_16x16x128_f8f6f4 v[38:41], v[18:25], v[208:215], v[38:41]
	v_mfma_f32_16x16x128_f8f6f4 v[34:37], v[26:33], v[208:215], v[34:37]
	s_barrier
	s_add_u32 s10, s10, 0x100
	s_addc_u32 s11, s11, 0
	s_add_u32 s18, s18, 0x100
	s_addc_u32 s19, s19, 0
	s_cmp_ge_i32 s20, s17
	s_mov_b32 s0, s20
	s_cbranch_scc0 .LBB0_1159
	s_and_b64 vcc, exec, s[38:39]
	s_cbranch_vccz .LBB0_1162

	.amdhsa_kernel _Z9hymba_fwd4Args
		.amdhsa_group_segment_fixed_size 0
		.amdhsa_private_segment_fixed_size 0
		.amdhsa_kernarg_size 528
		.amdhsa_user_sgpr_count 2
		.amdhsa_user_sgpr_dispatch_ptr 0
		.amdhsa_user_sgpr_queue_ptr 0
		.amdhsa_user_sgpr_kernarg_segment_ptr 1
		.amdhsa_user_sgpr_dispatch_id 0
		.amdhsa_user_sgpr_kernarg_preload_length 0
		.amdhsa_user_sgpr_kernarg_preload_offset 0
		.amdhsa_user_sgpr_private_segment_size 0
		.amdhsa_uses_dynamic_stack 0
		.amdhsa_enable_private_segment 0
		.amdhsa_system_sgpr_workgroup_id_x 1
		.amdhsa_system_sgpr_workgroup_id_y 0
		.amdhsa_system_sgpr_workgroup_id_z 0
		.amdhsa_system_sgpr_workgroup_info 0
		.amdhsa_system_vgpr_workitem_id 0
		.amdhsa_next_free_vgpr 256
		.amdhsa_next_free_sgpr 102
		.amdhsa_accum_offset 256
		.amdhsa_reserve_vcc 1
		.amdhsa_float_round_mode_32 0
		.amdhsa_float_round_mode_16_64 0
		.amdhsa_float_denorm_mode_32 3
		.amdhsa_float_denorm_mode_16_64 3
		.amdhsa_dx10_clamp 1
		.amdhsa_ieee_mode 1
		.amdhsa_fp16_overflow 0
		.amdhsa_tg_split 0
		.amdhsa_exception_fp_ieee_invalid_op 0
		.amdhsa_exception_fp_denorm_src 0
		.amdhsa_exception_fp_ieee_div_zero 0
		.amdhsa_exception_fp_ieee_overflow 0
		.amdhsa_exception_fp_ieee_underflow 0
		.amdhsa_exception_fp_ieee_inexact 0
		.amdhsa_exception_int_div_zero 0
	.end_amdhsa_kernel

amdhsa.kernels:
  - .agpr_count:     0
    .args:
      - .offset:         0
        .size:           272
        .value_kind:     by_value
      - .offset:         272
        .size:           4
        .value_kind:     hidden_block_count_x
      - .offset:         276
        .size:           4
        .value_kind:     hidden_block_count_y
      - .offset:         280
        .size:           4
        .value_kind:     hidden_block_count_z
      - .offset:         284
        .size:           2
        .value_kind:     hidden_group_size_x
      - .offset:         286
        .size:           2
        .value_kind:     hidden_group_size_y
      - .offset:         288
        .size:           2
        .value_kind:     hidden_group_size_z
      - .offset:         290
        .size:           2
        .value_kind:     hidden_remainder_x
      - .offset:         292
        .size:           2
        .value_kind:     hidden_remainder_y
      - .offset:         294
        .size:           2
        .value_kind:     hidden_remainder_z
      - .offset:         312
        .size:           8
        .value_kind:     hidden_global_offset_x
      - .offset:         320
        .size:           8
        .value_kind:     hidden_global_offset_y
      - .offset:         328
        .size:           8
        .value_kind:     hidden_global_offset_z
      - .offset:         336
        .size:           2
        .value_kind:     hidden_grid_dims
      - .offset:         392
        .size:           4
        .value_kind:     hidden_dynamic_lds_size
    .group_segment_fixed_size: 0
    .kernarg_segment_align: 8
    .kernarg_segment_size: 528
    .language:       OpenCL C
    .language_version:
      - 2
      - 0
    .max_flat_workgroup_size: 512
    .name:           _Z9hymba_fwd4Args
    .private_segment_fixed_size: 0
    .sgpr_count:     108
    .sgpr_spill_count: 53
    .symbol:         _Z9hymba_fwd4Args.kd
    .uniform_work_group_size: 1
    .uses_dynamic_stack: false
    .vgpr_count:     256
    .vgpr_spill_count: 0
    .wavefront_size: 64
